# GEMM k-loops hand-pipelined + next-tile k-slices 0/1 pre-issued; P1 column-tile rotation balances epilogue kinds across blocks; attention: LDS operand reads pipelined, mask-free softmax off-diagonal
# speedup vs baseline: 1.0490x; 1.0223x over previous
; DI int opaque_tid() { int t = threadIdx.x; asm volatile("" : "+v"(t)); return t; }
; #define GEMM_ISSUE(KT, ST) do { const int k1_ = (KT) << 6; unsigned char* d_ = ldst + (ST) * STAGE; \
;         _Pragma("unroll") for (int j_ = 0; j_ < 4; ++j_) dma16(ap + (size_t)(64 * j_) * lda + k1_, d_ + j_ * 8192); \
;         _Pragma("unroll") for (int j_ = 0; j_ < NBW; ++j_) dma16(bp + bro[j_] + k1_, d_ + BOFF + j_ * 8192); } while (0)
; template <int NBW>
; DI void gemm_mainloop(f32x16 (&acc)[2][NBW], const bf16_t* A, size_t lda, int m0, const bf16_t* Bt, size_t ldb, int n0, int K, unsigned char* lds, bool pre = false, bool only_issue = false) {
;     constexpr int STAGE = 65536, BOFF = 32768;
;     const int t = opaque_tid(), w = t >> 6, lane = t & 63, r = lane & 31, hh = lane >> 5, wm = w >> 1, wn = w & 1;
;     const int drow = w * 8 + (lane >> 3);
;     const int lchunk = (lane & 7) ^ ((drow >> 1) & 7);
;     const bf16_t* ap = A + (size_t)(m0 + drow) * lda + lchunk * 8;
;     const bf16_t* bp = Bt + (size_t)n0 * ldb + lchunk * 8;
;     size_t bro[NBW];
; #pragma unroll
;     for (int j = 0; j < NBW; ++j) {
;         const int rho = 64 * j + drow; const int wnh = rho / (32 * NBW), wi = rho % (32 * NBW);
;         bro[j] = (size_t)(wnh * 32 * NBW + NBW * (wi & 31) + (wi >> 5)) * ldb;
;     }
;     unsigned char* ldst = lds + w * 1024 + lane * 16;
;     ...
;     if (!pre) GEMM_ISSUE(0, 0);
; DI void phase_p1(const Params& P, unsigned char* lds) {
;     ...
;     for (int tile = blockIdx.x; tile < NTM * NTN; tile += gridDim.x) {
;         const int mt = tile / NTN, nt = tile % NTN;
.LBB0_143:
	v_mov_b32_e32 v13, v1
	s_ashr_i32 s0, s61, 31
	v_ashrrev_i32_e32 v12, 6, v13
	v_lshlrev_b32_e32 v6, 3, v12
	v_bfe_u32 v11, v13, 3, 3
	v_or_b32_e32 v15, v6, v11
	v_lshrrev_b32_e32 v2, 1, v15
	v_xor_b32_e32 v20, v2, v13
	v_ashrrev_i32_e32 v2, 31, v13
	v_lshrrev_b32_e32 v2, 25, v2
	v_add_u32_e32 v3, v15, v2
	v_lshrrev_b32_e32 v2, 7, v3
	v_mul_i32_i24_e32 v2, 0x80, v2
	v_sub_u32_e32 v16, v15, v2
	v_and_b32_e32 v3, 0xffffff80, v3
	v_ashrrev_i32_e32 v4, 5, v16
	v_add_u32_e32 v7, v4, v3
	v_add_u32_e32 v4, 64, v15
	v_ashrrev_i32_e32 v3, 31, v4
	v_lshrrev_b32_e32 v3, 25, v3
	v_add_u32_e32 v5, v4, v3
	v_lshrrev_b32_e32 v3, 7, v5
	v_mul_i32_i24_e32 v3, 0x80, v3
	v_sub_u32_e32 v17, v4, v3
	v_and_b32_e32 v4, 0xffffff80, v5
	v_ashrrev_i32_e32 v5, 5, v17
	v_add_u32_e32 v8, v5, v4
	v_add_u32_e32 v5, 0x80, v15
	v_ashrrev_i32_e32 v4, 31, v5
	v_lshrrev_b32_e32 v4, 25, v4
	v_add_u32_e32 v9, v5, v4
	v_lshrrev_b32_e32 v4, 7, v9
	v_mul_i32_i24_e32 v4, 0x80, v4
	v_sub_u32_e32 v18, v5, v4
	v_and_b32_e32 v5, 0xffffff80, v9
	v_ashrrev_i32_e32 v9, 5, v18
	v_add_u32_e32 v10, 0xc0, v15
	v_add_u32_e32 v9, v9, v5
	v_ashrrev_i32_e32 v5, 31, v10
	v_lshrrev_b32_e32 v5, 25, v5
	s_lshr_b32 s0, s0, 27
	v_add_u32_e32 v21, v10, v5
	s_add_i32 s0, s61, s0
	v_lshrrev_b32_e32 v5, 7, v21
	s_and_b32 s1, s0, 0xffffe0
	v_mul_i32_i24_e32 v5, 0x80, v5
	s_sub_i32 s1, s61, s1
	s_lshl_b32 s0, s0, 3
	v_sub_u32_e32 v19, v10, v5
	s_and_b32 s20, s0, 0xffffff00
	s_lshl_b32 s0, s1, 8
	s_lshr_b32 s1, s20, 11
	s_mul_i32 s1, s1, 0x500
	s_add_i32 s0, s0, s1
	s_and_b32 s0, s0, 0x1fff
	v_and_b32_e32 v14, 63, v13
	v_and_b32_e32 v10, 0xffffff80, v21
	v_ashrrev_i32_e32 v21, 5, v19
	s_ashr_i32 s1, s0, 31
	v_add_u32_e32 v10, v21, v10
	v_lshlrev_b32_e32 v21, 10, v12
	v_lshlrev_b32_e32 v22, 4, v14
	v_lshlrev_b32_e32 v20, 4, v20
	s_lshl_b64 s[2:3], s[0:1], 11
	v_add3_u32 v142, 0, v21, v22
	s_and_b64 vcc, exec, s[18:19]
	v_and_b32_e32 v138, 0x70, v20
	s_cbranch_vccnz .LBB0_145
	v_add_u32_e32 v20, s20, v15
	v_lshlrev_b32_e32 v15, 2, v16
	v_and_b32_e32 v15, 0x7c, v15
	v_add_u32_e32 v22, v7, v15
	v_lshlrev_b32_e32 v15, 2, v17
	v_and_b32_e32 v15, 0x7c, v15
	v_add_u32_e32 v16, v8, v15
	v_lshlrev_b32_e32 v15, 2, v18
	v_and_b32_e32 v15, 0x7c, v15
	v_ashrrev_i32_e32 v21, 31, v20
	v_add_u32_e32 v24, v9, v15
	v_lshlrev_b32_e32 v15, 2, v19
	v_and_b32_e32 v15, 0x7c, v15
	v_lshlrev_b64 v[20:21], 11, v[20:21]
	v_add_u32_e32 v18, v10, v15
	v_lshl_add_u64 v[20:21], s[4:5], 0, v[20:21]
	v_readfirstlane_b32 s1, v142
	v_add_u32_e32 v15, 0x2000, v142
	v_lshl_add_u64 v[20:21], v[20:21], 0, v[138:139]
	s_mov_b32 m0, s1
	v_readfirstlane_b32 s1, v15
	v_add_u32_e32 v15, 0x4000, v142
	global_load_lds_dwordx4 v[20:21], off
	s_nop 0
	s_cselect_b32 s98, 1, 0
	s_add_i32 m0, m0, 0xff80
	s_cmp_lg_u32 s98, 0
	global_load_lds_dwordx4 v[20:21], off offset:128
	s_nop 0
	v_lshl_add_u64 v[28:29], v[20:21], 0, s[12:13]
	s_mov_b32 m0, s1
	v_readfirstlane_b32 s1, v15
	v_add_u32_e32 v15, 0x6000, v142
	s_add_u32 s18, s36, s2
	global_load_lds_dwordx4 v[28:29], off
	s_nop 0
	s_cselect_b32 s98, 1, 0
	s_add_i32 m0, m0, 0xff80
	s_cmp_lg_u32 s98, 0
	global_load_lds_dwordx4 v[28:29], off offset:128
	s_nop 0
	v_lshl_add_u64 v[28:29], v[20:21], 0, s[14:15]
	s_mov_b32 m0, s1
	v_readfirstlane_b32 s1, v15
	s_addc_u32 s19, s37, s3
	v_ashrrev_i32_e32 v23, 31, v22
	global_load_lds_dwordx4 v[28:29], off
	s_nop 0
	s_cselect_b32 s98, 1, 0
	s_add_i32 m0, m0, 0xff80
	s_cmp_lg_u32 s98, 0
	global_load_lds_dwordx4 v[28:29], off offset:128
	s_nop 0
	v_lshl_add_u64 v[20:21], v[20:21], 0, s[16:17]
	s_mov_b32 m0, s1
	v_add_u32_e32 v15, 0x8000, v142
	v_ashrrev_i32_e32 v17, 31, v16
	v_lshl_add_u64 v[26:27], s[18:19], 0, v[138:139]
	global_load_lds_dwordx4 v[20:21], off
	s_nop 0
	s_cselect_b32 s98, 1, 0
	s_add_i32 m0, m0, 0xff80
	s_cmp_lg_u32 s98, 0
	global_load_lds_dwordx4 v[20:21], off offset:128
	s_nop 0
	v_lshlrev_b64 v[20:21], 11, v[22:23]
	v_readfirstlane_b32 s1, v15
	v_add_u32_e32 v15, 0xa000, v142
	v_lshl_add_u64 v[20:21], v[26:27], 0, v[20:21]
	s_mov_b32 m0, s1
	v_lshlrev_b64 v[16:17], 11, v[16:17]
	v_readfirstlane_b32 s1, v15
	v_ashrrev_i32_e32 v25, 31, v24
	global_load_lds_dwordx4 v[20:21], off
	s_nop 0
	s_cselect_b32 s98, 1, 0
	s_add_i32 m0, m0, 0xff80
	s_cmp_lg_u32 s98, 0
	global_load_lds_dwordx4 v[20:21], off offset:128
	s_nop 0
	v_lshl_add_u64 v[16:17], v[26:27], 0, v[16:17]
	s_mov_b32 m0, s1
	v_add_u32_e32 v15, 0xc000, v142
	global_load_lds_dwordx4 v[16:17], off
	s_nop 0
	s_cselect_b32 s98, 1, 0
	s_add_i32 m0, m0, 0xff80
	s_cmp_lg_u32 s98, 0
	global_load_lds_dwordx4 v[16:17], off offset:128
	s_nop 0
	v_lshlrev_b64 v[16:17], 11, v[24:25]
	v_readfirstlane_b32 s1, v15
	v_ashrrev_i32_e32 v19, 31, v18
	v_lshl_add_u64 v[16:17], v[26:27], 0, v[16:17]
	s_mov_b32 m0, s1
	v_add_u32_e32 v15, 0xe000, v142
	global_load_lds_dwordx4 v[16:17], off
	s_nop 0
	s_cselect_b32 s98, 1, 0
	s_add_i32 m0, m0, 0xff80
	s_cmp_lg_u32 s98, 0
	global_load_lds_dwordx4 v[16:17], off offset:128
	s_nop 0
	v_lshlrev_b64 v[16:17], 11, v[18:19]
	v_readfirstlane_b32 s1, v15
	v_lshl_add_u64 v[16:17], v[26:27], 0, v[16:17]
	s_mov_b32 m0, s1
	s_nop 0
	global_load_lds_dwordx4 v[16:17], off
	s_nop 0
	s_cselect_b32 s98, 1, 0
	s_add_i32 m0, m0, 0xff80
	s_cmp_lg_u32 s98, 0
	global_load_lds_dwordx4 v[16:17], off offset:128
	s_nop 0
; DI int opaque_tid() { int t = threadIdx.x; asm volatile("" : "+v"(t)); return t; }
; DI f32x16 zero16() { f32x16 z; for (int i = 0; i < 16; ++i) z[i] = 0.f; return z; }
; #define GEMM_ISSUE(KT, ST) do { const int k1_ = (KT) << 6; unsigned char* d_ = ldst + (ST) * STAGE; \
;         _Pragma("unroll") for (int j_ = 0; j_ < 4; ++j_) dma16(ap + (size_t)(64 * j_) * lda + k1_, d_ + j_ * 8192); \
;         _Pragma("unroll") for (int j_ = 0; j_ < NBW; ++j_) dma16(bp + bro[j_] + k1_, d_ + BOFF + j_ * 8192); } while (0)
; template <int NBW>
; DI void gemm_mainloop(f32x16 (&acc)[2][NBW], const bf16_t* A, size_t lda, int m0, const bf16_t* Bt, size_t ldb, int n0, int K, unsigned char* lds, bool pre = false, bool only_issue = false) {
;     ...
;     const int t = opaque_tid(), w = t >> 6, lane = t & 63, r = lane & 31, hh = lane >> 5, wm = w >> 1, wn = w & 1;
;     const int drow = w * 8 + (lane >> 3);
;     const int lchunk = (lane & 7) ^ ((drow >> 1) & 7);
;     const bf16_t* ap = A + (size_t)(m0 + drow) * lda + lchunk * 8;
;     const bf16_t* bp = Bt + (size_t)n0 * ldb + lchunk * 8;
;     size_t bro[NBW];
; #pragma unroll
;     for (int j = 0; j < NBW; ++j) {
;         const int rho = 64 * j + drow; const int wnh = rho / (32 * NBW), wi = rho % (32 * NBW);
;         bro[j] = (size_t)(wnh * 32 * NBW + NBW * (wi & 31) + (wi >> 5)) * ldb;
;     }
;     unsigned char* ldst = lds + w * 1024 + lane * 16;
;     ...
;     if (!pre) GEMM_ISSUE(0, 0);
;     if (only_issue) return;
;     __syncthreads();
;     const int nk = K >> 6;
;     const int xr = (r >> 1) & 7;
;     int xo[4];
; #pragma unroll
;     for (int s = 0; s < 4; ++s) xo[s] = ((2 * s + hh) ^ xr) << 4;
;     const int aofs = (wm * 64 + r) * 128;
;     const int bofs = BOFF + (wn * 32 * NBW + r) * 128;
; DI void phase_p1(const Params& P, unsigned char* lds) {
;     ...
;         f32x16 acc[2][4];
; #pragma unroll
;         for (int a = 0; a < 2; ++a)
; #pragma unroll
;             for (int b = 0; b < 4; ++b) acc[a][b] = zero16();
;         gemm_mainloop<4>(acc, A, 1024, mt * 256, Bt, 1024, nt * 256, 1024, lds, pre);
.LBB0_145:
	v_lshrrev_b32_e32 v16, 5, v14
	v_lshrrev_b32_e32 v18, 1, v13
	v_and_b32_e32 v15, 31, v13
	v_lshrrev_b32_e32 v17, 6, v13
	v_bfe_u32 v13, v13, 1, 3
	v_bitop3_b32 v19, v16, v18, 7 bitop3:0x78
	v_lshlrev_b32_e32 v143, 4, v19
	v_bitop3_b32 v19, v16, v13, 2 bitop3:0x36
	v_lshlrev_b32_e32 v144, 4, v19
	v_bitop3_b32 v19, v16, v13, 4 bitop3:0x36
	v_bitop3_b32 v13, v16, v13, 6 bitop3:0x36
	s_mov_b32 s1, 0x1ffffc0
	v_lshlrev_b32_e32 v146, 4, v13
	v_and_or_b32 v13, v18, s1, v15
	v_lshlrev_b32_e32 v12, 7, v12
	s_movk_i32 s1, 0x80
	v_and_or_b32 v12, v12, s1, v15
	v_lshrrev_b32_e32 v14, 3, v14
	v_lshlrev_b32_e32 v148, 7, v12
	v_add3_u32 v12, v11, s20, v6
	v_lshlrev_b16_e32 v6, 3, v17
	v_or_b32_e32 v11, v6, v14
	v_sub_u16_e32 v2, v11, v2
	v_and_b32_e32 v2, 31, v2
	v_lshl_add_u32 v6, v2, 2, v7
	v_sub_u16_e32 v2, v11, v3
	v_and_b32_e32 v2, 31, v2
	v_lshl_add_u32 v2, v2, 2, v8
	v_ashrrev_i32_e32 v3, 31, v2
	v_lshlrev_b64 v[2:3], 11, v[2:3]
	v_lshl_add_u64 v[2:3], v[2:3], 0, s[2:3]
	v_lshl_add_u64 v[2:3], v[2:3], 0, v[138:139]
	v_lshl_add_u64 v[134:135], s[10:11], 0, v[2:3]
	v_sub_u16_e32 v2, v11, v4
	v_and_b32_e32 v2, 31, v2
	v_lshl_add_u32 v2, v2, 2, v9
	v_ashrrev_i32_e32 v3, 31, v2
	v_lshlrev_b64 v[2:3], 11, v[2:3]
	v_lshl_add_u64 v[2:3], v[2:3], 0, s[2:3]
	v_lshl_add_u64 v[2:3], v[2:3], 0, v[138:139]
	v_lshl_add_u64 v[136:137], s[10:11], 0, v[2:3]
	v_sub_u16_e32 v2, v11, v5
	v_and_b32_e32 v2, 31, v2
	v_lshl_add_u32 v2, v2, 2, v10
	v_ashrrev_i32_e32 v3, 31, v2
	v_ashrrev_i32_e32 v7, 31, v6
	v_lshlrev_b64 v[2:3], 11, v[2:3]
	v_lshlrev_b32_e32 v147, 7, v13
	v_ashrrev_i32_e32 v13, 31, v12
	v_lshlrev_b64 v[6:7], 11, v[6:7]
	v_lshl_add_u64 v[2:3], v[2:3], 0, s[2:3]
	v_lshlrev_b64 v[12:13], 11, v[12:13]
	v_readlane_b32 s18, v223, 0
	v_lshl_add_u64 v[6:7], v[6:7], 0, s[2:3]
	v_lshl_add_u64 v[2:3], v[2:3], 0, v[138:139]
	v_or_b32_e32 v12, v12, v138
	v_readlane_b32 s19, v223, 1
	v_lshl_add_u64 v[6:7], v[6:7], 0, v[138:139]
	v_lshl_add_u64 v[140:141], s[10:11], 0, v[2:3]
	v_mov_b32_e32 v2, 0
	v_lshlrev_b32_e32 v145, 4, v19
	v_lshl_add_u64 v[130:131], s[18:19], 0, v[12:13]
	v_lshl_add_u64 v[132:133], s[10:11], 0, v[6:7]
	s_mov_b32 s1, 0
	s_mov_b64 s[2:3], 0
	s_mov_b32 s18, 0x10000
	v_mov_b32_e32 v3, v2
	v_mov_b32_e32 v4, v2
	v_mov_b32_e32 v5, v2
	v_mov_b32_e32 v6, v2
	v_mov_b32_e32 v7, v2
	v_mov_b32_e32 v8, v2
	v_mov_b32_e32 v9, v2
	v_mov_b32_e32 v10, v2
	v_mov_b32_e32 v11, v2
	v_mov_b32_e32 v12, v2
	v_mov_b32_e32 v13, v2
	v_mov_b32_e32 v14, v2
	v_mov_b32_e32 v15, v2
	v_mov_b32_e32 v16, v2
	v_mov_b32_e32 v17, v2
	v_mov_b32_e32 v34, v2
	v_mov_b32_e32 v35, v2
	v_mov_b32_e32 v36, v2
	v_mov_b32_e32 v37, v2
	v_mov_b32_e32 v38, v2
	v_mov_b32_e32 v39, v2
	v_mov_b32_e32 v40, v2
	v_mov_b32_e32 v41, v2
	v_mov_b32_e32 v42, v2
	v_mov_b32_e32 v43, v2
	v_mov_b32_e32 v44, v2
	v_mov_b32_e32 v45, v2
	v_mov_b32_e32 v46, v2
	v_mov_b32_e32 v47, v2
	v_mov_b32_e32 v48, v2
	v_mov_b32_e32 v49, v2
	v_mov_b32_e32 v18, v2
	v_mov_b32_e32 v19, v2
	v_mov_b32_e32 v20, v2
	v_mov_b32_e32 v21, v2
	v_mov_b32_e32 v22, v2
	v_mov_b32_e32 v23, v2
	v_mov_b32_e32 v24, v2
	v_mov_b32_e32 v25, v2
	v_mov_b32_e32 v26, v2
	v_mov_b32_e32 v27, v2
	v_mov_b32_e32 v28, v2
	v_mov_b32_e32 v29, v2
	v_mov_b32_e32 v30, v2
	v_mov_b32_e32 v31, v2
	v_mov_b32_e32 v32, v2
	v_mov_b32_e32 v33, v2
	v_mov_b32_e32 v50, v2
	v_mov_b32_e32 v51, v2
	v_mov_b32_e32 v52, v2
	v_mov_b32_e32 v53, v2
	v_mov_b32_e32 v54, v2
	v_mov_b32_e32 v55, v2
	v_mov_b32_e32 v56, v2
	v_mov_b32_e32 v57, v2
	v_mov_b32_e32 v58, v2
	v_mov_b32_e32 v59, v2
	v_mov_b32_e32 v60, v2
	v_mov_b32_e32 v61, v2
	v_mov_b32_e32 v62, v2
	v_mov_b32_e32 v63, v2
	v_mov_b32_e32 v64, v2
	v_mov_b32_e32 v65, v2
	v_mov_b32_e32 v66, v2
	v_mov_b32_e32 v67, v2
	v_mov_b32_e32 v68, v2
	v_mov_b32_e32 v69, v2
	v_mov_b32_e32 v70, v2
	v_mov_b32_e32 v71, v2
	v_mov_b32_e32 v72, v2
	v_mov_b32_e32 v73, v2
	v_mov_b32_e32 v74, v2
	v_mov_b32_e32 v75, v2
	v_mov_b32_e32 v76, v2
	v_mov_b32_e32 v77, v2
	v_mov_b32_e32 v78, v2
	v_mov_b32_e32 v79, v2
	v_mov_b32_e32 v80, v2
	v_mov_b32_e32 v81, v2
	v_mov_b32_e32 v98, v2
	v_mov_b32_e32 v99, v2
	v_mov_b32_e32 v100, v2
	v_mov_b32_e32 v101, v2
	v_mov_b32_e32 v102, v2
	v_mov_b32_e32 v103, v2
	v_mov_b32_e32 v104, v2
	v_mov_b32_e32 v105, v2
	v_mov_b32_e32 v106, v2
	v_mov_b32_e32 v107, v2
	v_mov_b32_e32 v108, v2
	v_mov_b32_e32 v109, v2
	v_mov_b32_e32 v110, v2
	v_mov_b32_e32 v111, v2
	v_mov_b32_e32 v112, v2
	v_mov_b32_e32 v113, v2
	v_mov_b32_e32 v82, v2
	v_mov_b32_e32 v83, v2
	v_mov_b32_e32 v84, v2
	v_mov_b32_e32 v85, v2
	v_mov_b32_e32 v86, v2
	v_mov_b32_e32 v87, v2
	v_mov_b32_e32 v88, v2
	v_mov_b32_e32 v89, v2
	v_mov_b32_e32 v90, v2
	v_mov_b32_e32 v91, v2
	v_mov_b32_e32 v92, v2
	v_mov_b32_e32 v93, v2
	v_mov_b32_e32 v94, v2
	v_mov_b32_e32 v95, v2
	v_mov_b32_e32 v96, v2
	v_mov_b32_e32 v97, v2
	v_mov_b32_e32 v114, v2
	v_mov_b32_e32 v115, v2
	v_mov_b32_e32 v116, v2
	v_mov_b32_e32 v117, v2
	v_mov_b32_e32 v118, v2
	v_mov_b32_e32 v119, v2
	v_mov_b32_e32 v120, v2
	v_mov_b32_e32 v121, v2
	v_mov_b32_e32 v122, v2
	v_mov_b32_e32 v123, v2
	v_mov_b32_e32 v124, v2
	v_mov_b32_e32 v125, v2
	v_mov_b32_e32 v126, v2
	v_mov_b32_e32 v127, v2
	v_mov_b32_e32 v128, v2
	v_mov_b32_e32 v129, v2
	s_waitcnt vmcnt(0) lgkmcnt(0)
	s_barrier
	v_mov_b32_e32 v138, v147
	v_mov_b32_e32 v149, v148
	s_add_u32 s2, s2, 0x80
	s_addc_u32 s3, s3, 0
	s_add_i32 s18, s18, 0x10000
	v_add_u32_e32 v252, v138, v143
	v_add_u32_e32 v253, v149, v143
	ds_read_b128 v[224:227], v252
	ds_read_b128 v[232:235], v253 offset:32768
	ds_read_b128 v[236:239], v253 offset:36864
	ds_read_b128 v[240:243], v253 offset:40960
	ds_read_b128 v[244:247], v253 offset:45056
	ds_read_b128 v[228:231], v252 offset:4096

; DI int opaque_tid() { int t = threadIdx.x; asm volatile("" : "+v"(t)); return t; }
; DI f32x16 zero16() { f32x16 z; for (int i = 0; i < 16; ++i) z[i] = 0.f; return z; }
; #define GEMM_ISSUE(KT, ST) do { const int k1_ = (KT) << 6; unsigned char* d_ = ldst + (ST) * STAGE; \
;         _Pragma("unroll") for (int j_ = 0; j_ < 4; ++j_) dma16(ap + (size_t)(64 * j_) * lda + k1_, d_ + j_ * 8192); \
;         _Pragma("unroll") for (int j_ = 0; j_ < NBW; ++j_) dma16(bp + bro[j_] + k1_, d_ + BOFF + j_ * 8192); } while (0)
; template <int NBW>
; DI void gemm_mainloop(f32x16 (&acc)[2][NBW], const bf16_t* A, size_t lda, int m0, const bf16_t* Bt, size_t ldb, int n0, int K, unsigned char* lds, bool pre = false, bool only_issue = false) {
;     constexpr int STAGE = 65536, BOFF = 32768;
;     const int t = opaque_tid(), w = t >> 6, lane = t & 63, r = lane & 31, hh = lane >> 5, wm = w >> 1, wn = w & 1;
;     const int drow = w * 8 + (lane >> 3);
;     const int lchunk = (lane & 7) ^ ((drow >> 1) & 7);
;     const bf16_t* ap = A + (size_t)(m0 + drow) * lda + lchunk * 8;
;     const bf16_t* bp = Bt + (size_t)n0 * ldb + lchunk * 8;
;     size_t bro[NBW];
; #pragma unroll
;     for (int j = 0; j < NBW; ++j) {
;         const int rho = 64 * j + drow; const int wnh = rho / (32 * NBW), wi = rho % (32 * NBW);
;         bro[j] = (size_t)(wnh * 32 * NBW + NBW * (wi & 31) + (wi >> 5)) * ldb;
;     }
;     unsigned char* ldst = lds + w * 1024 + lane * 16;
;     ...
;     if (!pre) GEMM_ISSUE(0, 0);
; DI void phase_p1(const Params& P, unsigned char* lds) {
;     ...
;     for (int tile = blockIdx.x; tile < NTM * NTN; tile += gridDim.x) {
;         const int mt = tile / NTN, nt = tile % NTN;
;         f32x16 acc[2][4];
; #pragma unroll
;         for (int a = 0; a < 2; ++a)
; #pragma unroll
;             for (int b = 0; b < 4; ++b) acc[a][b] = zero16();
;         gemm_mainloop<4>(acc, A, 1024, mt * 256, Bt, 1024, nt * 256, 1024, lds, pre);
;         { const int tn = tile + gridDim.x; pre = tn < NTM * NTN; if (pre) { const int mtn = tn / NTN, ntn_ = tn % NTN; f32x16 (&dummy)[2][4] = acc; gemm_mainloop<4>(dummy, A, 1024, mtn * 256, Bt, 1024, ntn_ * 256, 1024, lds, false, true); } }
.LBB0_149:
	v_readlane_b32 s2, v223, 3
	s_add_i32 s61, s61, s2
	s_cmpk_gt_i32 s61, 0x105f
	s_cselect_b64 s[18:19], -1, 0
	s_and_b64 vcc, exec, s[18:19]
	v_readlane_b32 s3, v223, 4
	s_cbranch_vccnz .LBB0_151
	v_mov_b32_e32 v132, v1
	s_ashr_i32 s1, s61, 31
	v_ashrrev_i32_e32 v144, 6, v132
	v_bfe_u32 v130, v132, 3, 3
	v_lshl_or_b32 v138, v144, 3, v130
	v_lshrrev_b32_e32 v130, 1, v138
	v_and_b32_e32 v145, 63, v132
	v_xor_b32_e32 v142, v130, v132
	v_ashrrev_i32_e32 v132, 31, v132
	v_lshrrev_b32_e32 v132, 25, v132
	v_add_u32_e32 v132, v138, v132
	v_lshrrev_b32_e32 v133, 7, v132
	v_mul_i32_i24_e32 v133, 0x80, v133
	v_sub_u32_e32 v133, v138, v133
	v_lshlrev_b32_e32 v134, 2, v133
	v_and_b32_e32 v132, 0xffffff80, v132
	v_and_b32_e32 v134, 0x7c, v134
	v_ashrrev_i32_e32 v133, 5, v133
	v_add3_u32 v132, v133, v132, v134
	v_add_u32_e32 v134, 64, v138
	v_ashrrev_i32_e32 v135, 31, v134
	v_lshrrev_b32_e32 v135, 25, v135
	v_add_u32_e32 v135, v134, v135
	v_lshrrev_b32_e32 v136, 7, v135
	v_mul_i32_i24_e32 v136, 0x80, v136
	v_sub_u32_e32 v134, v134, v136
	v_lshlrev_b32_e32 v136, 2, v134
	v_and_b32_e32 v135, 0xffffff80, v135
	v_and_b32_e32 v136, 0x7c, v136
	v_ashrrev_i32_e32 v134, 5, v134
	v_add3_u32 v134, v134, v135, v136
	v_add_u32_e32 v136, 0x80, v138
	v_ashrrev_i32_e32 v137, 31, v136
	v_lshrrev_b32_e32 v137, 25, v137
	v_add_u32_e32 v137, v136, v137
	s_lshr_b32 s1, s1, 27
	v_lshrrev_b32_e32 v140, 7, v137
	s_add_i32 s1, s61, s1
	v_mul_i32_i24_e32 v140, 0x80, v140
	s_and_b32 s2, s1, 0xffffe0
	s_lshl_b32 s1, s1, 3
	v_sub_u32_e32 v136, v136, v140
	s_and_b32 s1, s1, 0xffffff00
	v_lshlrev_b32_e32 v140, 2, v136
	v_add_u32_e32 v130, s1, v138
	v_and_b32_e32 v137, 0xffffff80, v137
	v_and_b32_e32 v140, 0x7c, v140
	v_ashrrev_i32_e32 v136, 5, v136
	v_add_u32_e32 v138, 0xc0, v138
	v_add3_u32 v136, v136, v137, v140
	v_ashrrev_i32_e32 v140, 31, v138
	v_lshrrev_b32_e32 v140, 25, v140
	v_add_u32_e32 v140, v138, v140
	v_lshrrev_b32_e32 v141, 7, v140
	s_sub_i32 s2, s61, s2
	v_mul_i32_i24_e32 v141, 0x80, v141
	s_lshl_b32 s2, s2, 8
	s_lshr_b32 s3, s1, 11
	s_mul_i32 s3, s3, 0x500
	s_add_i32 s2, s2, s3
	s_and_b32 s2, s2, 0x1fff
	v_sub_u32_e32 v138, v138, v141
	s_ashr_i32 s3, s2, 31
	v_lshlrev_b32_e32 v141, 2, v138
	v_ashrrev_i32_e32 v131, 31, v130
	s_lshl_b64 s[2:3], s[2:3], 11
	v_and_b32_e32 v140, 0xffffff80, v140
	v_and_b32_e32 v141, 0x7c, v141
	v_ashrrev_i32_e32 v138, 5, v138
	s_add_u32 s2, s36, s2
	v_add3_u32 v140, v138, v140, v141
	v_lshlrev_b64 v[130:131], 11, v[130:131]
	v_lshlrev_b32_e32 v138, 4, v142
	s_addc_u32 s3, s37, s3
	v_lshl_add_u64 v[130:131], s[4:5], 0, v[130:131]
	v_and_b32_e32 v138, 0x70, v138
	v_lshl_add_u64 v[130:131], v[130:131], 0, v[138:139]
	v_lshl_add_u64 v[142:143], s[2:3], 0, v[138:139]
	v_lshlrev_b32_e32 v138, 10, v144
	v_lshlrev_b32_e32 v144, 4, v145
	v_add3_u32 v138, 0, v138, v144
	v_add_u32_e32 v146, 0x2000, v138
	v_readfirstlane_b32 s1, v138
	s_mov_b32 m0, s1
	v_readfirstlane_b32 s1, v146
	v_add_u32_e32 v146, 0x4000, v138
	global_load_lds_dwordx4 v[130:131], off
	s_nop 0
	s_cselect_b32 s98, 1, 0
	s_add_i32 m0, m0, 0xff80
	s_cmp_lg_u32 s98, 0
	global_load_lds_dwordx4 v[130:131], off offset:128
	s_nop 0
	v_lshl_add_u64 v[144:145], v[130:131], 0, s[12:13]
	s_mov_b32 m0, s1
	v_readfirstlane_b32 s1, v146
	global_load_lds_dwordx4 v[144:145], off
	s_nop 0
	s_cselect_b32 s98, 1, 0
	s_add_i32 m0, m0, 0xff80
	s_cmp_lg_u32 s98, 0
	global_load_lds_dwordx4 v[144:145], off offset:128
	s_nop 0
	v_lshl_add_u64 v[144:145], v[130:131], 0, s[14:15]
	s_mov_b32 m0, s1
	v_ashrrev_i32_e32 v133, 31, v132
	global_load_lds_dwordx4 v[144:145], off
	s_nop 0
	s_cselect_b32 s98, 1, 0
	s_add_i32 m0, m0, 0xff80
	s_cmp_lg_u32 s98, 0
	global_load_lds_dwordx4 v[144:145], off offset:128
	s_nop 0
	v_add_u32_e32 v144, 0x6000, v138
	v_lshl_add_u64 v[130:131], v[130:131], 0, s[16:17]
	v_readfirstlane_b32 s1, v144
	s_mov_b32 m0, s1
	v_add_u32_e32 v144, 0x8000, v138
	global_load_lds_dwordx4 v[130:131], off
	s_nop 0
	s_cselect_b32 s98, 1, 0
	s_add_i32 m0, m0, 0xff80
	s_cmp_lg_u32 s98, 0
	global_load_lds_dwordx4 v[130:131], off offset:128
	s_nop 0
	v_lshlrev_b64 v[130:131], 11, v[132:133]
	v_readfirstlane_b32 s1, v144
	v_ashrrev_i32_e32 v135, 31, v134
	v_lshl_add_u64 v[130:131], v[142:143], 0, v[130:131]
	s_mov_b32 m0, s1
	v_add_u32_e32 v132, 0xa000, v138
	global_load_lds_dwordx4 v[130:131], off
	s_nop 0
	s_cselect_b32 s98, 1, 0
	s_add_i32 m0, m0, 0xff80
	s_cmp_lg_u32 s98, 0
	global_load_lds_dwordx4 v[130:131], off offset:128
	s_nop 0
	v_lshlrev_b64 v[130:131], 11, v[134:135]
	v_readfirstlane_b32 s1, v132
	v_ashrrev_i32_e32 v137, 31, v136
	v_lshl_add_u64 v[130:131], v[142:143], 0, v[130:131]
	s_mov_b32 m0, s1
	v_add_u32_e32 v132, 0xc000, v138
	global_load_lds_dwordx4 v[130:131], off
	s_nop 0
	s_cselect_b32 s98, 1, 0
	s_add_i32 m0, m0, 0xff80
	s_cmp_lg_u32 s98, 0
	global_load_lds_dwordx4 v[130:131], off offset:128
	s_nop 0
	v_lshlrev_b64 v[130:131], 11, v[136:137]
	v_readfirstlane_b32 s1, v132
	v_ashrrev_i32_e32 v141, 31, v140
	v_lshl_add_u64 v[130:131], v[142:143], 0, v[130:131]
	s_mov_b32 m0, s1
	v_add_u32_e32 v132, 0xe000, v138
	global_load_lds_dwordx4 v[130:131], off
	s_nop 0
	s_cselect_b32 s98, 1, 0
	s_add_i32 m0, m0, 0xff80
	s_cmp_lg_u32 s98, 0
	global_load_lds_dwordx4 v[130:131], off offset:128
	s_nop 0
	v_lshlrev_b64 v[130:131], 11, v[140:141]
	v_readfirstlane_b32 s1, v132
	v_lshl_add_u64 v[130:131], v[142:143], 0, v[130:131]
	s_mov_b32 m0, s1
	s_nop 0
	global_load_lds_dwordx4 v[130:131], off
	s_nop 0
	s_cselect_b32 s98, 1, 0
	s_add_i32 m0, m0, 0xff80
	s_cmp_lg_u32 s98, 0
	global_load_lds_dwordx4 v[130:131], off offset:128
	s_nop 0

; #define ATT_GLOAD(KT) do { const int kbase_ = (KT) * 64; \
;         kr[0] = *(const u32x4*)(kg + (size_t)kbase_ * 1024); kr[1] = *(const u32x4*)(kg + (size_t)(kbase_ + 32) * 1024); \
;         vr[0] = *(const u32x4*)(vg + kbase_); vr[1] = *(const u32x4*)(vg + (size_t)64 * LP + kbase_); \
;         if (t < 64) br = (NCK[kbase_ + t] + cref) * LOG2E; } while (0)
; DI void attn_prompt_item(const Params& P, unsigned char* lds, int b, int head, int qb, float qkb2) {
;     ...
; #pragma unroll 1
;     ...
;         const int bi = kt % 3;
;         const unsigned char* sb = lds + bi * BUF;
;         {
;             const f32x4 w0 = *(const f32x4*)(WM + ((kt + 1) & 1) * 8), w1 = *(const f32x4*)(WM + ((kt + 1) & 1) * 8 + 4);
;             const float mfloor = fminf(fminf(fminf(w0.x, w0.y), fminf(w0.z, w0.w)), fminf(fminf(w1.x, w1.y), fminf(w1.z, w1.w)));
;             const float blast = *(const float*)(sb + BOFF + 63 * 4);
;             if (blast + qkb2 < mfloor - 32.f) break;
;         }
;         const bool more = kt > 1;
;         if (more) ATT_GLOAD(kt - 1);
.LBB0_1221:
	s_and_b32 s28, s27, 8
	s_xor_b32 s6, s28, 8
	s_lshl_b32 s6, s6, 2
	s_add_i32 s6, s6, 0
	s_add_i32 s6, s6, 0x1b000
	v_mov_b32_e32 v2, s6
	ds_read_b128 v[86:89], v2
	ds_read_b128 v[90:93], v2 offset:16
	s_mul_hi_u32 s6, s24, 0xaaaaaaab
	s_lshr_b32 s30, s6, 1
	s_mul_i32 s6, s30, 0xfffe5000
	s_waitcnt lgkmcnt(1)
	v_max_f32_e32 v2, v87, v87
	v_max_f32_e32 v16, v86, v86
	v_min_f32_e32 v2, v16, v2
	v_max_f32_e32 v16, v89, v89
	v_max_f32_e32 v17, v88, v88
	s_add_i32 s29, s26, s6
	v_min_f32_e32 v17, v17, v16
	v_mov_b32_e32 v16, s29
	ds_read_b32 v16, v16 offset:36092
	s_waitcnt lgkmcnt(1)
	v_max_f32_e32 v86, v93, v93
	v_max_f32_e32 v87, v92, v92
	v_min_f32_e32 v86, v87, v86
	v_min3_f32 v86, v90, v91, v86
	v_min3_f32 v17, v2, v17, v86
	s_waitcnt lgkmcnt(0)
	v_pk_add_f32 v[16:17], v[162:163], v[16:17]
	s_andn2_b64 s[16:17], s[16:17], exec
	s_and_b64 s[18:19], s[0:1], exec
	v_cmp_nlt_f32_e64 s[6:7], v16, v17
	s_or_b64 s[16:17], s[16:17], s[18:19]
	s_and_saveexec_b64 s[18:19], s[6:7]
	s_cbranch_execz .LBB0_1220
	s_cmp_lg_u32 s66, 0
	s_cselect_b64 s[20:21], -1, 0
	s_cmp_eq_u32 s66, 0
	s_cbranch_scc1 .LBB0_1226
	s_lshl_b64 s[22:23], s[66:67], 11
	v_lshl_add_u64 v[16:17], v[170:171], 0, s[22:23]
	s_add_i32 s22, s66, 32
	s_mov_b32 s23, s67
	s_lshl_b64 s[22:23], s[22:23], 11
	v_lshl_add_u64 v[86:87], v[170:171], 0, s[22:23]
	s_lshl_b64 s[22:23], s[66:67], 1
	global_load_dwordx4 v[146:149], v[16:17], off
	global_load_dwordx4 v[150:153], v[86:87], off
	v_lshl_add_u64 v[16:17], v[172:173], 0, s[22:23]
	v_lshl_add_u64 v[86:87], v[174:175], 0, s[22:23]
	global_load_dwordx4 v[154:157], v[16:17], off
	global_load_dwordx4 v[158:161], v[86:87], off
	s_and_saveexec_b64 s[22:23], s[2:3]
	s_cbranch_execz .LBB0_1225
	global_load_dword v252, v[178:179], off

; #define MFMA(a, b, c) __builtin_amdgcn_mfma_f32_32x32x16_bf16((a), (b), (c), 0, 0, 0)
; DI f32x16 zero16() { f32x16 z; for (int i = 0; i < 16; ++i) z[i] = 0.f; return z; }
; DI void attn_prompt_item(const Params& P, unsigned char* lds, int b, int head, int qb, float qkb2) {
;     ...
;             f32x16 st[2];
; #pragma unroll
;             for (int kb = 0; kb < 2; ++kb) {
;                 st[kb] = zero16();
; #pragma unroll
;                 for (int s = 0; s < 8; ++s) {
;                     const bf16x8 a = *(const bf16x8*)(sb + (32 * kb + r) * 272 + (16 * s + 8 * hh) * 2);
;                     st[kb] = MFMA(a, qf[s], st[kb]);
;                 }
;             }
;             const bool need_mask = (kt * 64 + 63 > qw0);
.LBB0_1226:
	s_and_saveexec_b64 s[22:23], s[0:1]
	s_cbranch_execz .LBB0_1228
	v_mad_u64_u32 v[16:17], s[0:1], v203, s60, v[176:177]
	v_add_u32_e32 v2, 0x4000, v16
	ds_read2_b64 v[224:227], v2 offset0:128 offset1:130
	v_add_u32_e32 v17, 0x5000, v16
	ds_read2_b64 v[228:231], v17 offset0:192 offset1:194
	v_add_u32_e32 v90, 0x6800, v16
	ds_read2_b64 v[232:235], v90 offset1:2
	v_add_u32_e32 v16, 0x7800, v16
	ds_read2_b64 v[236:239], v16 offset0:64 offset1:66
	ds_read2_b64 v[240:243], v2 offset0:132 offset1:134
	ds_read2_b64 v[244:247], v17 offset0:196 offset1:198
	ds_read2_b64 v[248:251], v90 offset0:4 offset1:6
	s_waitcnt lgkmcnt(7)
	s_waitcnt lgkmcnt(6)
	v_mfma_f32_32x32x16_bf16 v[66:81], v[224:227], v[82:85], v[66:81]
	ds_read2_b64 v[224:227], v16 offset0:68 offset1:70
	s_waitcnt lgkmcnt(6)
	v_mfma_f32_32x32x16_bf16 v[50:65], v[228:231], v[82:85], v[50:65]
	ds_read2_b64 v[228:231], v2 offset0:136 offset1:138
	s_waitcnt lgkmcnt(6)
	v_mfma_f32_32x32x16_bf16 v[34:49], v[232:235], v[82:85], v[34:49]
	ds_read2_b64 v[232:235], v17 offset0:200 offset1:202
	s_waitcnt lgkmcnt(6)
	v_mfma_f32_32x32x16_bf16 v[18:33], v[236:239], v[82:85], v[18:33]
	ds_read2_b64 v[236:239], v90 offset0:8 offset1:10
	s_waitcnt lgkmcnt(6)
	v_mfma_f32_32x32x16_bf16 v[66:81], v[240:243], v[12:15], v[66:81]
	ds_read2_b64 v[240:243], v16 offset0:72 offset1:74
	s_waitcnt lgkmcnt(6)
	v_mfma_f32_32x32x16_bf16 v[50:65], v[244:247], v[12:15], v[50:65]
	ds_read2_b64 v[244:247], v2 offset0:140 offset1:142
	s_waitcnt lgkmcnt(6)
	v_mfma_f32_32x32x16_bf16 v[34:49], v[248:251], v[12:15], v[34:49]
	ds_read2_b64 v[248:251], v17 offset0:204 offset1:206
	s_waitcnt lgkmcnt(6)
	v_mfma_f32_32x32x16_bf16 v[18:33], v[224:227], v[12:15], v[18:33]
	ds_read2_b64 v[224:227], v90 offset0:12 offset1:14
	s_waitcnt lgkmcnt(6)
	v_mfma_f32_32x32x16_bf16 v[66:81], v[228:231], v[8:11], v[66:81]
	ds_read2_b64 v[228:231], v16 offset0:76 offset1:78
	s_waitcnt lgkmcnt(6)
	v_mfma_f32_32x32x16_bf16 v[50:65], v[232:235], v[8:11], v[50:65]
	s_waitcnt lgkmcnt(5)
	v_mfma_f32_32x32x16_bf16 v[34:49], v[236:239], v[8:11], v[34:49]
	s_waitcnt lgkmcnt(4)
	v_mfma_f32_32x32x16_bf16 v[18:33], v[240:243], v[8:11], v[18:33]
	s_waitcnt lgkmcnt(3)
	v_mfma_f32_32x32x16_bf16 v[66:81], v[244:247], v[4:7], v[66:81]
	s_waitcnt lgkmcnt(2)
	v_mfma_f32_32x32x16_bf16 v[50:65], v[248:251], v[4:7], v[50:65]
	s_waitcnt lgkmcnt(1)
	v_mfma_f32_32x32x16_bf16 v[34:49], v[224:227], v[4:7], v[34:49]
	s_waitcnt lgkmcnt(0)
	v_mfma_f32_32x32x16_bf16 v[18:33], v[228:231], v[4:7], v[18:33]
.LBB0_1228:
	s_or_b64 exec, exec, s[22:23]
	s_add_i32 s0, s66, 64
	v_cmp_le_i32_e32 vcc, s0, v205
	v_mov_b32_e32 v2, 0xf149f2ca
	s_mov_b64 s[0:1], 0
	s_and_saveexec_b64 s[22:23], vcc
	s_cbranch_execz .LBB0_1233
	v_add_u32_e32 v2, s29, v208
	ds_read_b128 v[224:227], v2
	ds_read_b128 v[228:231], v2 offset:32
	ds_read_b128 v[232:235], v2 offset:64
	ds_read_b128 v[236:239], v2 offset:96
	ds_read_b128 v[240:243], v2 offset:128
	ds_read_b128 v[244:247], v2 offset:160
	ds_read_b128 v[248:251], v2 offset:192
	v_add_u32_e32 v12, s29, v210
	s_add_i32 s0, s66, 0x7f
	v_cmp_gt_u32_e32 vcc, s0, v165
	s_waitcnt lgkmcnt(7)
	s_waitcnt lgkmcnt(6)
	v_mfma_f32_32x32x16_bf16 v[98:113], v[224:227], v[114:117], 0
	ds_read_b128 v[224:227], v2 offset:224
	s_waitcnt lgkmcnt(6)
	v_mfma_f32_32x32x16_bf16 v[98:113], v[228:231], v[118:121], v[98:113]
	ds_read_b128 v[228:231], v2 offset:8704
	v_add_u32_e32 v9, s66, v169
	v_add_u32_e32 v8, 64, v9
	v_cmp_gt_i32_e64 s[0:1], v8, v168
	s_and_b64 s[0:1], vcc, s[0:1]
	v_add_u32_e32 v11, 0x49, v9
	s_waitcnt lgkmcnt(6)
	v_mfma_f32_32x32x16_bf16 v[98:113], v[232:235], v[122:125], v[98:113]
	ds_read_b128 v[232:235], v2 offset:8736
	s_waitcnt lgkmcnt(6)
	v_mfma_f32_32x32x16_bf16 v[98:113], v[236:239], v[126:129], v[98:113]
	ds_read_b128 v[236:239], v2 offset:8768
	s_waitcnt lgkmcnt(6)
	v_mfma_f32_32x32x16_bf16 v[98:113], v[240:243], v[130:133], v[98:113]
	ds_read_b128 v[240:243], v2 offset:8800
	s_waitcnt lgkmcnt(6)
	v_mfma_f32_32x32x16_bf16 v[98:113], v[244:247], v[134:137], v[98:113]
	ds_read_b128 v[244:247], v2 offset:8832
	s_waitcnt lgkmcnt(6)
	v_mfma_f32_32x32x16_bf16 v[98:113], v[248:251], v[138:141], v[98:113]
	ds_read_b128 v[248:251], v2 offset:8864
	s_waitcnt lgkmcnt(6)
	v_mfma_f32_32x32x16_bf16 v[98:113], v[224:227], v[142:145], v[98:113]
	ds_read_b128 v[224:227], v2 offset:8896
	s_waitcnt lgkmcnt(6)
	v_mfma_f32_32x32x16_bf16 v[82:97], v[228:231], v[114:117], 0
	ds_read_b128 v[228:231], v2 offset:8928
	s_waitcnt lgkmcnt(6)
	v_mfma_f32_32x32x16_bf16 v[82:97], v[232:235], v[118:121], v[82:97]
	s_waitcnt lgkmcnt(5)
	v_mfma_f32_32x32x16_bf16 v[82:97], v[236:239], v[122:125], v[82:97]
	s_waitcnt lgkmcnt(4)
	v_mfma_f32_32x32x16_bf16 v[82:97], v[240:243], v[126:129], v[82:97]
	s_waitcnt lgkmcnt(3)
	v_mfma_f32_32x32x16_bf16 v[82:97], v[244:247], v[130:133], v[82:97]
	s_waitcnt lgkmcnt(2)
	v_mfma_f32_32x32x16_bf16 v[82:97], v[248:251], v[134:137], v[82:97]
	s_waitcnt lgkmcnt(1)
	v_mfma_f32_32x32x16_bf16 v[82:97], v[224:227], v[138:141], v[82:97]
	s_waitcnt lgkmcnt(0)
	v_mfma_f32_32x32x16_bf16 v[82:97], v[228:231], v[142:145], v[82:97]
	s_cbranch_vccz .Lattn_nomask_0
; DI void attn_prompt_item(const Params& P, unsigned char* lds, int b, int head, int qb, float qkb2) {
;     ...
;             float mx = -1e30f;
; #pragma unroll
;             for (int kb = 0; kb < 2; ++kb)
; #pragma unroll
;                 for (int g = 0; g < 4; ++g) {
;                     const f32x4 bz = *(const f32x4*)(sb + BOFF + (32 * kb + 8 * g + 4 * hh) * 4);
; #pragma unroll
;                     for (int e = 0; e < 4; ++e) {
;                         float v = st[kb][4 * g + e] * ATT_SC + bz[e];
;                         if (need_mask) { const int key = kt * 64 + 32 * kb + 8 * g + 4 * hh + e; v = (key > myq) ? -1e30f : v; }
;                         st[kb][4 * g + e] = v; mx = fmaxf(mx, v);
;                     }
;                 }
;             mx = fmaxf(mx, __shfl_xor(mx, 32));
	ds_read_b128 v[4:7], v12
	ds_read_b128 v[14:17], v12 offset:32
	s_waitcnt lgkmcnt(1)
	v_fmamk_f32 v2, v98, 0x3e0293ee, v4
	v_cndmask_b32_e64 v2, v2, v177, s[0:1]
	v_cmp_ge_i32_e64 s[0:1], v8, v168
	v_fmamk_f32 v4, v99, 0x3e0293ee, v5
	s_and_b64 s[0:1], vcc, s[0:1]
	v_fmamk_f32 v5, v100, 0x3e0293ee, v6
	v_add_u32_e32 v6, 0x42, v9
	v_cndmask_b32_e64 v4, v4, v177, s[0:1]
	v_cmp_gt_i32_e64 s[0:1], v6, v168
	s_and_b64 s[0:1], vcc, s[0:1]
	v_add_u32_e32 v6, 0x43, v9
	v_cndmask_b32_e64 v5, v5, v177, s[0:1]
	v_cmp_gt_i32_e64 s[0:1], v6, v168
	v_fmac_f32_e32 v7, 0x3e0293ee, v101
	s_and_b64 s[0:1], vcc, s[0:1]
	v_cndmask_b32_e64 v6, v7, v177, s[0:1]
	v_add_u32_e32 v7, 0x48, v9
	v_max3_f32 v8, v2, s61, v4
	v_cmp_gt_i32_e64 s[0:1], v7, v168
	v_max3_f32 v10, v8, v5, v6
	s_waitcnt lgkmcnt(0)
	v_fmamk_f32 v8, v102, 0x3e0293ee, v14
	s_and_b64 s[0:1], vcc, s[0:1]
	v_cndmask_b32_e64 v7, v8, v177, s[0:1]
	v_cmp_gt_i32_e64 s[0:1], v11, v168
	v_fmamk_f32 v8, v103, 0x3e0293ee, v15
	s_and_b64 s[0:1], vcc, s[0:1]
	v_add_u32_e32 v11, 0x4a, v9
	v_cndmask_b32_e64 v8, v8, v177, s[0:1]
	v_cmp_gt_i32_e64 s[0:1], v11, v168
	v_max3_f32 v13, v10, v7, v8
	v_fmamk_f32 v10, v104, 0x3e0293ee, v16
	s_and_b64 s[0:1], vcc, s[0:1]
	v_add_u32_e32 v11, 0x4b, v9
	v_cndmask_b32_e64 v10, v10, v177, s[0:1]
	v_cmp_gt_i32_e64 s[0:1], v11, v168
	v_fmac_f32_e32 v17, 0x3e0293ee, v105
	s_and_b64 s[0:1], vcc, s[0:1]
	v_cndmask_b32_e64 v11, v17, v177, s[0:1]
	ds_read_b128 v[14:17], v12 offset:64
	v_max3_f32 v98, v13, v10, v11
	v_add_u32_e32 v13, 0x50, v9
	v_cmp_gt_i32_e64 s[0:1], v13, v168
	s_and_b64 s[0:1], vcc, s[0:1]
	s_waitcnt lgkmcnt(0)
	v_fmamk_f32 v14, v106, 0x3e0293ee, v14
	v_cndmask_b32_e64 v13, v14, v177, s[0:1]
	v_fmamk_f32 v14, v107, 0x3e0293ee, v15
	v_add_u32_e32 v15, 0x51, v9
	v_cmp_gt_i32_e64 s[0:1], v15, v168
	s_and_b64 s[0:1], vcc, s[0:1]
	v_fmamk_f32 v15, v108, 0x3e0293ee, v16
	v_add_u32_e32 v16, 0x52, v9
	v_cndmask_b32_e64 v14, v14, v177, s[0:1]
	v_cmp_gt_i32_e64 s[0:1], v16, v168
	s_and_b64 s[0:1], vcc, s[0:1]
	v_add_u32_e32 v16, 0x53, v9
	v_cndmask_b32_e64 v15, v15, v177, s[0:1]
	v_cmp_gt_i32_e64 s[0:1], v16, v168
	v_fmac_f32_e32 v17, 0x3e0293ee, v109
	s_and_b64 s[0:1], vcc, s[0:1]
	v_max3_f32 v98, v98, v13, v14
	v_cndmask_b32_e64 v16, v17, v177, s[0:1]
	v_max3_f32 v102, v98, v15, v16
	ds_read_b128 v[98:101], v12 offset:96
	v_add_u32_e32 v17, 0x58, v9
	v_cmp_gt_i32_e64 s[0:1], v17, v168
	s_and_b64 s[0:1], vcc, s[0:1]
	v_add_u32_e32 v106, 0x60, v9
	s_waitcnt lgkmcnt(0)
	v_fmamk_f32 v98, v110, 0x3e0293ee, v98
	v_cndmask_b32_e64 v17, v98, v177, s[0:1]
	v_fmamk_f32 v98, v111, 0x3e0293ee, v99
	v_add_u32_e32 v99, 0x59, v9
	v_cmp_gt_i32_e64 s[0:1], v99, v168
	s_and_b64 s[0:1], vcc, s[0:1]
	v_fmamk_f32 v99, v112, 0x3e0293ee, v100
	v_add_u32_e32 v100, 0x5a, v9
	v_cndmask_b32_e64 v98, v98, v177, s[0:1]
	v_cmp_gt_i32_e64 s[0:1], v100, v168
	s_and_b64 s[0:1], vcc, s[0:1]
	v_add_u32_e32 v100, 0x5b, v9
	v_cndmask_b32_e64 v99, v99, v177, s[0:1]
	v_cmp_gt_i32_e64 s[0:1], v100, v168
	v_fmac_f32_e32 v101, 0x3e0293ee, v113
	s_and_b64 s[0:1], vcc, s[0:1]
	v_max3_f32 v102, v102, v17, v98
	v_cndmask_b32_e64 v100, v101, v177, s[0:1]
	v_max3_f32 v101, v102, v99, v100
	ds_read_b128 v[102:105], v12 offset:128
	v_cmp_gt_i32_e64 s[0:1], v106, v168
	s_and_b64 s[0:1], vcc, s[0:1]
	v_add_u32_e32 v106, 0x68, v9
	s_waitcnt lgkmcnt(0)
	v_fmamk_f32 v82, v82, 0x3e0293ee, v102
	v_add_u32_e32 v102, 0x61, v9
	v_cndmask_b32_e64 v82, v82, v177, s[0:1]
	v_cmp_gt_i32_e64 s[0:1], v102, v168
	v_fmamk_f32 v83, v83, 0x3e0293ee, v103
	s_and_b64 s[0:1], vcc, s[0:1]
	v_add_u32_e32 v102, 0x62, v9
	v_cndmask_b32_e64 v83, v83, v177, s[0:1]
	v_cmp_gt_i32_e64 s[0:1], v102, v168
	v_fmamk_f32 v84, v84, 0x3e0293ee, v104
	s_and_b64 s[0:1], vcc, s[0:1]
	v_fmac_f32_e32 v105, 0x3e0293ee, v85
	v_add_u32_e32 v85, 0x63, v9
	v_cndmask_b32_e64 v84, v84, v177, s[0:1]
	v_cmp_gt_i32_e64 s[0:1], v85, v168
	s_and_b64 s[0:1], vcc, s[0:1]
	v_max3_f32 v101, v101, v82, v83
	v_cndmask_b32_e64 v85, v105, v177, s[0:1]
	ds_read_b128 v[102:105], v12 offset:160
	v_cmp_gt_i32_e64 s[0:1], v106, v168
	s_and_b64 s[0:1], vcc, s[0:1]
	v_add_u32_e32 v106, 0x70, v9
	v_max3_f32 v101, v101, v84, v85
	s_waitcnt lgkmcnt(0)
	v_fmamk_f32 v86, v86, 0x3e0293ee, v102
	v_add_u32_e32 v102, 0x69, v9
	v_cndmask_b32_e64 v86, v86, v177, s[0:1]
	v_cmp_gt_i32_e64 s[0:1], v102, v168
	v_fmamk_f32 v87, v87, 0x3e0293ee, v103
	s_and_b64 s[0:1], vcc, s[0:1]
	v_add_u32_e32 v102, 0x6a, v9
	v_cndmask_b32_e64 v87, v87, v177, s[0:1]
	v_cmp_gt_i32_e64 s[0:1], v102, v168
	v_fmamk_f32 v88, v88, 0x3e0293ee, v104
	s_and_b64 s[0:1], vcc, s[0:1]
	v_fmac_f32_e32 v105, 0x3e0293ee, v89
	v_add_u32_e32 v89, 0x6b, v9
	v_cndmask_b32_e64 v88, v88, v177, s[0:1]
	v_cmp_gt_i32_e64 s[0:1], v89, v168
	s_and_b64 s[0:1], vcc, s[0:1]
	v_max3_f32 v101, v101, v86, v87
	v_cndmask_b32_e64 v89, v105, v177, s[0:1]
	ds_read_b128 v[102:105], v12 offset:192
	v_cmp_gt_i32_e64 s[0:1], v106, v168
	s_and_b64 s[0:1], vcc, s[0:1]
	v_max3_f32 v101, v101, v88, v89
	s_waitcnt lgkmcnt(0)
	v_fmamk_f32 v90, v90, 0x3e0293ee, v102
	v_add_u32_e32 v102, 0x71, v9
	v_cndmask_b32_e64 v90, v90, v177, s[0:1]
	v_cmp_gt_i32_e64 s[0:1], v102, v168
	v_fmamk_f32 v91, v91, 0x3e0293ee, v103
	s_and_b64 s[0:1], vcc, s[0:1]
	v_add_u32_e32 v102, 0x72, v9
	v_cndmask_b32_e64 v91, v91, v177, s[0:1]
	v_cmp_gt_i32_e64 s[0:1], v102, v168
	v_fmamk_f32 v92, v92, 0x3e0293ee, v104
	s_and_b64 s[0:1], vcc, s[0:1]
	v_fmac_f32_e32 v105, 0x3e0293ee, v93
	v_add_u32_e32 v93, 0x73, v9
	v_cndmask_b32_e64 v92, v92, v177, s[0:1]
	v_cmp_gt_i32_e64 s[0:1], v93, v168
	s_and_b64 s[0:1], vcc, s[0:1]
	v_max3_f32 v101, v101, v90, v91
	v_cndmask_b32_e64 v93, v105, v177, s[0:1]
	ds_read_b128 v[102:105], v12 offset:224
	v_add_u32_e32 v12, 0x78, v9
	v_cmp_gt_i32_e64 s[0:1], v12, v168
	s_and_b64 s[0:1], vcc, s[0:1]
	v_max3_f32 v106, v101, v92, v93
	s_waitcnt lgkmcnt(0)
	v_fmamk_f32 v94, v94, 0x3e0293ee, v102
	v_cndmask_b32_e64 v12, v94, v177, s[0:1]
	v_fmamk_f32 v94, v95, 0x3e0293ee, v103
	v_add_u32_e32 v95, 0x79, v9
	v_cmp_gt_i32_e64 s[0:1], v95, v168
	s_and_b64 s[0:1], vcc, s[0:1]
	v_fmamk_f32 v95, v96, 0x3e0293ee, v104
	v_add_u32_e32 v96, 0x7a, v9
	v_cndmask_b32_e64 v101, v94, v177, s[0:1]
	v_cmp_gt_i32_e64 s[0:1], v96, v168
	s_and_b64 s[0:1], vcc, s[0:1]
	v_add_u32_e32 v9, 0x7b, v9
	v_cndmask_b32_e64 v214, v95, v177, s[0:1]
	v_cmp_gt_i32_e64 s[0:1], v9, v168
	v_fmac_f32_e32 v105, 0x3e0293ee, v97
	s_and_b64 vcc, vcc, s[0:1]
	v_max3_f32 v94, v106, v12, v101
	v_cndmask_b32_e32 v9, v105, v177, vcc
	v_max3_f32 v94, v94, v214, v9
	s_branch .Lattn_join_0
; DI float ex2(float x) { return __builtin_amdgcn_exp2f(x); }
; DI void attn_prompt_item(const Params& P, unsigned char* lds, int b, int head, int qb, float qkb2) {
;     ...
;             float mx = -1e30f;
; #pragma unroll
;             for (int kb = 0; kb < 2; ++kb)
; #pragma unroll
;                 for (int g = 0; g < 4; ++g) {
;                     const f32x4 bz = *(const f32x4*)(sb + BOFF + (32 * kb + 8 * g + 4 * hh) * 4);
; #pragma unroll
;                     for (int e = 0; e < 4; ++e) {
;                         float v = st[kb][4 * g + e] * ATT_SC + bz[e];
;                         if (need_mask) { const int key = kt * 64 + 32 * kb + 8 * g + 4 * hh + e; v = (key > myq) ? -1e30f : v; }
;                         st[kb][4 * g + e] = v; mx = fmaxf(mx, v);
;                     }
;                 }
;             mx = fmaxf(mx, __shfl_xor(mx, 32));
;             const float m_new = fmaxf(m_run, mx);
;             const bool grew = __builtin_amdgcn_ballot_w64(m_new > m_run) != 0ull;
;             float ps = 0.f;
; #pragma unroll
;             for (int kb = 0; kb < 2; ++kb)
; #pragma unroll
;                 for (int i = 0; i < 16; ++i) { const float pv = ex2(st[kb][i] - m_new); st[kb][i] = pv; ps += pv; }
;             if (grew) {
;                 const float alpha = ex2(m_run - m_new); m_run = m_new;
;                 l_run = l_run * alpha;
; #pragma unroll
;                 for (int db = 0; db < 4; ++db) o[db] = o[db] * alpha;
.Lattn_nomask_0:
	ds_read_b128 v[4:7], v12
	ds_read_b128 v[14:17], v12 offset:32
	s_waitcnt lgkmcnt(1)
	v_fmamk_f32 v2, v98, 0x3e0293ee, v4
	v_fmamk_f32 v4, v99, 0x3e0293ee, v5
	v_fmamk_f32 v5, v100, 0x3e0293ee, v6
	v_fmac_f32_e32 v7, 0x3e0293ee, v101
	v_mov_b32_e32 v6, v7
	v_max3_f32 v8, v2, s61, v4
	v_max3_f32 v10, v8, v5, v6
	s_waitcnt lgkmcnt(0)
	v_fmamk_f32 v8, v102, 0x3e0293ee, v14
	v_mov_b32_e32 v7, v8
	v_fmamk_f32 v8, v103, 0x3e0293ee, v15
	v_max3_f32 v13, v10, v7, v8
	v_fmamk_f32 v10, v104, 0x3e0293ee, v16
	v_fmac_f32_e32 v17, 0x3e0293ee, v105
	v_mov_b32_e32 v11, v17
	ds_read_b128 v[14:17], v12 offset:64
	v_max3_f32 v98, v13, v10, v11
	s_waitcnt lgkmcnt(0)
	v_fmamk_f32 v14, v106, 0x3e0293ee, v14
	v_mov_b32_e32 v13, v14
	v_fmamk_f32 v14, v107, 0x3e0293ee, v15
	v_fmamk_f32 v15, v108, 0x3e0293ee, v16
	v_fmac_f32_e32 v17, 0x3e0293ee, v109
	v_max3_f32 v98, v98, v13, v14
	v_mov_b32_e32 v16, v17
	v_max3_f32 v102, v98, v15, v16
	ds_read_b128 v[98:101], v12 offset:96
	s_waitcnt lgkmcnt(0)
	v_fmamk_f32 v98, v110, 0x3e0293ee, v98
	v_mov_b32_e32 v17, v98
	v_fmamk_f32 v98, v111, 0x3e0293ee, v99
	v_fmamk_f32 v99, v112, 0x3e0293ee, v100
	v_fmac_f32_e32 v101, 0x3e0293ee, v113
	v_max3_f32 v102, v102, v17, v98
	v_mov_b32_e32 v100, v101
	v_max3_f32 v101, v102, v99, v100
	ds_read_b128 v[102:105], v12 offset:128
	s_waitcnt lgkmcnt(0)
	v_fmamk_f32 v82, v82, 0x3e0293ee, v102
	v_fmamk_f32 v83, v83, 0x3e0293ee, v103
	v_fmamk_f32 v84, v84, 0x3e0293ee, v104
	v_fmac_f32_e32 v105, 0x3e0293ee, v85
	v_max3_f32 v101, v101, v82, v83
	v_mov_b32_e32 v85, v105
	ds_read_b128 v[102:105], v12 offset:160
	v_max3_f32 v101, v101, v84, v85
	s_waitcnt lgkmcnt(0)
	v_fmamk_f32 v86, v86, 0x3e0293ee, v102
	v_fmamk_f32 v87, v87, 0x3e0293ee, v103
	v_fmamk_f32 v88, v88, 0x3e0293ee, v104
	v_fmac_f32_e32 v105, 0x3e0293ee, v89
	v_max3_f32 v101, v101, v86, v87
	v_mov_b32_e32 v89, v105
	ds_read_b128 v[102:105], v12 offset:192
	v_max3_f32 v101, v101, v88, v89
	s_waitcnt lgkmcnt(0)
	v_fmamk_f32 v90, v90, 0x3e0293ee, v102
	v_fmamk_f32 v91, v91, 0x3e0293ee, v103
	v_fmamk_f32 v92, v92, 0x3e0293ee, v104
	v_fmac_f32_e32 v105, 0x3e0293ee, v93
	v_max3_f32 v101, v101, v90, v91
	v_mov_b32_e32 v93, v105
	ds_read_b128 v[102:105], v12 offset:224
	v_max3_f32 v106, v101, v92, v93
	s_waitcnt lgkmcnt(0)
	v_fmamk_f32 v94, v94, 0x3e0293ee, v102
	v_mov_b32_e32 v12, v94
	v_fmamk_f32 v94, v95, 0x3e0293ee, v103
	v_fmamk_f32 v95, v96, 0x3e0293ee, v104
	v_mov_b32_e32 v101, v94
	v_mov_b32_e32 v214, v95
	v_fmac_f32_e32 v105, 0x3e0293ee, v97
	v_max3_f32 v94, v106, v12, v101
	v_mov_b32_e32 v9, v105
	v_max3_f32 v94, v94, v214, v9
.Lattn_join_0:
	ds_bpermute_b32 v95, v186, v94
	s_waitcnt lgkmcnt(0)
	v_max3_f32 v215, v212, v94, v95
	v_cmp_gt_f32_e32 vcc, v215, v212
	s_cbranch_vccz .LBB0_1231
	v_sub_f32_e32 v94, v212, v215
	v_exp_f32_e32 v94, v94
	v_mov_b32_e32 v212, v215
	v_pk_mul_f32 v[80:81], v[80:81], v[94:95] op_sel_hi:[1,0]
	v_pk_mul_f32 v[78:79], v[78:79], v[94:95] op_sel_hi:[1,0]
	v_pk_mul_f32 v[76:77], v[76:77], v[94:95] op_sel_hi:[1,0]
	v_pk_mul_f32 v[74:75], v[74:75], v[94:95] op_sel_hi:[1,0]
	v_pk_mul_f32 v[72:73], v[72:73], v[94:95] op_sel_hi:[1,0]
	v_pk_mul_f32 v[70:71], v[70:71], v[94:95] op_sel_hi:[1,0]
	v_pk_mul_f32 v[68:69], v[68:69], v[94:95] op_sel_hi:[1,0]
	v_pk_mul_f32 v[66:67], v[66:67], v[94:95] op_sel_hi:[1,0]
	v_pk_mul_f32 v[64:65], v[64:65], v[94:95] op_sel_hi:[1,0]
	v_pk_mul_f32 v[62:63], v[62:63], v[94:95] op_sel_hi:[1,0]
	v_pk_mul_f32 v[60:61], v[60:61], v[94:95] op_sel_hi:[1,0]
	v_pk_mul_f32 v[58:59], v[58:59], v[94:95] op_sel_hi:[1,0]
	v_pk_mul_f32 v[56:57], v[56:57], v[94:95] op_sel_hi:[1,0]
	v_pk_mul_f32 v[54:55], v[54:55], v[94:95] op_sel_hi:[1,0]
	v_pk_mul_f32 v[52:53], v[52:53], v[94:95] op_sel_hi:[1,0]
	v_pk_mul_f32 v[50:51], v[50:51], v[94:95] op_sel_hi:[1,0]
	v_pk_mul_f32 v[48:49], v[48:49], v[94:95] op_sel_hi:[1,0]
	v_pk_mul_f32 v[46:47], v[46:47], v[94:95] op_sel_hi:[1,0]
	v_pk_mul_f32 v[44:45], v[44:45], v[94:95] op_sel_hi:[1,0]
	v_pk_mul_f32 v[42:43], v[42:43], v[94:95] op_sel_hi:[1,0]
	v_pk_mul_f32 v[40:41], v[40:41], v[94:95] op_sel_hi:[1,0]
	v_pk_mul_f32 v[38:39], v[38:39], v[94:95] op_sel_hi:[1,0]
	v_pk_mul_f32 v[36:37], v[36:37], v[94:95] op_sel_hi:[1,0]
	v_pk_mul_f32 v[34:35], v[34:35], v[94:95] op_sel_hi:[1,0]
	v_pk_mul_f32 v[32:33], v[32:33], v[94:95] op_sel_hi:[1,0]
	v_pk_mul_f32 v[30:31], v[30:31], v[94:95] op_sel_hi:[1,0]
	v_pk_mul_f32 v[28:29], v[28:29], v[94:95] op_sel_hi:[1,0]
	v_pk_mul_f32 v[26:27], v[26:27], v[94:95] op_sel_hi:[1,0]
	v_pk_mul_f32 v[24:25], v[24:25], v[94:95] op_sel_hi:[1,0]
	v_pk_mul_f32 v[22:23], v[22:23], v[94:95] op_sel_hi:[1,0]
	v_pk_mul_f32 v[20:21], v[20:21], v[94:95] op_sel_hi:[1,0]
	v_pk_mul_f32 v[18:19], v[18:19], v[94:95] op_sel_hi:[1,0]
	v_mul_f32_e32 v199, v199, v94
; DI float ex2(float x) { return __builtin_amdgcn_exp2f(x); }
; DI void attn_prompt_item(const Params& P, unsigned char* lds, int b, int head, int qb, float qkb2) {
;     ...
;             float ps = 0.f;
; #pragma unroll
;             for (int kb = 0; kb < 2; ++kb)
; #pragma unroll
;                 for (int i = 0; i < 16; ++i) { const float pv = ex2(st[kb][i] - m_new); st[kb][i] = pv; ps += pv; }
;             if (grew) {
;                 const float alpha = ex2(m_run - m_new); m_run = m_new;
;                 l_run = l_run * alpha;
; #pragma unroll
;                 for (int db = 0; db < 4; ++db) o[db] = o[db] * alpha;
;             }
;             l_run += ps;
; #pragma unroll
;             for (int kb = 0; kb < 2; ++kb)
; #pragma unroll
;                 for (int sp = 0; sp < 2; ++sp) pp[kb][sp] = pack8(st[kb], sp);
;             if (late) { pending = true; pbuf = bi; }
;             else ATT_PV(sb, pp);
.LBB0_1231:
	v_sub_f32_e32 v2, v2, v215
	v_exp_f32_e32 v102, v2
	v_sub_f32_e32 v2, v4, v215
	v_exp_f32_e32 v103, v2
	v_sub_f32_e32 v2, v5, v215
	v_exp_f32_e32 v104, v2
	v_sub_f32_e32 v2, v6, v215
	v_exp_f32_e32 v105, v2
	v_sub_f32_e32 v2, v7, v215
	v_exp_f32_e32 v106, v2
	v_sub_f32_e32 v2, v8, v215
	v_exp_f32_e32 v107, v2
	v_sub_f32_e32 v2, v10, v215
	v_exp_f32_e32 v108, v2
	v_sub_f32_e32 v2, v11, v215
	v_exp_f32_e32 v109, v2
	v_sub_f32_e32 v2, v13, v215
	v_exp_f32_e32 v110, v2
	v_sub_f32_e32 v2, v14, v215
	v_exp_f32_e32 v111, v2
	v_sub_f32_e32 v2, v15, v215
	v_exp_f32_e32 v112, v2
	v_sub_f32_e32 v2, v16, v215
	v_sub_f32_e32 v4, v99, v215
	v_exp_f32_e32 v113, v2
	v_sub_f32_e32 v2, v17, v215
	v_exp_f32_e32 v17, v4
	v_sub_f32_e32 v4, v100, v215
	v_exp_f32_e32 v95, v4
	v_sub_f32_e32 v4, v82, v215
	v_exp_f32_e32 v97, v4
	v_sub_f32_e32 v4, v83, v215
	v_exp_f32_e32 v16, v4
	v_sub_f32_e32 v4, v84, v215
	v_exp_f32_e32 v94, v4
	v_sub_f32_e32 v4, v85, v215
	v_exp_f32_e32 v96, v4
	v_sub_f32_e32 v4, v86, v215
	v_exp_f32_e32 v213, v2
	v_sub_f32_e32 v2, v98, v215
	v_exp_f32_e32 v98, v4
	v_sub_f32_e32 v4, v87, v215
	v_exp_f32_e32 v86, v4
	v_sub_f32_e32 v4, v88, v215
	v_exp_f32_e32 v87, v4
	v_sub_f32_e32 v4, v89, v215
	v_exp_f32_e32 v89, v4
	v_sub_f32_e32 v4, v90, v215
	v_exp_f32_e32 v99, v4
	v_sub_f32_e32 v4, v91, v215
	v_exp_f32_e32 v88, v4
	v_sub_f32_e32 v4, v92, v215
	v_exp_f32_e32 v90, v4
	v_sub_f32_e32 v4, v93, v215
	v_exp_f32_e32 v92, v4
	v_sub_f32_e32 v4, v12, v215
	v_exp_f32_e32 v100, v4
	v_sub_f32_e32 v4, v101, v215
	v_exp_f32_e32 v91, v4
	v_sub_f32_e32 v4, v214, v215
	v_exp_f32_e32 v93, v4
	v_sub_f32_e32 v4, v9, v215
	v_exp_f32_e32 v2, v2
	v_exp_f32_e32 v101, v4
	s_mul_i32 s30, s30, 3
	s_sub_i32 s0, s24, s30
	v_cvt_pk_bf16_f32 v82, v102, v103
	v_cvt_pk_bf16_f32 v83, v104, v105
	v_cvt_pk_bf16_f32 v84, v106, v107
	v_cvt_pk_bf16_f32 v85, v108, v109
	v_cvt_pk_bf16_f32 v12, v110, v111
	v_cvt_pk_bf16_f32 v13, v112, v113
	v_cvt_pk_bf16_f32 v14, v213, v2
	v_cvt_pk_bf16_f32 v15, v17, v95
	v_cvt_pk_bf16_f32 v8, v97, v16
	v_cvt_pk_bf16_f32 v9, v94, v96
	v_cvt_pk_bf16_f32 v10, v98, v86
	v_cvt_pk_bf16_f32 v11, v87, v89
	v_cvt_pk_bf16_f32 v4, v99, v88
	v_cvt_pk_bf16_f32 v5, v90, v92
	v_cvt_pk_bf16_f32 v6, v100, v91
	v_cvt_pk_bf16_f32 v7, v93, v101
	s_andn2_b64 vcc, exec, s[10:11]
	s_cbranch_vccnz .LBB0_1235
	v_add_u32_e32 v218, s29, v211
	v_add_u32_e32 v219, 0x4000, v218
	ds_read2_b64 v[224:227], v219 offset0:128 offset1:130
	v_add_u32_e32 v220, 0x5000, v218
	ds_read2_b64 v[228:231], v220 offset0:192 offset1:194
	v_add_u32_e32 v221, 0x6800, v218
	ds_read2_b64 v[232:235], v221 offset1:2
	v_add_u32_e32 v218, 0x7800, v218
	ds_read2_b64 v[236:239], v218 offset0:64 offset1:66
	ds_read2_b64 v[240:243], v219 offset0:132 offset1:134
	ds_read2_b64 v[244:247], v220 offset0:196 offset1:198
	ds_read2_b64 v[248:251], v221 offset0:4 offset1:6
	s_waitcnt lgkmcnt(7)
	s_waitcnt lgkmcnt(6)
	v_mfma_f32_32x32x16_bf16 v[66:81], v[224:227], v[82:85], v[66:81]
	ds_read2_b64 v[224:227], v218 offset0:68 offset1:70
	s_waitcnt lgkmcnt(6)
	v_mfma_f32_32x32x16_bf16 v[50:65], v[228:231], v[82:85], v[50:65]
	ds_read2_b64 v[228:231], v219 offset0:136 offset1:138
	s_waitcnt lgkmcnt(6)
	v_mfma_f32_32x32x16_bf16 v[34:49], v[232:235], v[82:85], v[34:49]
	ds_read2_b64 v[232:235], v220 offset0:200 offset1:202
	s_waitcnt lgkmcnt(6)
	v_mfma_f32_32x32x16_bf16 v[18:33], v[236:239], v[82:85], v[18:33]
	ds_read2_b64 v[236:239], v221 offset0:8 offset1:10
	s_waitcnt lgkmcnt(6)
	v_mfma_f32_32x32x16_bf16 v[66:81], v[240:243], v[12:15], v[66:81]
	ds_read2_b64 v[240:243], v218 offset0:72 offset1:74
	s_waitcnt lgkmcnt(6)
	v_mfma_f32_32x32x16_bf16 v[50:65], v[244:247], v[12:15], v[50:65]
	ds_read2_b64 v[244:247], v219 offset0:140 offset1:142
	s_waitcnt lgkmcnt(6)
	v_mfma_f32_32x32x16_bf16 v[34:49], v[248:251], v[12:15], v[34:49]
	ds_read2_b64 v[248:251], v220 offset0:204 offset1:206
	s_waitcnt lgkmcnt(6)
	v_mfma_f32_32x32x16_bf16 v[18:33], v[224:227], v[12:15], v[18:33]
	ds_read2_b64 v[224:227], v221 offset0:12 offset1:14
	s_waitcnt lgkmcnt(6)
	v_mfma_f32_32x32x16_bf16 v[66:81], v[228:231], v[8:11], v[66:81]
	ds_read2_b64 v[228:231], v218 offset0:76 offset1:78
	s_waitcnt lgkmcnt(6)
	v_mfma_f32_32x32x16_bf16 v[50:65], v[232:235], v[8:11], v[50:65]
	s_waitcnt lgkmcnt(5)
	v_mfma_f32_32x32x16_bf16 v[34:49], v[236:239], v[8:11], v[34:49]
	s_waitcnt lgkmcnt(4)
	v_mfma_f32_32x32x16_bf16 v[18:33], v[240:243], v[8:11], v[18:33]
	s_waitcnt lgkmcnt(3)
	v_mfma_f32_32x32x16_bf16 v[66:81], v[244:247], v[4:7], v[66:81]
	s_waitcnt lgkmcnt(2)
	v_mfma_f32_32x32x16_bf16 v[50:65], v[248:251], v[4:7], v[50:65]
	s_waitcnt lgkmcnt(1)
	v_mfma_f32_32x32x16_bf16 v[34:49], v[224:227], v[4:7], v[34:49]
	s_waitcnt lgkmcnt(0)
	v_mfma_f32_32x32x16_bf16 v[18:33], v[228:231], v[4:7], v[18:33]
	s_branch .LBB0_1236

; DI void attn_prompt_item(const Params& P, unsigned char* lds, int b, int head, int qb, float qkb2) {
;     ...
;     if (pending) ATT_PV(lds + pbuf * BUF, pp);
.LBB0_1238:
	s_mul_hi_u32 s20, s25, 0xaaaaaaab
	s_lshr_b32 s20, s20, 1
	s_mul_i32 s20, s20, 0xfffe5000
	s_add_i32 s22, s26, s20
	v_add_u32_e32 v2, s22, v209
	v_add_u32_e32 v16, 0xffff7000, v2
	v_add_u32_e32 v2, 0xffff9200, v2
	s_waitcnt vmcnt(2)
	ds_write_b128 v2, v[150:153]
	v_add_u32_e32 v2, s22, v207
	ds_write_b128 v16, v[146:149]
	v_add_u32_e32 v16, 0xffffb400, v2
	v_add_u32_e32 v2, 0xffffd800, v2
	s_waitcnt vmcnt(1)
	ds_write_b128 v16, v[154:157]
	s_waitcnt vmcnt(0)
	ds_write_b128 v2, v[158:161]
	s_and_saveexec_b64 s[20:21], s[2:3]
	s_cbranch_execz .LBB0_1218
	v_sub_f32_e32 v252, v252, v198
	v_mul_f32_e32 v200, 0x3fb8aa3b, v252
	v_add_u32_e32 v2, s22, v206
	ds_write_b32 v2, v200
	s_branch .LBB0_1218
.LBB0_1240:
	s_or_b64 exec, exec, s[14:15]
	s_and_saveexec_b64 s[0:1], s[12:13]
	s_cbranch_execz .LBB0_1242
	v_mul_lo_u32 v2, v203, s60
	v_add_u32_e32 v2, 0, v2
	v_add3_u32 v2, v2, v201, v202
	v_add_u32_e32 v16, 0x4000, v2
	ds_read2_b64 v[224:227], v16 offset0:128 offset1:130
	v_add_u32_e32 v17, 0x5000, v2
	ds_read2_b64 v[228:231], v17 offset0:192 offset1:194
	v_add_u32_e32 v90, 0x6800, v2
	ds_read2_b64 v[232:235], v90 offset1:2
	v_add_u32_e32 v2, 0x7800, v2
	ds_read2_b64 v[236:239], v2 offset0:64 offset1:66
	ds_read2_b64 v[240:243], v16 offset0:132 offset1:134
	ds_read2_b64 v[244:247], v17 offset0:196 offset1:198
	ds_read2_b64 v[248:251], v90 offset0:4 offset1:6
	s_waitcnt lgkmcnt(7)
	s_waitcnt lgkmcnt(6)
	v_mfma_f32_32x32x16_bf16 v[66:81], v[224:227], v[82:85], v[66:81]
	ds_read2_b64 v[224:227], v2 offset0:68 offset1:70
	s_waitcnt lgkmcnt(6)
	v_mfma_f32_32x32x16_bf16 v[50:65], v[228:231], v[82:85], v[50:65]
	ds_read2_b64 v[228:231], v16 offset0:136 offset1:138
	s_waitcnt lgkmcnt(6)
	v_mfma_f32_32x32x16_bf16 v[34:49], v[232:235], v[82:85], v[34:49]
	ds_read2_b64 v[232:235], v17 offset0:200 offset1:202
	s_waitcnt lgkmcnt(6)
	v_mfma_f32_32x32x16_bf16 v[18:33], v[236:239], v[82:85], v[18:33]
	ds_read2_b64 v[236:239], v90 offset0:8 offset1:10
	s_waitcnt lgkmcnt(6)
	v_mfma_f32_32x32x16_bf16 v[66:81], v[240:243], v[12:15], v[66:81]
	ds_read2_b64 v[240:243], v2 offset0:72 offset1:74
	s_waitcnt lgkmcnt(6)
	v_mfma_f32_32x32x16_bf16 v[50:65], v[244:247], v[12:15], v[50:65]
	ds_read2_b64 v[244:247], v16 offset0:140 offset1:142
	s_waitcnt lgkmcnt(6)
	v_mfma_f32_32x32x16_bf16 v[34:49], v[248:251], v[12:15], v[34:49]
	ds_read2_b64 v[248:251], v17 offset0:204 offset1:206
	s_waitcnt lgkmcnt(6)
	v_mfma_f32_32x32x16_bf16 v[18:33], v[224:227], v[12:15], v[18:33]
	ds_read2_b64 v[224:227], v90 offset0:12 offset1:14
	s_waitcnt lgkmcnt(6)
	v_mfma_f32_32x32x16_bf16 v[66:81], v[228:231], v[8:11], v[66:81]
	ds_read2_b64 v[228:231], v2 offset0:76 offset1:78
	s_waitcnt lgkmcnt(6)
	v_mfma_f32_32x32x16_bf16 v[50:65], v[232:235], v[8:11], v[50:65]
	s_waitcnt lgkmcnt(5)
	v_mfma_f32_32x32x16_bf16 v[34:49], v[236:239], v[8:11], v[34:49]
	s_waitcnt lgkmcnt(4)
	v_mfma_f32_32x32x16_bf16 v[18:33], v[240:243], v[8:11], v[18:33]
	s_waitcnt lgkmcnt(3)
	v_mfma_f32_32x32x16_bf16 v[66:81], v[244:247], v[4:7], v[66:81]
	s_waitcnt lgkmcnt(2)
	v_mfma_f32_32x32x16_bf16 v[50:65], v[248:251], v[4:7], v[50:65]
	s_waitcnt lgkmcnt(1)
	v_mfma_f32_32x32x16_bf16 v[34:49], v[224:227], v[4:7], v[34:49]
	s_waitcnt lgkmcnt(0)
	v_mfma_f32_32x32x16_bf16 v[18:33], v[228:231], v[4:7], v[18:33]

; DI void attn_prompt_item(const Params& P, unsigned char* lds, int b, int head, int qb, float qkb2) {
;     ...
;     if (pending) ATT_PV(lds + pbuf * BUF, pp);
.LBB0_1318:
	s_or_b64 exec, exec, s[14:15]
	s_and_saveexec_b64 s[0:1], s[12:13]
	s_cbranch_execz .LBB0_1197
	v_mul_lo_u32 v2, v203, s60
	v_add_u32_e32 v2, 0, v2
	v_add3_u32 v2, v2, v201, v202
	v_add_u32_e32 v16, 0x4000, v2
	ds_read2_b64 v[224:227], v16 offset0:128 offset1:130
	v_add_u32_e32 v17, 0x5000, v2
	ds_read2_b64 v[228:231], v17 offset0:192 offset1:194
	v_add_u32_e32 v90, 0x6800, v2
	ds_read2_b64 v[232:235], v90 offset1:2
	v_add_u32_e32 v2, 0x7800, v2
	ds_read2_b64 v[236:239], v2 offset0:64 offset1:66
	ds_read2_b64 v[240:243], v16 offset0:132 offset1:134
	ds_read2_b64 v[244:247], v17 offset0:196 offset1:198
	ds_read2_b64 v[248:251], v90 offset0:4 offset1:6
	s_waitcnt lgkmcnt(7)
	s_waitcnt lgkmcnt(6)
	v_mfma_f32_32x32x16_bf16 v[66:81], v[224:227], v[82:85], v[66:81]
	ds_read2_b64 v[224:227], v2 offset0:68 offset1:70
	s_waitcnt lgkmcnt(6)
	v_mfma_f32_32x32x16_bf16 v[50:65], v[228:231], v[82:85], v[50:65]
	ds_read2_b64 v[228:231], v16 offset0:136 offset1:138
	s_waitcnt lgkmcnt(6)
	v_mfma_f32_32x32x16_bf16 v[34:49], v[232:235], v[82:85], v[34:49]
	ds_read2_b64 v[232:235], v17 offset0:200 offset1:202
	s_waitcnt lgkmcnt(6)
	v_mfma_f32_32x32x16_bf16 v[18:33], v[236:239], v[82:85], v[18:33]
	ds_read2_b64 v[236:239], v90 offset0:8 offset1:10
	s_waitcnt lgkmcnt(6)
	v_mfma_f32_32x32x16_bf16 v[66:81], v[240:243], v[12:15], v[66:81]
	ds_read2_b64 v[240:243], v2 offset0:72 offset1:74
	s_waitcnt lgkmcnt(6)
	v_mfma_f32_32x32x16_bf16 v[50:65], v[244:247], v[12:15], v[50:65]
	ds_read2_b64 v[244:247], v16 offset0:140 offset1:142
	s_waitcnt lgkmcnt(6)
	v_mfma_f32_32x32x16_bf16 v[34:49], v[248:251], v[12:15], v[34:49]
	ds_read2_b64 v[248:251], v17 offset0:204 offset1:206
	s_waitcnt lgkmcnt(6)
	v_mfma_f32_32x32x16_bf16 v[18:33], v[224:227], v[12:15], v[18:33]
	ds_read2_b64 v[224:227], v90 offset0:12 offset1:14
	s_waitcnt lgkmcnt(6)
	v_mfma_f32_32x32x16_bf16 v[66:81], v[228:231], v[8:11], v[66:81]
	ds_read2_b64 v[228:231], v2 offset0:76 offset1:78
	s_waitcnt lgkmcnt(6)
	v_mfma_f32_32x32x16_bf16 v[50:65], v[232:235], v[8:11], v[50:65]
	s_waitcnt lgkmcnt(5)
	v_mfma_f32_32x32x16_bf16 v[34:49], v[236:239], v[8:11], v[34:49]
	s_waitcnt lgkmcnt(4)
	v_mfma_f32_32x32x16_bf16 v[18:33], v[240:243], v[8:11], v[18:33]
	s_waitcnt lgkmcnt(3)
	v_mfma_f32_32x32x16_bf16 v[66:81], v[244:247], v[4:7], v[66:81]
	s_waitcnt lgkmcnt(2)
	v_mfma_f32_32x32x16_bf16 v[50:65], v[248:251], v[4:7], v[50:65]
	s_waitcnt lgkmcnt(1)
	v_mfma_f32_32x32x16_bf16 v[34:49], v[224:227], v[4:7], v[34:49]
	s_waitcnt lgkmcnt(0)
	v_mfma_f32_32x32x16_bf16 v[18:33], v[228:231], v[4:7], v[18:33]
	s_branch .LBB0_1197

; DI int opaque_tid() { int t = threadIdx.x; asm volatile("" : "+v"(t)); return t; }
; #define GEMM_ISSUE(KT, ST) do { const int k1_ = (KT) << 6; unsigned char* d_ = ldst + (ST) * STAGE; \
;         _Pragma("unroll") for (int j_ = 0; j_ < 4; ++j_) dma16(ap + (size_t)(64 * j_) * lda + k1_, d_ + j_ * 8192); \
;         _Pragma("unroll") for (int j_ = 0; j_ < NBW; ++j_) dma16(bp + bro[j_] + k1_, d_ + BOFF + j_ * 8192); } while (0)
; template <int NBW>
; DI void gemm_mainloop(f32x16 (&acc)[2][NBW], const bf16_t* A, size_t lda, int m0, const bf16_t* Bt, size_t ldb, int n0, int K, unsigned char* lds, bool pre = false, bool only_issue = false) {
;     ...
;     const int t = opaque_tid(), w = t >> 6, lane = t & 63, r = lane & 31, hh = lane >> 5, wm = w >> 1, wn = w & 1;
;     const int drow = w * 8 + (lane >> 3);
;     const int lchunk = (lane & 7) ^ ((drow >> 1) & 7);
;     const bf16_t* ap = A + (size_t)(m0 + drow) * lda + lchunk * 8;
;     const bf16_t* bp = Bt + (size_t)n0 * ldb + lchunk * 8;
;     size_t bro[NBW];
; #pragma unroll
;     for (int j = 0; j < NBW; ++j) {
;         const int rho = 64 * j + drow; const int wnh = rho / (32 * NBW), wi = rho % (32 * NBW);
;         bro[j] = (size_t)(wnh * 32 * NBW + NBW * (wi & 31) + (wi >> 5)) * ldb;
;     }
;     unsigned char* ldst = lds + w * 1024 + lane * 16;
;     ...
;     if (!pre) GEMM_ISSUE(0, 0);
.LBB0_1396:
	v_mov_b32_e32 v4, v1
	s_ashr_i32 s64, s82, 31
	v_ashrrev_i32_e32 v13, 6, v4
	v_lshlrev_b32_e32 v5, 3, v13
	v_bfe_u32 v8, v4, 3, 3
	v_or_b32_e32 v10, v5, v8
	v_lshrrev_b32_e32 v2, 1, v10
	v_xor_b32_e32 v14, v2, v4
	v_ashrrev_i32_e32 v2, 31, v4
	v_lshrrev_b32_e32 v2, 26, v2
	v_add_u32_e32 v3, v10, v2
	v_lshrrev_b32_e32 v2, 6, v3
	v_mul_i32_i24_e32 v2, 64, v2
	v_sub_u32_e32 v11, v10, v2
	v_and_b32_e32 v3, 0xffffffc0, v3
	s_waitcnt lgkmcnt(0)
	v_ashrrev_i32_e32 v6, 5, v11
	v_add_u32_e32 v7, 64, v10
	v_add_u32_e32 v6, v6, v3
	v_ashrrev_i32_e32 v3, 31, v7
	v_lshrrev_b32_e32 v3, 26, v3
	v_add_u32_e32 v15, v7, v3
	s_lshr_b32 s64, s64, 29
	v_lshrrev_b32_e32 v3, 6, v15
	s_add_i32 s67, s82, s64
	v_mul_i32_i24_e32 v3, 64, v3
	s_ashr_i32 s64, s67, 3
	s_and_b32 s67, s67, 0x1fffff8
	v_sub_u32_e32 v12, v7, v3
	s_lshr_b32 s65, s64, 5
	s_lshl_b32 s66, s64, 8
	s_sub_i32 s67, s82, s67
	v_and_b32_e32 v9, 63, v4
	v_and_b32_e32 v7, 0xffffffc0, v15
	v_ashrrev_i32_e32 v15, 5, v12
	s_mulk_i32 s65, 0x2080
	s_and_b32 s66, s66, 0x1f00
	s_lshl_b32 s70, s67, 7
	v_add_u32_e32 v7, v15, v7
	v_lshlrev_b32_e32 v13, 10, v13
	v_lshlrev_b32_e32 v15, 4, v9
	s_add_i32 s65, s65, s66
	s_ashr_i32 s71, s70, 31
	v_add3_u32 v56, 0, v13, v15
	v_lshlrev_b32_e32 v13, 4, v14
	s_add_i32 s66, s65, 0x80
	s_lshl_b64 s[72:73], s[70:71], 11
	s_and_b64 vcc, exec, s[76:77]
	v_and_b32_e32 v134, 0x70, v13
	s_cbranch_vccnz .LBB0_1398
	v_add_u32_e32 v14, s66, v10
	v_ashrrev_i32_e32 v15, 31, v14
	v_lshlrev_b64 v[14:15], 11, v[14:15]
	v_lshl_add_u64 v[14:15], s[2:3], 0, v[14:15]
	v_readfirstlane_b32 s67, v56
	v_add_u32_e32 v20, 0x2000, v56
	v_lshl_add_u64 v[14:15], v[14:15], 0, v[134:135]
	s_mov_b32 m0, s67
	v_readfirstlane_b32 s67, v20
	v_add_u32_e32 v20, 0x4000, v56
	global_load_lds_dwordx4 v[14:15], off
	s_nop 0
	s_cselect_b32 s98, 1, 0
	s_add_i32 m0, m0, 0xff80
	s_cmp_lg_u32 s98, 0
	global_load_lds_dwordx4 v[14:15], off offset:128
	s_nop 0
	v_lshl_add_u64 v[18:19], v[14:15], 0, s[12:13]
	s_mov_b32 m0, s67
	v_readfirstlane_b32 s67, v20
	global_load_lds_dwordx4 v[18:19], off
	s_nop 0
	s_cselect_b32 s98, 1, 0
	s_add_i32 m0, m0, 0xff80
	s_cmp_lg_u32 s98, 0
	global_load_lds_dwordx4 v[18:19], off offset:128
	s_nop 0
	v_lshl_add_u64 v[18:19], v[14:15], 0, s[14:15]
	s_mov_b32 m0, s67
	v_lshlrev_b32_e32 v10, 1, v11
	global_load_lds_dwordx4 v[18:19], off
	s_nop 0
	s_cselect_b32 s98, 1, 0
	s_add_i32 m0, m0, 0xff80
	s_cmp_lg_u32 s98, 0
	global_load_lds_dwordx4 v[18:19], off offset:128
	s_nop 0
	v_add_u32_e32 v18, 0x6000, v56
	v_and_b32_e32 v10, 62, v10
	v_readfirstlane_b32 s67, v18
	s_add_u32 s76, s36, s72
	v_add_u32_e32 v10, v6, v10
	v_lshlrev_b32_e32 v12, 1, v12
	v_lshl_add_u64 v[14:15], v[14:15], 0, s[16:17]
	s_mov_b32 m0, s67
	s_addc_u32 s77, s37, s73
	v_ashrrev_i32_e32 v11, 31, v10
	v_and_b32_e32 v12, 62, v12
	global_load_lds_dwordx4 v[14:15], off
	s_nop 0
	s_cselect_b32 s98, 1, 0
	s_add_i32 m0, m0, 0xff80
	s_cmp_lg_u32 s98, 0
	global_load_lds_dwordx4 v[14:15], off offset:128
	s_nop 0
	v_add_u32_e32 v14, 0x8000, v56
	v_add_u32_e32 v12, v7, v12
	v_lshl_add_u64 v[16:17], s[76:77], 0, v[134:135]
	v_lshlrev_b64 v[10:11], 11, v[10:11]
	v_readfirstlane_b32 s67, v14
	v_ashrrev_i32_e32 v13, 31, v12
	v_lshl_add_u64 v[10:11], v[16:17], 0, v[10:11]
	s_mov_b32 m0, s67
	s_nop 0
	global_load_lds_dwordx4 v[10:11], off
	s_nop 0
	s_cselect_b32 s98, 1, 0
	s_add_i32 m0, m0, 0xff80
	s_cmp_lg_u32 s98, 0
	global_load_lds_dwordx4 v[10:11], off offset:128
	s_nop 0
	v_lshlrev_b64 v[10:11], 11, v[12:13]
	v_add_u32_e32 v12, 0xa000, v56
	v_lshl_add_u64 v[10:11], v[16:17], 0, v[10:11]
	v_readfirstlane_b32 s67, v12
	s_mov_b32 m0, s67
	s_nop 0
	global_load_lds_dwordx4 v[10:11], off
	s_nop 0
	s_cselect_b32 s98, 1, 0
	s_add_i32 m0, m0, 0xff80
	s_cmp_lg_u32 s98, 0
	global_load_lds_dwordx4 v[10:11], off offset:128
	s_nop 0
; #define GEMM_ISSUE(KT, ST) do { const int k1_ = (KT) << 6; unsigned char* d_ = ldst + (ST) * STAGE; \
;         _Pragma("unroll") for (int j_ = 0; j_ < 4; ++j_) dma16(ap + (size_t)(64 * j_) * lda + k1_, d_ + j_ * 8192); \
;         _Pragma("unroll") for (int j_ = 0; j_ < NBW; ++j_) dma16(bp + bro[j_] + k1_, d_ + BOFF + j_ * 8192); } while (0)
; template <int NBW>
; DI void gemm_mainloop(f32x16 (&acc)[2][NBW], const bf16_t* A, size_t lda, int m0, const bf16_t* Bt, size_t ldb, int n0, int K, unsigned char* lds, bool pre = false, bool only_issue = false) {
;     ...
;     __syncthreads();
;     const int nk = K >> 6;
;     const int xr = (r >> 1) & 7;
;     int xo[4];
; #pragma unroll
;     for (int s = 0; s < 4; ++s) xo[s] = ((2 * s + hh) ^ xr) << 4;
;     const int aofs = (wm * 64 + r) * 128;
;     const int bofs = BOFF + (wn * 32 * NBW + r) * 128;
; #pragma unroll 1
;     for (int kt = 0; kt < nk; ++kt) {
;         const unsigned char* st = lds + (kt & 1) * STAGE;
; #pragma unroll
;         for (int s = 0; s < 4; ++s) {
;             if (s == 1 && kt + 1 < nk) GEMM_ISSUE(kt + 1, (kt + 1) & 1);
;             bf16x8 a[2], b[NBW];
; #pragma unroll
;             for (int mb = 0; mb < 2; ++mb) a[mb] = *(const bf16x8*)(st + aofs + mb * 4096 + xo[s]);
; #pragma unroll
;             for (int nb = 0; nb < NBW; ++nb) b[nb] = *(const bf16x8*)(st + bofs + nb * 4096 + xo[s]);
.LBB0_1398:
	v_and_b32_e32 v10, 31, v4
	v_lshrrev_b32_e32 v12, 6, v4
	v_lshrrev_b32_e32 v13, 1, v4
	v_bfe_u32 v14, v4, 1, 3
	v_lshlrev_b32_e32 v4, 7, v4
	v_and_b32_e32 v62, 0x2f80, v4
	v_add_u32_e32 v4, s65, v8
	v_add3_u32 v4, v4, v5, s78
	v_ashrrev_i32_e32 v5, 31, v4
	v_lshlrev_b64 v[4:5], 11, v[4:5]
	v_readlane_b32 s76, v223, 0
	v_or_b32_e32 v4, v4, v134
	v_readlane_b32 s77, v223, 1
	v_lshrrev_b32_e32 v11, 5, v9
	v_lshrrev_b32_e32 v9, 3, v9
	v_lshl_add_u64 v[50:51], s[76:77], 0, v[4:5]
	v_lshlrev_b16_e32 v4, 3, v12
	v_or_b32_e32 v8, v4, v9
	v_sub_u16_e32 v2, v8, v2
	v_and_b32_e32 v2, 31, v2
	v_lshl_add_u32 v4, v2, 1, v6
	v_sub_u16_e32 v2, v8, v3
	v_and_b32_e32 v2, 31, v2
	v_lshl_add_u32 v2, v2, 1, v7
	v_ashrrev_i32_e32 v3, 31, v2
	v_ashrrev_i32_e32 v5, 31, v4
	v_lshlrev_b64 v[2:3], 11, v[2:3]
	v_bitop3_b32 v15, v11, v13, 7 bitop3:0x78
	v_lshlrev_b64 v[4:5], 11, v[4:5]
	v_lshl_add_u64 v[2:3], v[2:3], 0, s[72:73]
	v_lshlrev_b32_e32 v57, 4, v15
	v_bitop3_b32 v15, v11, v14, 2 bitop3:0x36
	v_lshl_add_u64 v[4:5], v[4:5], 0, s[72:73]
	v_lshl_add_u64 v[2:3], v[2:3], 0, v[134:135]
	v_lshlrev_b32_e32 v58, 4, v15
	v_bitop3_b32 v15, v11, v14, 4 bitop3:0x36
	v_bitop3_b32 v11, v11, v14, 6 bitop3:0x36
	v_and_or_b32 v10, v13, s79, v10
	v_lshl_add_u64 v[4:5], v[4:5], 0, v[134:135]
	v_lshl_add_u64 v[54:55], s[8:9], 0, v[2:3]
	v_mov_b32_e32 v2, 0
	v_lshlrev_b32_e32 v59, 4, v15
	v_lshlrev_b32_e32 v60, 4, v11
	v_lshlrev_b32_e32 v61, 7, v10
	v_lshl_add_u64 v[52:53], s[8:9], 0, v[4:5]
	s_mov_b64 s[76:77], 0
	s_mov_b32 s67, 0x10000
	v_mov_b32_e32 v3, v2
	v_mov_b32_e32 v4, v2
	v_mov_b32_e32 v5, v2
	v_mov_b32_e32 v6, v2
	v_mov_b32_e32 v7, v2
	v_mov_b32_e32 v8, v2
	v_mov_b32_e32 v9, v2
	v_mov_b32_e32 v10, v2
	v_mov_b32_e32 v11, v2
	v_mov_b32_e32 v12, v2
	v_mov_b32_e32 v13, v2
	v_mov_b32_e32 v14, v2
	v_mov_b32_e32 v15, v2
	v_mov_b32_e32 v16, v2
	v_mov_b32_e32 v17, v2
	v_mov_b32_e32 v18, v2
	v_mov_b32_e32 v19, v2
	v_mov_b32_e32 v20, v2
	v_mov_b32_e32 v21, v2
	v_mov_b32_e32 v22, v2
	v_mov_b32_e32 v23, v2
	v_mov_b32_e32 v24, v2
	v_mov_b32_e32 v25, v2
	v_mov_b32_e32 v26, v2
	v_mov_b32_e32 v27, v2
	v_mov_b32_e32 v28, v2
	v_mov_b32_e32 v29, v2
	v_mov_b32_e32 v30, v2
	v_mov_b32_e32 v31, v2
	v_mov_b32_e32 v32, v2
	v_mov_b32_e32 v33, v2
	v_mov_b32_e32 v34, v2
	v_mov_b32_e32 v35, v2
	v_mov_b32_e32 v36, v2
	v_mov_b32_e32 v37, v2
	v_mov_b32_e32 v38, v2
	v_mov_b32_e32 v39, v2
	v_mov_b32_e32 v40, v2
	v_mov_b32_e32 v41, v2
	v_mov_b32_e32 v42, v2
	v_mov_b32_e32 v43, v2
	v_mov_b32_e32 v44, v2
	v_mov_b32_e32 v45, v2
	v_mov_b32_e32 v46, v2
	v_mov_b32_e32 v47, v2
	v_mov_b32_e32 v48, v2
	v_mov_b32_e32 v49, v2
	v_mov_b32_e32 v66, v2
	v_mov_b32_e32 v67, v2
	v_mov_b32_e32 v68, v2
	v_mov_b32_e32 v69, v2
	v_mov_b32_e32 v70, v2
	v_mov_b32_e32 v71, v2
	v_mov_b32_e32 v72, v2
	v_mov_b32_e32 v73, v2
	v_mov_b32_e32 v74, v2
	v_mov_b32_e32 v75, v2
	v_mov_b32_e32 v76, v2
	v_mov_b32_e32 v77, v2
	v_mov_b32_e32 v78, v2
	v_mov_b32_e32 v79, v2
	v_mov_b32_e32 v80, v2
	v_mov_b32_e32 v81, v2
	s_waitcnt vmcnt(0) lgkmcnt(0)
	s_barrier
	v_mov_b32_e32 v63, v61
	v_mov_b32_e32 v64, v62
	s_add_u32 s76, s76, 0x80
	s_addc_u32 s77, s77, 0
	s_add_i32 s67, s67, 0x10000
	v_add_u32_e32 v65, v63, v57
	v_add_u32_e32 v88, v64, v57
	ds_read_b128 v[240:243], v65
	ds_read_b128 v[248:251], v88 offset:32768
	ds_read_b128 v[252:255], v88 offset:36864
	ds_read_b128 v[244:247], v65 offset:4096

; DI int opaque_tid() { int t = threadIdx.x; asm volatile("" : "+v"(t)); return t; }
; #define GEMM_ISSUE(KT, ST) do { const int k1_ = (KT) << 6; unsigned char* d_ = ldst + (ST) * STAGE; \
;         _Pragma("unroll") for (int j_ = 0; j_ < 4; ++j_) dma16(ap + (size_t)(64 * j_) * lda + k1_, d_ + j_ * 8192); \
;         _Pragma("unroll") for (int j_ = 0; j_ < NBW; ++j_) dma16(bp + bro[j_] + k1_, d_ + BOFF + j_ * 8192); } while (0)
; template <int NBW>
; DI void gemm_mainloop(f32x16 (&acc)[2][NBW], const bf16_t* A, size_t lda, int m0, const bf16_t* Bt, size_t ldb, int n0, int K, unsigned char* lds, bool pre = false, bool only_issue = false) {
;     constexpr int STAGE = 65536, BOFF = 32768;
;     const int t = opaque_tid(), w = t >> 6, lane = t & 63, r = lane & 31, hh = lane >> 5, wm = w >> 1, wn = w & 1;
;     const int drow = w * 8 + (lane >> 3);
;     const int lchunk = (lane & 7) ^ ((drow >> 1) & 7);
;     const bf16_t* ap = A + (size_t)(m0 + drow) * lda + lchunk * 8;
;     const bf16_t* bp = Bt + (size_t)n0 * ldb + lchunk * 8;
;     size_t bro[NBW];
; #pragma unroll
;     for (int j = 0; j < NBW; ++j) {
;         const int rho = 64 * j + drow; const int wnh = rho / (32 * NBW), wi = rho % (32 * NBW);
;         bro[j] = (size_t)(wnh * 32 * NBW + NBW * (wi & 31) + (wi >> 5)) * ldb;
;     }
;     unsigned char* ldst = lds + w * 1024 + lane * 16;
;     ...
;     if (!pre) GEMM_ISSUE(0, 0);
;     if (only_issue) return;
;     __syncthreads();
;     const int nk = K >> 6;
;     const int xr = (r >> 1) & 7;
;     int xo[4];
; #pragma unroll
;     for (int s = 0; s < 4; ++s) xo[s] = ((2 * s + hh) ^ xr) << 4;
;     const int aofs = (wm * 64 + r) * 128;
;     const int bofs = BOFF + (wn * 32 * NBW + r) * 128;
.LBB0_1402:
	v_mov_b32_e32 v60, v1
	s_add_u32 s76, s38, s72
	v_ashrrev_i32_e32 v61, 6, v60
	v_lshlrev_b32_e32 v63, 3, v61
	v_bfe_u32 v64, v60, 3, 3
	v_ashrrev_i32_e32 v52, 31, v60
	v_or_b32_e32 v54, v63, v64
	v_lshrrev_b32_e32 v52, 26, v52
	v_add_u32_e32 v52, v54, v52
	v_lshrrev_b32_e32 v53, 6, v52
	v_mul_i32_i24_e32 v53, 64, v53
	v_sub_u32_e32 v53, v54, v53
	v_and_b32_e32 v58, 63, v60
	v_lshrrev_b32_e32 v65, 1, v54
	v_add_u32_e32 v50, s66, v54
	v_and_b32_e32 v52, 0xffffffc0, v52
	v_lshlrev_b32_e32 v55, 1, v53
	v_ashrrev_i32_e32 v53, 5, v53
	v_xor_b32_e32 v56, v65, v60
	v_ashrrev_i32_e32 v51, 31, v50
	v_and_b32_e32 v55, 62, v55
	v_add_u32_e32 v82, v53, v52
	v_add_u32_e32 v54, 64, v54
	v_lshlrev_b32_e32 v59, 10, v61
	v_lshlrev_b32_e32 v58, 4, v58
	v_lshlrev_b64 v[50:51], 11, v[50:51]
	v_add_u32_e32 v52, v82, v55
	v_ashrrev_i32_e32 v55, 31, v54
	v_lshlrev_b32_e32 v56, 4, v56
	v_add3_u32 v141, 0, v59, v58
	v_lshrrev_b32_e32 v55, 26, v55
	v_lshl_add_u64 v[50:51], s[4:5], 0, v[50:51]
	v_and_b32_e32 v134, 0x70, v56
	v_readfirstlane_b32 s67, v141
	v_add_u32_e32 v85, 0x2000, v141
	v_add_u32_e32 v55, v54, v55
	v_lshl_add_u64 v[50:51], v[50:51], 0, v[134:135]
	s_mov_b32 m0, s67
	v_readfirstlane_b32 s67, v85
	v_add_u32_e32 v85, 0x4000, v141
	v_lshrrev_b32_e32 v57, 6, v55
	global_load_lds_dwordx4 v[50:51], off
	s_nop 0
	s_cselect_b32 s98, 1, 0
	s_add_i32 m0, m0, 0xff80
	s_cmp_lg_u32 s98, 0
	global_load_lds_dwordx4 v[50:51], off offset:128
	s_nop 0
	v_lshl_add_u64 v[58:59], v[50:51], 0, s[12:13]
	s_mov_b32 m0, s67
	v_readfirstlane_b32 s67, v85
	v_mul_i32_i24_e32 v57, 64, v57
	global_load_lds_dwordx4 v[58:59], off
	s_nop 0
	s_cselect_b32 s98, 1, 0
	s_add_i32 m0, m0, 0xff80
	s_cmp_lg_u32 s98, 0
	global_load_lds_dwordx4 v[58:59], off offset:128
	s_nop 0
	v_lshl_add_u64 v[58:59], v[50:51], 0, s[14:15]
	s_mov_b32 m0, s67
	v_sub_u32_e32 v54, v54, v57
	global_load_lds_dwordx4 v[58:59], off
	s_nop 0
	s_cselect_b32 s98, 1, 0
	s_add_i32 m0, m0, 0xff80
	s_cmp_lg_u32 s98, 0
	global_load_lds_dwordx4 v[58:59], off offset:128
	s_nop 0
	v_add_u32_e32 v58, 0x6000, v141
	v_and_b32_e32 v55, 0xffffffc0, v55
	v_lshlrev_b32_e32 v57, 1, v54
	v_ashrrev_i32_e32 v54, 5, v54
	v_readfirstlane_b32 s67, v58
	s_addc_u32 s77, s39, s73
	v_ashrrev_i32_e32 v53, 31, v52
	v_and_b32_e32 v57, 62, v57
	v_add_u32_e32 v83, v54, v55
	v_lshl_add_u64 v[50:51], v[50:51], 0, s[16:17]
	s_mov_b32 m0, s67
	v_add_u32_e32 v58, 0x8000, v141
	v_add_u32_e32 v54, v83, v57
	v_lshl_add_u64 v[56:57], s[76:77], 0, v[134:135]
	global_load_lds_dwordx4 v[50:51], off
	s_nop 0
	s_cselect_b32 s98, 1, 0
	s_add_i32 m0, m0, 0xff80
	s_cmp_lg_u32 s98, 0
	global_load_lds_dwordx4 v[50:51], off offset:128
	s_nop 0
	v_lshlrev_b64 v[50:51], 11, v[52:53]
	v_readfirstlane_b32 s67, v58
	v_ashrrev_i32_e32 v55, 31, v54
	v_lshl_add_u64 v[50:51], v[56:57], 0, v[50:51]
	s_mov_b32 m0, s67
	v_add_u32_e32 v52, 0xa000, v141
	global_load_lds_dwordx4 v[50:51], off
	s_nop 0
	s_cselect_b32 s98, 1, 0
	s_add_i32 m0, m0, 0xff80
	s_cmp_lg_u32 s98, 0
	global_load_lds_dwordx4 v[50:51], off offset:128
	s_nop 0
	v_lshlrev_b64 v[50:51], 11, v[54:55]
	v_readfirstlane_b32 s67, v52
	v_lshl_add_u64 v[50:51], v[56:57], 0, v[50:51]
	s_mov_b32 m0, s67
	v_and_b32_e32 v62, 31, v60
	global_load_lds_dwordx4 v[50:51], off
	s_nop 0
	s_cselect_b32 s98, 1, 0
	s_add_i32 m0, m0, 0xff80
	s_cmp_lg_u32 s98, 0
	global_load_lds_dwordx4 v[50:51], off offset:128
	s_nop 0
	v_bfe_u32 v84, v60, 5, 1
	v_lshrrev_b32_e32 v50, 1, v60
	v_bitop3_b32 v52, v84, v50, 7 bitop3:0x78
	v_and_or_b32 v50, v50, s79, v62
	v_bfe_u32 v51, v60, 1, 3
	v_lshlrev_b32_e32 v151, 7, v50
	v_lshlrev_b32_e32 v50, 7, v60
	v_lshlrev_b32_e32 v143, 4, v52
	v_bitop3_b32 v52, v84, v51, 2 bitop3:0x36
	v_and_b32_e32 v153, 0x2f80, v50
	v_add_u32_e32 v50, s65, v64
	v_lshlrev_b32_e32 v145, 4, v52
	v_bitop3_b32 v52, v84, v51, 4 bitop3:0x36
	v_bitop3_b32 v51, v84, v51, 6 bitop3:0x36
	v_add3_u32 v50, v50, v63, s78
	v_lshlrev_b32_e32 v147, 4, v52
	v_lshlrev_b32_e32 v149, 4, v51
	v_ashrrev_i32_e32 v51, 31, v50
	v_bitop3_b32 v52, v65, 7, v60 bitop3:0x48
	v_lshlrev_b64 v[50:51], 11, v[50:51]
	v_lshlrev_b32_e32 v134, 4, v52
	v_readlane_b32 s76, v223, 0
	v_or_b32_e32 v50, v50, v134
	v_readlane_b32 s77, v223, 1
	s_mov_b32 s65, 0x10000
	s_waitcnt vmcnt(0) lgkmcnt(0)
	v_lshl_add_u64 v[168:169], s[76:77], 0, v[50:51]
	v_lshlrev_b16_e32 v50, 3, v61
	v_or_b32_e32 v50, v50, v64
	v_and_b32_e32 v50, 31, v50
	v_lshlrev_b32_e32 v52, 1, v50
	v_add_u32_e32 v50, v82, v52
	v_ashrrev_i32_e32 v51, 31, v50
	v_lshlrev_b64 v[50:51], 11, v[50:51]
	v_lshl_add_u64 v[50:51], v[50:51], 0, s[72:73]
	v_lshl_add_u64 v[50:51], v[50:51], 0, v[134:135]
	v_lshl_add_u64 v[170:171], s[10:11], 0, v[50:51]
	v_add_u32_e32 v50, v83, v52
	v_ashrrev_i32_e32 v51, 31, v50
	v_lshlrev_b64 v[50:51], 11, v[50:51]
	v_lshl_add_u64 v[50:51], v[50:51], 0, s[72:73]
	v_lshl_add_u64 v[50:51], v[50:51], 0, v[134:135]
	v_lshl_add_u64 v[172:173], s[10:11], 0, v[50:51]
	v_mov_b32_e32 v50, 0
	s_mov_b64 s[72:73], 0
	v_mov_b32_e32 v51, v50
	v_mov_b32_e32 v52, v50
	v_mov_b32_e32 v53, v50
	v_mov_b32_e32 v54, v50
	v_mov_b32_e32 v55, v50
	v_mov_b32_e32 v56, v50
	v_mov_b32_e32 v57, v50
	v_mov_b32_e32 v58, v50
	v_mov_b32_e32 v59, v50
	v_mov_b32_e32 v60, v50
	v_mov_b32_e32 v61, v50
	v_mov_b32_e32 v62, v50
	v_mov_b32_e32 v63, v50
	v_mov_b32_e32 v64, v50
	v_mov_b32_e32 v65, v50
	v_mov_b32_e32 v82, v50
	v_mov_b32_e32 v83, v50
	v_mov_b32_e32 v84, v50
	v_mov_b32_e32 v85, v50
	v_mov_b32_e32 v86, v50
	v_mov_b32_e32 v87, v50
	v_mov_b32_e32 v88, v50
	v_mov_b32_e32 v89, v50
	v_mov_b32_e32 v90, v50
	v_mov_b32_e32 v91, v50
	v_mov_b32_e32 v92, v50
	v_mov_b32_e32 v93, v50
	v_mov_b32_e32 v94, v50
	v_mov_b32_e32 v95, v50
	v_mov_b32_e32 v96, v50
	v_mov_b32_e32 v97, v50
	v_mov_b32_e32 v98, v50
	v_mov_b32_e32 v99, v50
	v_mov_b32_e32 v100, v50
	v_mov_b32_e32 v101, v50
	v_mov_b32_e32 v102, v50
	v_mov_b32_e32 v103, v50
	v_mov_b32_e32 v104, v50
	v_mov_b32_e32 v105, v50
	v_mov_b32_e32 v106, v50
	v_mov_b32_e32 v107, v50
	v_mov_b32_e32 v108, v50
	v_mov_b32_e32 v109, v50
	v_mov_b32_e32 v110, v50
	v_mov_b32_e32 v111, v50
	v_mov_b32_e32 v112, v50
	v_mov_b32_e32 v113, v50
	v_mov_b32_e32 v114, v50
	v_mov_b32_e32 v115, v50
	v_mov_b32_e32 v116, v50
	v_mov_b32_e32 v117, v50
	v_mov_b32_e32 v118, v50
	v_mov_b32_e32 v119, v50
	v_mov_b32_e32 v120, v50
	v_mov_b32_e32 v121, v50
	v_mov_b32_e32 v122, v50
	v_mov_b32_e32 v123, v50
	v_mov_b32_e32 v124, v50
	v_mov_b32_e32 v125, v50
	v_mov_b32_e32 v126, v50
	v_mov_b32_e32 v127, v50
	v_mov_b32_e32 v128, v50
	v_mov_b32_e32 v129, v50
	s_barrier
	v_mov_b32_e32 v134, v151
	v_mov_b32_e32 v155, v153
	s_add_u32 s72, s72, 0x80
	s_addc_u32 s73, s73, 0
	s_add_i32 s65, s65, 0x10000
	v_add_u32_e32 v157, v134, v143
	v_add_u32_e32 v159, v155, v143
	ds_read_b128 v[240:243], v157
	ds_read_b128 v[248:251], v159 offset:32768
	ds_read_b128 v[252:255], v159 offset:36864
	ds_read_b128 v[244:247], v157 offset:4096

; DI f32x16 zero16() { f32x16 z; for (int i = 0; i < 16; ++i) z[i] = 0.f; return z; }
; DI void phase_p4(const Params& P, unsigned char* lds) {
;     ...
;     for (int tile = blockIdx.x; tile < 128 * NTN; tile += gridDim.x) {
;         const int mt = tile / NTN, nt = tile % NTN; const int m0 = (mt >> 5) * LP + OFF + (mt & 31) * 256, n0 = nt * 128;
;         f32x16 a1[2][2], a2[2][2];
; #pragma unroll
;         for (int a = 0; a < 2; ++a)
; #pragma unroll
;             for (int b = 0; b < 2; ++b) { a1[a][b] = zero16(); a2[a][b] = zero16(); }
;         gemm_mainloop<2>(a1, RO, 1024, m0, W1, 1024, n0, 1024, lds, pre);
;         gemm_mainloop<2>(a2, FO, 1024, m0, W2, 1024, n0, 1024, lds);
;         { const int tn = tile + gridDim.x; pre = tn < 128 * NTN; if (pre) { const int mtn = tn / NTN, ntn_ = tn % NTN; gemm_mainloop<2>(a1, RO, 1024, (mtn >> 5) * LP + OFF + (mtn & 31) * 256, W1, 1024, ntn_ * 128, 1024, lds, false, true); } }
.LBB0_1406:
	v_readlane_b32 s72, v223, 3
	s_add_i32 s82, s82, s72
	v_readlane_b32 s73, v223, 4
	s_cmpk_gt_i32 s82, 0x3ff
	s_cselect_b64 s[72:73], -1, 0
	s_and_b64 vcc, exec, s[72:73]
	s_cbranch_vccnz .LBB0_1395
	v_mov_b32_e32 v134, v1
	s_ashr_i32 s65, s82, 31
	v_ashrrev_i32_e32 v141, 6, v134
	v_bfe_u32 v145, v134, 3, 3
	v_lshl_or_b32 v145, v141, 3, v145
	v_lshrrev_b32_e32 v147, 1, v145
	v_and_b32_e32 v143, 63, v134
	v_xor_b32_e32 v147, v147, v134
	v_ashrrev_i32_e32 v134, 31, v134
	v_lshrrev_b32_e32 v134, 26, v134
	s_lshr_b32 s65, s65, 29
	v_add_u32_e32 v134, v145, v134
	s_add_i32 s65, s82, s65
	v_lshrrev_b32_e32 v149, 6, v134
	s_ashr_i32 s67, s65, 3
	v_mul_i32_i24_e32 v149, 64, v149
	s_lshr_b32 s71, s67, 5
	s_lshl_b32 s67, s67, 8
	v_sub_u32_e32 v149, v145, v149
	s_mulk_i32 s71, 0x2080
	s_and_b32 s67, s67, 0x1f00
	v_lshlrev_b32_e32 v151, 1, v149
	s_add_i32 s67, s71, s67
	v_and_b32_e32 v134, 0xffffffc0, v134
	v_and_b32_e32 v151, 62, v151
	v_ashrrev_i32_e32 v149, 5, v149
	s_addk_i32 s67, 0x80
	v_add3_u32 v170, v149, v134, v151
	v_add_u32_e32 v134, 64, v145
	v_add_u32_e32 v168, s67, v145
	v_ashrrev_i32_e32 v145, 31, v134
	v_lshrrev_b32_e32 v145, 26, v145
	v_add_u32_e32 v145, v134, v145
	s_and_b32 s65, s65, 0x1fffff8
	v_lshrrev_b32_e32 v149, 6, v145
	s_sub_i32 s65, s82, s65
	v_mul_i32_i24_e32 v149, 64, v149
	s_lshl_b32 s76, s65, 7
	v_sub_u32_e32 v134, v134, v149
	s_ashr_i32 s77, s76, 31
	v_lshlrev_b32_e32 v149, 1, v134
	v_ashrrev_i32_e32 v169, 31, v168
	s_lshl_b64 s[76:77], s[76:77], 11
	v_and_b32_e32 v145, 0xffffffc0, v145
	v_and_b32_e32 v149, 62, v149
	v_ashrrev_i32_e32 v134, 5, v134
	v_lshlrev_b64 v[168:169], 11, v[168:169]
	s_add_u32 s76, s36, s76
	v_add3_u32 v172, v134, v145, v149
	v_lshlrev_b32_e32 v134, 4, v147
	s_addc_u32 s77, s37, s77
	v_lshl_add_u64 v[168:169], s[2:3], 0, v[168:169]
	v_and_b32_e32 v134, 0x70, v134
	v_lshl_add_u64 v[168:169], v[168:169], 0, v[134:135]
	v_lshl_add_u64 v[174:175], s[76:77], 0, v[134:135]
	v_lshlrev_b32_e32 v134, 10, v141
	v_lshlrev_b32_e32 v141, 4, v143
	v_add3_u32 v134, 0, v134, v141
	v_add_u32_e32 v141, 0x2000, v134
	v_readfirstlane_b32 s65, v134
	s_mov_b32 m0, s65
	v_readfirstlane_b32 s65, v141
	v_add_u32_e32 v141, 0x4000, v134
	global_load_lds_dwordx4 v[168:169], off
	s_nop 0
	s_cselect_b32 s98, 1, 0
	s_add_i32 m0, m0, 0xff80
	s_cmp_lg_u32 s98, 0
	global_load_lds_dwordx4 v[168:169], off offset:128
	s_nop 0
	v_lshl_add_u64 v[176:177], v[168:169], 0, s[12:13]
	s_mov_b32 m0, s65
	v_readfirstlane_b32 s65, v141
	v_add_u32_e32 v141, 0x6000, v134
	global_load_lds_dwordx4 v[176:177], off
	s_nop 0
	s_cselect_b32 s98, 1, 0
	s_add_i32 m0, m0, 0xff80
	s_cmp_lg_u32 s98, 0
	global_load_lds_dwordx4 v[176:177], off offset:128
	s_nop 0
	v_lshl_add_u64 v[176:177], v[168:169], 0, s[14:15]
	s_mov_b32 m0, s65
	v_readfirstlane_b32 s65, v141
	v_ashrrev_i32_e32 v171, 31, v170
	global_load_lds_dwordx4 v[176:177], off
	s_nop 0
	s_cselect_b32 s98, 1, 0
	s_add_i32 m0, m0, 0xff80
	s_cmp_lg_u32 s98, 0
	global_load_lds_dwordx4 v[176:177], off offset:128
	s_nop 0
	v_lshl_add_u64 v[168:169], v[168:169], 0, s[16:17]
	s_mov_b32 m0, s65
	v_add_u32_e32 v141, 0x8000, v134
	global_load_lds_dwordx4 v[168:169], off
	s_nop 0
	s_cselect_b32 s98, 1, 0
	s_add_i32 m0, m0, 0xff80
	s_cmp_lg_u32 s98, 0
	global_load_lds_dwordx4 v[168:169], off offset:128
	s_nop 0
	v_lshlrev_b64 v[168:169], 11, v[170:171]
	v_readfirstlane_b32 s65, v141
	v_ashrrev_i32_e32 v173, 31, v172
	v_lshl_add_u64 v[168:169], v[174:175], 0, v[168:169]
	s_mov_b32 m0, s65
	v_add_u32_e32 v134, 0xa000, v134
	global_load_lds_dwordx4 v[168:169], off
	s_nop 0
	s_cselect_b32 s98, 1, 0
	s_add_i32 m0, m0, 0xff80
	s_cmp_lg_u32 s98, 0
	global_load_lds_dwordx4 v[168:169], off offset:128
	s_nop 0
	v_lshlrev_b64 v[168:169], 11, v[172:173]
	v_readfirstlane_b32 s65, v134
	v_lshl_add_u64 v[168:169], v[174:175], 0, v[168:169]
	s_mov_b32 m0, s65
	s_nop 0
	global_load_lds_dwordx4 v[168:169], off
	s_nop 0
	s_cselect_b32 s98, 1, 0
	s_add_i32 m0, m0, 0xff80
	s_cmp_lg_u32 s98, 0
	global_load_lds_dwordx4 v[168:169], off offset:128
	s_nop 0
	s_branch .LBB0_1395

; DI int opaque_tid() { int t = threadIdx.x; asm volatile("" : "+v"(t)); return t; }
; #define GEMM_ISSUE(KT, ST) do { const int k1_ = (KT) << 6; unsigned char* d_ = ldst + (ST) * STAGE; \
;         _Pragma("unroll") for (int j_ = 0; j_ < 4; ++j_) dma16(ap + (size_t)(64 * j_) * lda + k1_, d_ + j_ * 8192); \
;         _Pragma("unroll") for (int j_ = 0; j_ < NBW; ++j_) dma16(bp + bro[j_] + k1_, d_ + BOFF + j_ * 8192); } while (0)
; template <int NBW>
; DI void gemm_mainloop(f32x16 (&acc)[2][NBW], const bf16_t* A, size_t lda, int m0, const bf16_t* Bt, size_t ldb, int n0, int K, unsigned char* lds, bool pre = false, bool only_issue = false) {
;     ...
;     const int t = opaque_tid(), w = t >> 6, lane = t & 63, r = lane & 31, hh = lane >> 5, wm = w >> 1, wn = w & 1;
;     const int drow = w * 8 + (lane >> 3);
;     const int lchunk = (lane & 7) ^ ((drow >> 1) & 7);
;     const bf16_t* ap = A + (size_t)(m0 + drow) * lda + lchunk * 8;
;     const bf16_t* bp = Bt + (size_t)n0 * ldb + lchunk * 8;
;     size_t bro[NBW];
; #pragma unroll
;     for (int j = 0; j < NBW; ++j) {
;         const int rho = 64 * j + drow; const int wnh = rho / (32 * NBW), wi = rho % (32 * NBW);
;         bro[j] = (size_t)(wnh * 32 * NBW + NBW * (wi & 31) + (wi >> 5)) * ldb;
;     }
;     unsigned char* ldst = lds + w * 1024 + lane * 16;
;     ...
;     if (!pre) GEMM_ISSUE(0, 0);
.LBB0_1485:
	v_mov_b32_e32 v13, v1
	s_ashr_i32 s22, s38, 31
	v_ashrrev_i32_e32 v11, 6, v13
	s_waitcnt lgkmcnt(0)
	v_lshlrev_b32_e32 v6, 3, v11
	v_bfe_u32 v12, v13, 3, 3
	v_or_b32_e32 v15, v6, v12
	v_lshrrev_b32_e32 v2, 1, v15
	v_xor_b32_e32 v20, v2, v13
	v_ashrrev_i32_e32 v2, 31, v13
	v_lshrrev_b32_e32 v2, 25, v2
	v_add_u32_e32 v3, v15, v2
	v_lshrrev_b32_e32 v2, 7, v3
	v_mul_i32_i24_e32 v2, 0x80, v2
	v_sub_u32_e32 v16, v15, v2
	v_and_b32_e32 v3, 0xffffff80, v3
	v_ashrrev_i32_e32 v4, 5, v16
	v_add_u32_e32 v7, v4, v3
	v_add_u32_e32 v4, 64, v15
	v_ashrrev_i32_e32 v3, 31, v4
	v_lshrrev_b32_e32 v3, 25, v3
	v_add_u32_e32 v5, v4, v3
	v_lshrrev_b32_e32 v3, 7, v5
	v_mul_i32_i24_e32 v3, 0x80, v3
	v_sub_u32_e32 v17, v4, v3
	v_and_b32_e32 v4, 0xffffff80, v5
	v_ashrrev_i32_e32 v5, 5, v17
	v_add_u32_e32 v8, v5, v4
	v_add_u32_e32 v5, 0x80, v15
	v_ashrrev_i32_e32 v4, 31, v5
	v_lshrrev_b32_e32 v4, 25, v4
	v_add_u32_e32 v9, v5, v4
	v_lshrrev_b32_e32 v4, 7, v9
	v_mul_i32_i24_e32 v4, 0x80, v4
	v_sub_u32_e32 v18, v5, v4
	v_and_b32_e32 v5, 0xffffff80, v9
	v_ashrrev_i32_e32 v9, 5, v18
	v_add_u32_e32 v10, 0xc0, v15
	v_add_u32_e32 v9, v9, v5
	v_ashrrev_i32_e32 v5, 31, v10
	s_lshr_b32 s22, s22, 30
	v_lshrrev_b32_e32 v5, 25, v5
	s_add_i32 s22, s38, s22
	v_add_u32_e32 v21, v10, v5
	s_ashr_i32 s26, s22, 2
	v_lshrrev_b32_e32 v5, 7, v21
	s_lshr_b32 s23, s26, 5
	s_and_b32 s22, s22, -4
	v_mul_i32_i24_e32 v5, 0x80, v5
	s_mul_i32 s25, s23, 0x2080
	s_lshl_b32 s23, s26, 8
	s_sub_i32 s39, s38, s22
	v_sub_u32_e32 v19, v10, v5
	s_and_b32 s23, s23, 0x1f00
	s_lshl_b32 s28, s39, 8
	v_and_b32_e32 v14, 63, v13
	v_and_b32_e32 v10, 0xffffff80, v21
	v_ashrrev_i32_e32 v21, 5, v19
	s_add_i32 s25, s25, s23
	s_ashr_i32 s29, s28, 31
	v_add_u32_e32 v10, v21, v10
	v_lshlrev_b32_e32 v21, 10, v11
	v_lshlrev_b32_e32 v22, 4, v14
	v_lshlrev_b32_e32 v20, 4, v20
	s_add_i32 s24, s25, 0x80
	s_lshl_b64 s[22:23], s[28:29], 11
	v_add3_u32 v140, 0, v21, v22
	s_and_b64 vcc, exec, s[30:31]
	v_and_b32_e32 v164, 0x70, v20
	s_cbranch_vccnz .LBB0_1487
	v_add_u32_e32 v20, s24, v15
	v_lshlrev_b32_e32 v15, 2, v16
	v_and_b32_e32 v15, 0x7c, v15
	v_add_u32_e32 v22, v7, v15
	v_lshlrev_b32_e32 v15, 2, v17
	v_and_b32_e32 v15, 0x7c, v15
	v_add_u32_e32 v16, v8, v15
	v_lshlrev_b32_e32 v15, 2, v18
	v_and_b32_e32 v15, 0x7c, v15
	v_ashrrev_i32_e32 v21, 31, v20
	v_add_u32_e32 v24, v9, v15
	v_lshlrev_b32_e32 v15, 2, v19
	v_and_b32_e32 v15, 0x7c, v15
	v_lshlrev_b64 v[20:21], 11, v[20:21]
	v_add_u32_e32 v18, v10, v15
	v_lshl_add_u64 v[20:21], s[0:1], 0, v[20:21]
	v_readfirstlane_b32 s27, v140
	v_add_u32_e32 v15, 0x2000, v140
	v_lshl_add_u64 v[20:21], v[20:21], 0, v[164:165]
	s_mov_b32 m0, s27
	v_readfirstlane_b32 s27, v15
	v_add_u32_e32 v15, 0x4000, v140
	global_load_lds_dwordx4 v[20:21], off
	s_nop 0
	s_cselect_b32 s98, 1, 0
	s_add_i32 m0, m0, 0xff80
	s_cmp_lg_u32 s98, 0
	global_load_lds_dwordx4 v[20:21], off offset:128
	s_nop 0
	v_lshl_add_u64 v[28:29], v[20:21], 0, s[8:9]
	s_mov_b32 m0, s27
	v_readfirstlane_b32 s27, v15
	v_add_u32_e32 v15, 0x6000, v140
	s_add_u32 s30, s34, s22
	global_load_lds_dwordx4 v[28:29], off
	s_nop 0
	s_cselect_b32 s98, 1, 0
	s_add_i32 m0, m0, 0xff80
	s_cmp_lg_u32 s98, 0
	global_load_lds_dwordx4 v[28:29], off offset:128
	s_nop 0
	v_lshl_add_u64 v[28:29], v[20:21], 0, s[10:11]
	s_mov_b32 m0, s27
	v_readfirstlane_b32 s27, v15
	s_addc_u32 s31, s35, s23
	v_ashrrev_i32_e32 v23, 31, v22
	global_load_lds_dwordx4 v[28:29], off
	s_nop 0
	s_cselect_b32 s98, 1, 0
	s_add_i32 m0, m0, 0xff80
	s_cmp_lg_u32 s98, 0
	global_load_lds_dwordx4 v[28:29], off offset:128
	s_nop 0
	v_lshl_add_u64 v[20:21], v[20:21], 0, s[12:13]
	s_mov_b32 m0, s27
	v_add_u32_e32 v15, 0x8000, v140
	v_ashrrev_i32_e32 v17, 31, v16
	v_lshl_add_u64 v[26:27], s[30:31], 0, v[164:165]
	global_load_lds_dwordx4 v[20:21], off
	s_nop 0
	s_cselect_b32 s98, 1, 0
	s_add_i32 m0, m0, 0xff80
	s_cmp_lg_u32 s98, 0
	global_load_lds_dwordx4 v[20:21], off offset:128
	s_nop 0
	v_lshlrev_b64 v[20:21], 11, v[22:23]
	v_readfirstlane_b32 s27, v15
	v_add_u32_e32 v15, 0xa000, v140
	v_lshl_add_u64 v[20:21], v[26:27], 0, v[20:21]
	s_mov_b32 m0, s27
	v_lshlrev_b64 v[16:17], 11, v[16:17]
	v_readfirstlane_b32 s27, v15
	v_ashrrev_i32_e32 v25, 31, v24
	global_load_lds_dwordx4 v[20:21], off
	s_nop 0
	s_cselect_b32 s98, 1, 0
	s_add_i32 m0, m0, 0xff80
	s_cmp_lg_u32 s98, 0
	global_load_lds_dwordx4 v[20:21], off offset:128
	s_nop 0
	v_lshl_add_u64 v[16:17], v[26:27], 0, v[16:17]
	s_mov_b32 m0, s27
	v_add_u32_e32 v15, 0xc000, v140
	global_load_lds_dwordx4 v[16:17], off
	s_nop 0
	s_cselect_b32 s98, 1, 0
	s_add_i32 m0, m0, 0xff80
	s_cmp_lg_u32 s98, 0
	global_load_lds_dwordx4 v[16:17], off offset:128
	s_nop 0
	v_lshlrev_b64 v[16:17], 11, v[24:25]
	v_readfirstlane_b32 s27, v15
	v_ashrrev_i32_e32 v19, 31, v18
	v_lshl_add_u64 v[16:17], v[26:27], 0, v[16:17]
	s_mov_b32 m0, s27
	v_add_u32_e32 v15, 0xe000, v140
	global_load_lds_dwordx4 v[16:17], off
	s_nop 0
	s_cselect_b32 s98, 1, 0
	s_add_i32 m0, m0, 0xff80
	s_cmp_lg_u32 s98, 0
	global_load_lds_dwordx4 v[16:17], off offset:128
	s_nop 0
	v_lshlrev_b64 v[16:17], 11, v[18:19]
	v_readfirstlane_b32 s27, v15
	v_lshl_add_u64 v[16:17], v[26:27], 0, v[16:17]
	s_mov_b32 m0, s27
	s_nop 0
	global_load_lds_dwordx4 v[16:17], off
	s_nop 0
	s_cselect_b32 s98, 1, 0
	s_add_i32 m0, m0, 0xff80
	s_cmp_lg_u32 s98, 0
	global_load_lds_dwordx4 v[16:17], off offset:128
	s_nop 0
; #define GEMM_ISSUE(KT, ST) do { const int k1_ = (KT) << 6; unsigned char* d_ = ldst + (ST) * STAGE; \
;         _Pragma("unroll") for (int j_ = 0; j_ < 4; ++j_) dma16(ap + (size_t)(64 * j_) * lda + k1_, d_ + j_ * 8192); \
;         _Pragma("unroll") for (int j_ = 0; j_ < NBW; ++j_) dma16(bp + bro[j_] + k1_, d_ + BOFF + j_ * 8192); } while (0)
; template <int NBW>
; DI void gemm_mainloop(f32x16 (&acc)[2][NBW], const bf16_t* A, size_t lda, int m0, const bf16_t* Bt, size_t ldb, int n0, int K, unsigned char* lds, bool pre = false, bool only_issue = false) {
;     ...
;     __syncthreads();
;     const int nk = K >> 6;
;     const int xr = (r >> 1) & 7;
;     int xo[4];
; #pragma unroll
;     for (int s = 0; s < 4; ++s) xo[s] = ((2 * s + hh) ^ xr) << 4;
;     const int aofs = (wm * 64 + r) * 128;
;     const int bofs = BOFF + (wn * 32 * NBW + r) * 128;
; #pragma unroll 1
;     for (int kt = 0; kt < nk; ++kt) {
;         const unsigned char* st = lds + (kt & 1) * STAGE;
; #pragma unroll
;         for (int s = 0; s < 4; ++s) {
;             if (s == 1 && kt + 1 < nk) GEMM_ISSUE(kt + 1, (kt + 1) & 1);
;             bf16x8 a[2], b[NBW];
; #pragma unroll
;             for (int mb = 0; mb < 2; ++mb) a[mb] = *(const bf16x8*)(st + aofs + mb * 4096 + xo[s]);
; #pragma unroll
;             for (int nb = 0; nb < NBW; ++nb) b[nb] = *(const bf16x8*)(st + bofs + nb * 4096 + xo[s]);
.LBB0_1487:
	v_and_b32_e32 v15, 31, v13
	v_lshlrev_b32_e32 v11, 7, v11
	v_and_or_b32 v11, v11, s36, v15
	v_lshrrev_b32_e32 v17, 6, v13
	s_waitcnt vmcnt(0)
	v_lshlrev_b32_e32 v146, 7, v11
	v_add_u32_e32 v11, s25, v12
	v_lshrrev_b32_e32 v16, 5, v14
	v_lshrrev_b32_e32 v14, 3, v14
	v_add3_u32 v12, v11, v6, s36
	v_lshlrev_b16_e32 v6, 3, v17
	v_or_b32_e32 v11, v6, v14
	v_sub_u16_e32 v2, v11, v2
	v_and_b32_e32 v2, 31, v2
	v_lshl_add_u32 v6, v2, 2, v7
	v_sub_u16_e32 v2, v11, v3
	v_and_b32_e32 v2, 31, v2
	v_lshl_add_u32 v2, v2, 2, v8
	v_ashrrev_i32_e32 v3, 31, v2
	v_lshlrev_b64 v[2:3], 11, v[2:3]
	v_lshl_add_u64 v[2:3], v[2:3], 0, s[22:23]
	v_lshl_add_u64 v[2:3], v[2:3], 0, v[164:165]
	v_lshl_add_u64 v[134:135], s[6:7], 0, v[2:3]
	v_sub_u16_e32 v2, v11, v4
	v_and_b32_e32 v2, 31, v2
	v_lshl_add_u32 v2, v2, 2, v9
	v_ashrrev_i32_e32 v3, 31, v2
	v_lshlrev_b64 v[2:3], 11, v[2:3]
	v_lshl_add_u64 v[2:3], v[2:3], 0, s[22:23]
	v_lshl_add_u64 v[2:3], v[2:3], 0, v[164:165]
	v_lshrrev_b32_e32 v18, 1, v13
	v_lshl_add_u64 v[136:137], s[6:7], 0, v[2:3]
	v_sub_u16_e32 v2, v11, v5
	v_bfe_u32 v13, v13, 1, 3
	v_bitop3_b32 v19, v16, v18, 7 bitop3:0x78
	v_and_b32_e32 v2, 31, v2
	v_lshlrev_b32_e32 v141, 4, v19
	v_bitop3_b32 v19, v16, v13, 2 bitop3:0x36
	v_lshl_add_u32 v2, v2, 2, v10
	v_lshlrev_b32_e32 v142, 4, v19
	v_bitop3_b32 v19, v16, v13, 4 bitop3:0x36
	v_bitop3_b32 v13, v16, v13, 6 bitop3:0x36
	v_ashrrev_i32_e32 v3, 31, v2
	v_lshlrev_b32_e32 v144, 4, v13
	v_and_or_b32 v13, v18, s37, v15
	v_ashrrev_i32_e32 v7, 31, v6
	v_lshlrev_b64 v[2:3], 11, v[2:3]
	v_lshlrev_b32_e32 v145, 7, v13
	v_ashrrev_i32_e32 v13, 31, v12
	v_lshlrev_b64 v[6:7], 11, v[6:7]
	v_lshl_add_u64 v[2:3], v[2:3], 0, s[22:23]
	v_lshlrev_b64 v[12:13], 11, v[12:13]
	v_readlane_b32 s30, v223, 0
	v_lshl_add_u64 v[6:7], v[6:7], 0, s[22:23]
	v_lshl_add_u64 v[2:3], v[2:3], 0, v[164:165]
	v_or_b32_e32 v12, v12, v164
	v_readlane_b32 s31, v223, 1
	v_lshl_add_u64 v[6:7], v[6:7], 0, v[164:165]
	v_lshl_add_u64 v[138:139], s[6:7], 0, v[2:3]
	v_mov_b32_e32 v2, 0
	v_lshlrev_b32_e32 v143, 4, v19
	v_lshl_add_u64 v[130:131], s[30:31], 0, v[12:13]
	v_lshl_add_u64 v[132:133], s[6:7], 0, v[6:7]
	s_mov_b32 s25, 0
	s_mov_b64 s[22:23], 0
	s_mov_b32 s27, 0x10000
	v_mov_b32_e32 v3, v2
	v_mov_b32_e32 v4, v2
	v_mov_b32_e32 v5, v2
	v_mov_b32_e32 v6, v2
	v_mov_b32_e32 v7, v2
	v_mov_b32_e32 v8, v2
	v_mov_b32_e32 v9, v2
	v_mov_b32_e32 v10, v2
	v_mov_b32_e32 v11, v2
	v_mov_b32_e32 v12, v2
	v_mov_b32_e32 v13, v2
	v_mov_b32_e32 v14, v2
	v_mov_b32_e32 v15, v2
	v_mov_b32_e32 v16, v2
	v_mov_b32_e32 v17, v2
	v_mov_b32_e32 v18, v2
	v_mov_b32_e32 v19, v2
	v_mov_b32_e32 v20, v2
	v_mov_b32_e32 v21, v2
	v_mov_b32_e32 v22, v2
	v_mov_b32_e32 v23, v2
	v_mov_b32_e32 v24, v2
	v_mov_b32_e32 v25, v2
	v_mov_b32_e32 v26, v2
	v_mov_b32_e32 v27, v2
	v_mov_b32_e32 v28, v2
	v_mov_b32_e32 v29, v2
	v_mov_b32_e32 v30, v2
	v_mov_b32_e32 v31, v2
	v_mov_b32_e32 v32, v2
	v_mov_b32_e32 v33, v2
	v_mov_b32_e32 v34, v2
	v_mov_b32_e32 v35, v2
	v_mov_b32_e32 v36, v2
	v_mov_b32_e32 v37, v2
	v_mov_b32_e32 v38, v2
	v_mov_b32_e32 v39, v2
	v_mov_b32_e32 v40, v2
	v_mov_b32_e32 v41, v2
	v_mov_b32_e32 v42, v2
	v_mov_b32_e32 v43, v2
	v_mov_b32_e32 v44, v2
	v_mov_b32_e32 v45, v2
	v_mov_b32_e32 v46, v2
	v_mov_b32_e32 v47, v2
	v_mov_b32_e32 v48, v2
	v_mov_b32_e32 v49, v2
	v_mov_b32_e32 v50, v2
	v_mov_b32_e32 v51, v2
	v_mov_b32_e32 v52, v2
	v_mov_b32_e32 v53, v2
	v_mov_b32_e32 v54, v2
	v_mov_b32_e32 v55, v2
	v_mov_b32_e32 v56, v2
	v_mov_b32_e32 v57, v2
	v_mov_b32_e32 v58, v2
	v_mov_b32_e32 v59, v2
	v_mov_b32_e32 v60, v2
	v_mov_b32_e32 v61, v2
	v_mov_b32_e32 v62, v2
	v_mov_b32_e32 v63, v2
	v_mov_b32_e32 v64, v2
	v_mov_b32_e32 v65, v2
	v_mov_b32_e32 v66, v2
	v_mov_b32_e32 v67, v2
	v_mov_b32_e32 v68, v2
	v_mov_b32_e32 v69, v2
	v_mov_b32_e32 v70, v2
	v_mov_b32_e32 v71, v2
	v_mov_b32_e32 v72, v2
	v_mov_b32_e32 v73, v2
	v_mov_b32_e32 v74, v2
	v_mov_b32_e32 v75, v2
	v_mov_b32_e32 v76, v2
	v_mov_b32_e32 v77, v2
	v_mov_b32_e32 v78, v2
	v_mov_b32_e32 v79, v2
	v_mov_b32_e32 v80, v2
	v_mov_b32_e32 v81, v2
	v_mov_b32_e32 v82, v2
	v_mov_b32_e32 v83, v2
	v_mov_b32_e32 v84, v2
	v_mov_b32_e32 v85, v2
	v_mov_b32_e32 v86, v2
	v_mov_b32_e32 v87, v2
	v_mov_b32_e32 v88, v2
	v_mov_b32_e32 v89, v2
	v_mov_b32_e32 v90, v2
	v_mov_b32_e32 v91, v2
	v_mov_b32_e32 v92, v2
	v_mov_b32_e32 v93, v2
	v_mov_b32_e32 v94, v2
	v_mov_b32_e32 v95, v2
	v_mov_b32_e32 v96, v2
	v_mov_b32_e32 v97, v2
	v_mov_b32_e32 v98, v2
	v_mov_b32_e32 v99, v2
	v_mov_b32_e32 v100, v2
	v_mov_b32_e32 v101, v2
	v_mov_b32_e32 v102, v2
	v_mov_b32_e32 v103, v2
	v_mov_b32_e32 v104, v2
	v_mov_b32_e32 v105, v2
	v_mov_b32_e32 v106, v2
	v_mov_b32_e32 v107, v2
	v_mov_b32_e32 v108, v2
	v_mov_b32_e32 v109, v2
	v_mov_b32_e32 v110, v2
	v_mov_b32_e32 v111, v2
	v_mov_b32_e32 v112, v2
	v_mov_b32_e32 v113, v2
	v_mov_b32_e32 v114, v2
	v_mov_b32_e32 v115, v2
	v_mov_b32_e32 v116, v2
	v_mov_b32_e32 v117, v2
	v_mov_b32_e32 v118, v2
	v_mov_b32_e32 v119, v2
	v_mov_b32_e32 v120, v2
	v_mov_b32_e32 v121, v2
	v_mov_b32_e32 v122, v2
	v_mov_b32_e32 v123, v2
	v_mov_b32_e32 v124, v2
	v_mov_b32_e32 v125, v2
	v_mov_b32_e32 v126, v2
	v_mov_b32_e32 v127, v2
	v_mov_b32_e32 v128, v2
	v_mov_b32_e32 v129, v2
	s_waitcnt lgkmcnt(0)
	s_barrier
	v_mov_b32_e32 v147, v145
	v_mov_b32_e32 v148, v146
	s_add_u32 s22, s22, 0x80
	s_addc_u32 s23, s23, 0
	s_add_i32 s27, s27, 0x10000
	v_add_u32_e32 v252, v147, v141
	v_add_u32_e32 v253, v148, v141
	ds_read_b128 v[224:227], v252
	ds_read_b128 v[232:235], v253 offset:32768
	ds_read_b128 v[236:239], v253 offset:36864
	ds_read_b128 v[240:243], v253 offset:40960
	ds_read_b128 v[244:247], v253 offset:45056
	ds_read_b128 v[228:231], v252 offset:4096

; DI f32x16 zero16() { f32x16 z; for (int i = 0; i < 16; ++i) z[i] = 0.f; return z; }
; DI void phase_p5(const Params& P, unsigned char* lds) {
;     ...
;     for (int tile = blockIdx.x; tile < 128 * NTN; tile += gridDim.x) {
;         const int mt = tile / NTN, nt = tile % NTN; const int m0 = (mt >> 5) * LP + OFF + (mt & 31) * 256, n0 = nt * 256;
;         f32x16 acc[2][4];
; #pragma unroll
;         for (int a = 0; a < 2; ++a)
; #pragma unroll
;             for (int b = 0; b < 4; ++b) acc[a][b] = zero16();
;         gemm_mainloop<4>(acc, M, 1024, m0, W, 1024, n0, 1024, lds, pre);
;         { const int tn = tile + gridDim.x; pre = tn < 128 * NTN; if (pre) { const int mtn = tn / NTN, ntn_ = tn % NTN; f32x16 (&dummy)[2][4] = acc; gemm_mainloop<4>(dummy, M, 1024, (mtn >> 5) * LP + OFF + (mtn & 31) * 256, W, 1024, ntn_ * 256, 1024, lds, false, true); } }
.LBB0_1491:
	v_readlane_b32 s22, v223, 3
	s_add_i32 s38, s38, s22
	v_readlane_b32 s23, v223, 4
	s_cmpk_gt_i32 s38, 0x1ff
	s_cselect_b64 s[22:23], -1, 0
	s_and_b64 vcc, exec, s[22:23]
	s_cbranch_vccnz .LBB0_1493
	v_mov_b32_e32 v132, v1
	s_ashr_i32 s25, s38, 31
	v_ashrrev_i32_e32 v142, 6, v132
	v_bfe_u32 v130, v132, 3, 3
	v_lshl_or_b32 v138, v142, 3, v130
	v_lshrrev_b32_e32 v130, 1, v138
	v_and_b32_e32 v143, 63, v132
	v_xor_b32_e32 v140, v130, v132
	v_ashrrev_i32_e32 v132, 31, v132
	v_lshrrev_b32_e32 v132, 25, v132
	v_add_u32_e32 v132, v138, v132
	v_lshrrev_b32_e32 v133, 7, v132
	v_mul_i32_i24_e32 v133, 0x80, v133
	v_sub_u32_e32 v133, v138, v133
	v_lshlrev_b32_e32 v134, 2, v133
	v_and_b32_e32 v132, 0xffffff80, v132
	v_and_b32_e32 v134, 0x7c, v134
	v_ashrrev_i32_e32 v133, 5, v133
	v_add3_u32 v132, v133, v132, v134
	v_add_u32_e32 v134, 64, v138
	v_ashrrev_i32_e32 v135, 31, v134
	v_lshrrev_b32_e32 v135, 25, v135
	v_add_u32_e32 v135, v134, v135
	v_lshrrev_b32_e32 v136, 7, v135
	v_mul_i32_i24_e32 v136, 0x80, v136
	v_sub_u32_e32 v134, v134, v136
	v_lshlrev_b32_e32 v136, 2, v134
	v_and_b32_e32 v135, 0xffffff80, v135
	v_and_b32_e32 v136, 0x7c, v136
	v_ashrrev_i32_e32 v134, 5, v134
	s_lshr_b32 s25, s25, 30
	v_add3_u32 v134, v134, v135, v136
	v_add_u32_e32 v136, 0x80, v138
	s_add_i32 s25, s38, s25
	v_ashrrev_i32_e32 v137, 31, v136
	s_ashr_i32 s27, s25, 2
	v_lshrrev_b32_e32 v137, 25, v137
	s_lshr_b32 s29, s27, 5
	s_lshl_b32 s27, s27, 8
	v_add_u32_e32 v137, v136, v137
	s_mulk_i32 s29, 0x2080
	s_and_b32 s27, s27, 0x1f00
	v_lshrrev_b32_e32 v139, 7, v137
	s_add_i32 s27, s29, s27
	v_mul_i32_i24_e32 v139, 0x80, v139
	s_addk_i32 s27, 0x80
	v_sub_u32_e32 v136, v136, v139
	v_add_u32_e32 v130, s27, v138
	v_lshlrev_b32_e32 v139, 2, v136
	s_and_b32 s25, s25, 0xfffffc
	v_ashrrev_i32_e32 v131, 31, v130
	v_and_b32_e32 v137, 0xffffff80, v137
	v_and_b32_e32 v139, 0x7c, v139
	v_ashrrev_i32_e32 v136, 5, v136
	v_add_u32_e32 v138, 0xc0, v138
	v_lshlrev_b32_e32 v142, 10, v142
	v_lshlrev_b32_e32 v143, 4, v143
	s_sub_i32 s25, s38, s25
	v_add3_u32 v136, v136, v137, v139
	v_ashrrev_i32_e32 v139, 31, v138
	v_lshlrev_b64 v[130:131], 11, v[130:131]
	v_lshlrev_b32_e32 v140, 4, v140
	v_add3_u32 v144, 0, v142, v143
	s_lshl_b32 s30, s25, 8
	v_lshrrev_b32_e32 v139, 25, v139
	v_lshl_add_u64 v[130:131], s[0:1], 0, v[130:131]
	v_and_b32_e32 v164, 0x70, v140
	v_readfirstlane_b32 s25, v144
	v_add_u32_e32 v145, 0x2000, v144
	v_add_u32_e32 v139, v138, v139
	v_lshl_add_u64 v[130:131], v[130:131], 0, v[164:165]
	s_mov_b32 m0, s25
	v_readfirstlane_b32 s25, v145
	v_add_u32_e32 v145, 0x4000, v144
	v_lshrrev_b32_e32 v141, 7, v139
	global_load_lds_dwordx4 v[130:131], off
	s_nop 0
	s_cselect_b32 s98, 1, 0
	s_add_i32 m0, m0, 0xff80
	s_cmp_lg_u32 s98, 0
	global_load_lds_dwordx4 v[130:131], off offset:128
	s_nop 0
	v_lshl_add_u64 v[142:143], v[130:131], 0, s[8:9]
	s_mov_b32 m0, s25
	v_readfirstlane_b32 s25, v145
	s_ashr_i32 s31, s30, 31
	v_mul_i32_i24_e32 v141, 0x80, v141
	global_load_lds_dwordx4 v[142:143], off
	s_nop 0
	s_cselect_b32 s98, 1, 0
	s_add_i32 m0, m0, 0xff80
	s_cmp_lg_u32 s98, 0
	global_load_lds_dwordx4 v[142:143], off offset:128
	s_nop 0
	v_lshl_add_u64 v[142:143], v[130:131], 0, s[10:11]
	s_mov_b32 m0, s25
	s_lshl_b64 s[30:31], s[30:31], 11
	v_sub_u32_e32 v138, v138, v141
	global_load_lds_dwordx4 v[142:143], off
	s_nop 0
	s_cselect_b32 s98, 1, 0
	s_add_i32 m0, m0, 0xff80
	s_cmp_lg_u32 s98, 0
	global_load_lds_dwordx4 v[142:143], off offset:128
	s_nop 0
	v_add_u32_e32 v142, 0x6000, v144
	s_add_u32 s30, s34, s30
	v_lshlrev_b32_e32 v141, 2, v138
	v_readfirstlane_b32 s25, v142
	s_addc_u32 s31, s35, s31
	v_ashrrev_i32_e32 v133, 31, v132
	v_and_b32_e32 v139, 0xffffff80, v139
	v_and_b32_e32 v141, 0x7c, v141
	v_ashrrev_i32_e32 v138, 5, v138
	v_lshl_add_u64 v[130:131], v[130:131], 0, s[12:13]
	s_mov_b32 m0, s25
	v_add_u32_e32 v142, 0x8000, v144
	v_add3_u32 v138, v138, v139, v141
	v_lshl_add_u64 v[140:141], s[30:31], 0, v[164:165]
	global_load_lds_dwordx4 v[130:131], off
	s_nop 0
	s_cselect_b32 s98, 1, 0
	s_add_i32 m0, m0, 0xff80
	s_cmp_lg_u32 s98, 0
	global_load_lds_dwordx4 v[130:131], off offset:128
	s_nop 0
	v_lshlrev_b64 v[130:131], 11, v[132:133]
	v_readfirstlane_b32 s25, v142
	v_ashrrev_i32_e32 v135, 31, v134
	v_lshl_add_u64 v[130:131], v[140:141], 0, v[130:131]
	s_mov_b32 m0, s25
	v_add_u32_e32 v132, 0xa000, v144
	global_load_lds_dwordx4 v[130:131], off
	s_nop 0
	s_cselect_b32 s98, 1, 0
	s_add_i32 m0, m0, 0xff80
	s_cmp_lg_u32 s98, 0
	global_load_lds_dwordx4 v[130:131], off offset:128
	s_nop 0
	v_lshlrev_b64 v[130:131], 11, v[134:135]
	v_readfirstlane_b32 s25, v132
	v_ashrrev_i32_e32 v137, 31, v136
	v_lshl_add_u64 v[130:131], v[140:141], 0, v[130:131]
	s_mov_b32 m0, s25
	v_add_u32_e32 v132, 0xc000, v144
	global_load_lds_dwordx4 v[130:131], off
	s_nop 0
	s_cselect_b32 s98, 1, 0
	s_add_i32 m0, m0, 0xff80
	s_cmp_lg_u32 s98, 0
	global_load_lds_dwordx4 v[130:131], off offset:128
	s_nop 0
	v_lshlrev_b64 v[130:131], 11, v[136:137]
	v_readfirstlane_b32 s25, v132
	v_ashrrev_i32_e32 v139, 31, v138
	v_lshl_add_u64 v[130:131], v[140:141], 0, v[130:131]
	s_mov_b32 m0, s25
	v_add_u32_e32 v132, 0xe000, v144
	global_load_lds_dwordx4 v[130:131], off
	s_nop 0
	s_cselect_b32 s98, 1, 0
	s_add_i32 m0, m0, 0xff80
	s_cmp_lg_u32 s98, 0
	global_load_lds_dwordx4 v[130:131], off offset:128
	s_nop 0
	v_lshlrev_b64 v[130:131], 11, v[138:139]
	v_readfirstlane_b32 s25, v132
	v_lshl_add_u64 v[130:131], v[140:141], 0, v[130:131]
	s_mov_b32 m0, s25
	s_nop 0
	global_load_lds_dwordx4 v[130:131], off
	s_nop 0
	s_cselect_b32 s98, 1, 0
	s_add_i32 m0, m0, 0xff80
	s_cmp_lg_u32 s98, 0
	global_load_lds_dwordx4 v[130:131], off offset:128
	s_nop 0

; DI int opaque_tid() { int t = threadIdx.x; asm volatile("" : "+v"(t)); return t; }
; #define GEMM_ISSUE(KT, ST) do { const int k1_ = (KT) << 6; unsigned char* d_ = ldst + (ST) * STAGE; \
;         _Pragma("unroll") for (int j_ = 0; j_ < 4; ++j_) dma16(ap + (size_t)(64 * j_) * lda + k1_, d_ + j_ * 8192); \
;         _Pragma("unroll") for (int j_ = 0; j_ < NBW; ++j_) dma16(bp + bro[j_] + k1_, d_ + BOFF + j_ * 8192); } while (0)
; template <int NBW>
; DI void gemm_mainloop(f32x16 (&acc)[2][NBW], const bf16_t* A, size_t lda, int m0, const bf16_t* Bt, size_t ldb, int n0, int K, unsigned char* lds, bool pre = false, bool only_issue = false) {
;     ...
;     const int t = opaque_tid(), w = t >> 6, lane = t & 63, r = lane & 31, hh = lane >> 5, wm = w >> 1, wn = w & 1;
;     const int drow = w * 8 + (lane >> 3);
;     const int lchunk = (lane & 7) ^ ((drow >> 1) & 7);
;     const bf16_t* ap = A + (size_t)(m0 + drow) * lda + lchunk * 8;
;     const bf16_t* bp = Bt + (size_t)n0 * ldb + lchunk * 8;
;     size_t bro[NBW];
; #pragma unroll
;     for (int j = 0; j < NBW; ++j) {
;         const int rho = 64 * j + drow; const int wnh = rho / (32 * NBW), wi = rho % (32 * NBW);
;         bro[j] = (size_t)(wnh * 32 * NBW + NBW * (wi & 31) + (wi >> 5)) * ldb;
;     }
;     unsigned char* ldst = lds + w * 1024 + lane * 16;
;     ...
;     if (!pre) GEMM_ISSUE(0, 0);
.LBB0_1636:
	s_or_b64 exec, exec, s[26:27]
	v_mov_b32_e32 v13, v1
	s_lshl_b32 s25, s28, 4
	s_waitcnt lgkmcnt(0)
	v_ashrrev_i32_e32 v7, 6, v13
	v_lshlrev_b32_e32 v2, 3, v7
	v_bfe_u32 v8, v13, 3, 3
	v_or_b32_e32 v15, v2, v8
	v_lshrrev_b32_e32 v3, 1, v15
	v_xor_b32_e32 v20, v3, v13
	v_ashrrev_i32_e32 v3, 31, v13
	v_lshrrev_b32_e32 v3, 25, v3
	v_add_u32_e32 v4, v15, v3
	v_lshrrev_b32_e32 v3, 7, v4
	v_mul_i32_i24_e32 v3, 0x80, v3
	v_sub_u32_e32 v16, v15, v3
	v_and_b32_e32 v4, 0xffffff80, v4
	v_ashrrev_i32_e32 v5, 5, v16
	v_add_u32_e32 v9, v5, v4
	v_add_u32_e32 v5, 64, v15
	v_ashrrev_i32_e32 v4, 31, v5
	v_lshrrev_b32_e32 v4, 25, v4
	v_add_u32_e32 v6, v5, v4
	v_lshrrev_b32_e32 v4, 7, v6
	v_mul_i32_i24_e32 v4, 0x80, v4
	v_sub_u32_e32 v17, v5, v4
	v_and_b32_e32 v5, 0xffffff80, v6
	v_ashrrev_i32_e32 v6, 5, v17
	v_add_u32_e32 v10, v6, v5
	v_add_u32_e32 v6, 0x80, v15
	v_ashrrev_i32_e32 v5, 31, v6
	v_lshrrev_b32_e32 v5, 25, v5
	v_add_u32_e32 v11, v6, v5
	v_lshrrev_b32_e32 v5, 7, v11
	v_mul_i32_i24_e32 v5, 0x80, v5
	v_sub_u32_e32 v18, v6, v5
	v_and_b32_e32 v6, 0xffffff80, v11
	v_ashrrev_i32_e32 v11, 5, v18
	v_add_u32_e32 v12, 0xc0, v15
	v_add_u32_e32 v11, v11, v6
	v_ashrrev_i32_e32 v6, 31, v12
	v_lshrrev_b32_e32 v6, 25, v6
	v_add_u32_e32 v21, v12, v6
	v_lshrrev_b32_e32 v6, 7, v21
	v_mul_i32_i24_e32 v6, 0x80, v6
	s_sub_i32 s25, s39, s25
	v_sub_u32_e32 v19, v12, v6
	s_lshl_b32 s26, s25, 8
	v_and_b32_e32 v14, 63, v13
	v_and_b32_e32 v12, 0xffffff80, v21
	v_ashrrev_i32_e32 v21, 5, v19
	s_ashr_i32 s27, s26, 31
	v_add_u32_e32 v12, v21, v12
	v_lshlrev_b32_e32 v21, 10, v7
	v_lshlrev_b32_e32 v22, 4, v14
	s_xor_b64 s[30:31], s[30:31], -1
	v_lshlrev_b32_e32 v20, 4, v20
	s_lshl_b64 s[28:29], s[26:27], 11
	v_add3_u32 v164, 0, v21, v22
	s_andn2_b64 vcc, exec, s[30:31]
	v_and_b32_e32 v132, 0x70, v20
	s_cbranch_vccnz .LBB0_1638
	v_add_u32_e32 v20, s24, v15
	v_lshlrev_b32_e32 v15, 2, v16
	v_and_b32_e32 v15, 0x7c, v15
	v_add_u32_e32 v22, v9, v15
	v_lshlrev_b32_e32 v15, 2, v17
	v_and_b32_e32 v15, 0x7c, v15
	v_add_u32_e32 v16, v10, v15
	v_lshlrev_b32_e32 v15, 2, v18
	v_and_b32_e32 v15, 0x7c, v15
	v_ashrrev_i32_e32 v21, 31, v20
	v_add_u32_e32 v24, v11, v15
	v_lshlrev_b32_e32 v15, 2, v19
	v_and_b32_e32 v15, 0x7c, v15
	v_lshlrev_b64 v[20:21], 11, v[20:21]
	v_add_u32_e32 v18, v12, v15
	v_lshl_add_u64 v[20:21], s[4:5], 0, v[20:21]
	v_readfirstlane_b32 s25, v164
	v_add_u32_e32 v15, 0x2000, v164
	v_lshl_add_u64 v[20:21], v[20:21], 0, v[132:133]
	s_mov_b32 m0, s25
	v_readfirstlane_b32 s25, v15
	v_add_u32_e32 v15, 0x4000, v164
	global_load_lds_dwordx4 v[20:21], off
	s_nop 0
	s_cselect_b32 s98, 1, 0
	s_add_i32 m0, m0, 0xff80
	s_cmp_lg_u32 s98, 0
	global_load_lds_dwordx4 v[20:21], off offset:128
	s_nop 0
	v_lshl_add_u64 v[28:29], v[20:21], 0, s[10:11]
	s_mov_b32 m0, s25
	v_readfirstlane_b32 s25, v15
	v_add_u32_e32 v15, 0x6000, v164
	s_add_u32 s30, s34, s28
	global_load_lds_dwordx4 v[28:29], off
	s_nop 0
	s_cselect_b32 s98, 1, 0
	s_add_i32 m0, m0, 0xff80
	s_cmp_lg_u32 s98, 0
	global_load_lds_dwordx4 v[28:29], off offset:128
	s_nop 0
	v_lshl_add_u64 v[28:29], v[20:21], 0, s[12:13]
	s_mov_b32 m0, s25
	v_readfirstlane_b32 s25, v15
	s_addc_u32 s31, s35, s29
	v_ashrrev_i32_e32 v23, 31, v22
	global_load_lds_dwordx4 v[28:29], off
	s_nop 0
	s_cselect_b32 s98, 1, 0
	s_add_i32 m0, m0, 0xff80
	s_cmp_lg_u32 s98, 0
	global_load_lds_dwordx4 v[28:29], off offset:128
	s_nop 0
	v_lshl_add_u64 v[20:21], v[20:21], 0, s[14:15]
	s_mov_b32 m0, s25
	v_add_u32_e32 v15, 0x8000, v164
	v_ashrrev_i32_e32 v17, 31, v16
	v_lshl_add_u64 v[26:27], s[30:31], 0, v[132:133]
	global_load_lds_dwordx4 v[20:21], off
	s_nop 0
	s_cselect_b32 s98, 1, 0
	s_add_i32 m0, m0, 0xff80
	s_cmp_lg_u32 s98, 0
	global_load_lds_dwordx4 v[20:21], off offset:128
	s_nop 0
	v_lshlrev_b64 v[20:21], 11, v[22:23]
	v_readfirstlane_b32 s25, v15
	v_add_u32_e32 v15, 0xa000, v164
	v_lshl_add_u64 v[20:21], v[26:27], 0, v[20:21]
	s_mov_b32 m0, s25
	v_lshlrev_b64 v[16:17], 11, v[16:17]
	v_readfirstlane_b32 s25, v15
	v_ashrrev_i32_e32 v25, 31, v24
	global_load_lds_dwordx4 v[20:21], off
	s_nop 0
	s_cselect_b32 s98, 1, 0
	s_add_i32 m0, m0, 0xff80
	s_cmp_lg_u32 s98, 0
	global_load_lds_dwordx4 v[20:21], off offset:128
	s_nop 0
	v_lshl_add_u64 v[16:17], v[26:27], 0, v[16:17]
	s_mov_b32 m0, s25
	v_add_u32_e32 v15, 0xc000, v164
	global_load_lds_dwordx4 v[16:17], off
	s_nop 0
	s_cselect_b32 s98, 1, 0
	s_add_i32 m0, m0, 0xff80
	s_cmp_lg_u32 s98, 0
	global_load_lds_dwordx4 v[16:17], off offset:128
	s_nop 0
	v_lshlrev_b64 v[16:17], 11, v[24:25]
	v_readfirstlane_b32 s25, v15
	v_ashrrev_i32_e32 v19, 31, v18
	v_lshl_add_u64 v[16:17], v[26:27], 0, v[16:17]
	s_mov_b32 m0, s25
	v_add_u32_e32 v15, 0xe000, v164
	global_load_lds_dwordx4 v[16:17], off
	s_nop 0
	s_cselect_b32 s98, 1, 0
	s_add_i32 m0, m0, 0xff80
	s_cmp_lg_u32 s98, 0
	global_load_lds_dwordx4 v[16:17], off offset:128
	s_nop 0
	v_lshlrev_b64 v[16:17], 11, v[18:19]
	v_readfirstlane_b32 s25, v15
	v_lshl_add_u64 v[16:17], v[26:27], 0, v[16:17]
	s_mov_b32 m0, s25
	s_nop 0
	global_load_lds_dwordx4 v[16:17], off
	s_nop 0
	s_cselect_b32 s98, 1, 0
	s_add_i32 m0, m0, 0xff80
	s_cmp_lg_u32 s98, 0
	global_load_lds_dwordx4 v[16:17], off offset:128
	s_nop 0
; #define GEMM_ISSUE(KT, ST) do { const int k1_ = (KT) << 6; unsigned char* d_ = ldst + (ST) * STAGE; \
;         _Pragma("unroll") for (int j_ = 0; j_ < 4; ++j_) dma16(ap + (size_t)(64 * j_) * lda + k1_, d_ + j_ * 8192); \
;         _Pragma("unroll") for (int j_ = 0; j_ < NBW; ++j_) dma16(bp + bro[j_] + k1_, d_ + BOFF + j_ * 8192); } while (0)
; template <int NBW>
; DI void gemm_mainloop(f32x16 (&acc)[2][NBW], const bf16_t* A, size_t lda, int m0, const bf16_t* Bt, size_t ldb, int n0, int K, unsigned char* lds, bool pre = false, bool only_issue = false) {
;     ...
;     __syncthreads();
;     const int nk = K >> 6;
;     const int xr = (r >> 1) & 7;
;     int xo[4];
; #pragma unroll
;     for (int s = 0; s < 4; ++s) xo[s] = ((2 * s + hh) ^ xr) << 4;
;     const int aofs = (wm * 64 + r) * 128;
;     const int bofs = BOFF + (wn * 32 * NBW + r) * 128;
; #pragma unroll 1
;     for (int kt = 0; kt < nk; ++kt) {
;         const unsigned char* st = lds + (kt & 1) * STAGE;
; #pragma unroll
;         for (int s = 0; s < 4; ++s) {
;             if (s == 1 && kt + 1 < nk) GEMM_ISSUE(kt + 1, (kt + 1) & 1);
;             bf16x8 a[2], b[NBW];
; #pragma unroll
;             for (int mb = 0; mb < 2; ++mb) a[mb] = *(const bf16x8*)(st + aofs + mb * 4096 + xo[s]);
; #pragma unroll
;             for (int nb = 0; nb < NBW; ++nb) b[nb] = *(const bf16x8*)(st + bofs + nb * 4096 + xo[s]);
.LBB0_1638:
	v_lshrrev_b32_e32 v16, 5, v14
	v_lshrrev_b32_e32 v17, 3, v14
	v_lshrrev_b32_e32 v14, 1, v13
	v_and_b32_e32 v15, 31, v13
	v_lshrrev_b32_e32 v18, 6, v13
	v_bfe_u32 v13, v13, 1, 3
	v_bitop3_b32 v19, v16, v14, 7 bitop3:0x78
	v_lshlrev_b32_e32 v7, 7, v7
	v_lshlrev_b32_e32 v165, 4, v19
	v_bitop3_b32 v19, v16, v13, 2 bitop3:0x36
	v_and_or_b32 v7, v7, s36, v15
	v_lshlrev_b32_e32 v166, 4, v19
	v_bitop3_b32 v19, v16, v13, 4 bitop3:0x36
	v_bitop3_b32 v13, v16, v13, 6 bitop3:0x36
	v_lshlrev_b32_e32 v170, 7, v7
	v_add_u32_e32 v7, s41, v8
	v_lshlrev_b32_e32 v168, 4, v13
	v_and_or_b32 v13, v14, s38, v15
	v_add3_u32 v14, v7, v2, s36
	v_lshlrev_b16_e32 v2, 3, v18
	v_or_b32_e32 v7, v2, v17
	v_sub_u16_e32 v2, v7, v3
	v_and_b32_e32 v2, 31, v2
	v_lshl_add_u32 v2, v2, 2, v9
	v_ashrrev_i32_e32 v3, 31, v2
	v_lshlrev_b64 v[2:3], 11, v[2:3]
	v_lshl_add_u64 v[2:3], v[2:3], 0, s[28:29]
	v_lshl_add_u64 v[2:3], v[2:3], 0, v[132:133]
	v_lshl_add_u64 v[136:137], s[8:9], 0, v[2:3]
	v_sub_u16_e32 v2, v7, v4
	v_and_b32_e32 v2, 31, v2
	v_lshl_add_u32 v2, v2, 2, v10
	v_ashrrev_i32_e32 v3, 31, v2
	v_lshlrev_b64 v[2:3], 11, v[2:3]
	v_lshl_add_u64 v[2:3], v[2:3], 0, s[28:29]
	v_lshl_add_u64 v[2:3], v[2:3], 0, v[132:133]
	v_lshl_add_u64 v[138:139], s[8:9], 0, v[2:3]
	v_sub_u16_e32 v2, v7, v5
	v_and_b32_e32 v2, 31, v2
	v_lshl_add_u32 v2, v2, 2, v11
	v_ashrrev_i32_e32 v3, 31, v2
	v_lshlrev_b64 v[2:3], 11, v[2:3]
	v_lshl_add_u64 v[2:3], v[2:3], 0, s[28:29]
	v_lshl_add_u64 v[2:3], v[2:3], 0, v[132:133]
	v_lshl_add_u64 v[140:141], s[8:9], 0, v[2:3]
	v_sub_u16_e32 v2, v7, v6
	v_and_b32_e32 v2, 31, v2
	v_lshl_add_u32 v2, v2, 2, v12
	v_ashrrev_i32_e32 v3, 31, v2
	v_lshlrev_b64 v[2:3], 11, v[2:3]
	v_ashrrev_i32_e32 v15, 31, v14
	v_lshl_add_u64 v[2:3], v[2:3], 0, s[28:29]
	v_lshlrev_b64 v[14:15], 11, v[14:15]
	v_lshl_add_u64 v[2:3], v[2:3], 0, v[132:133]
	v_or_b32_e32 v14, v14, v132
	v_lshl_add_u64 v[142:143], s[8:9], 0, v[2:3]
	v_mov_b32_e32 v2, 0
	v_lshlrev_b32_e32 v167, 4, v19
	v_lshlrev_b32_e32 v169, 7, v13
	v_lshl_add_u64 v[134:135], s[50:51], 0, v[14:15]
	s_mov_b32 s25, 0
	s_mov_b64 s[28:29], 0
	s_mov_b32 s27, 0x10000
	v_mov_b32_e32 v3, v2
	v_mov_b32_e32 v4, v2
	v_mov_b32_e32 v5, v2
	v_mov_b32_e32 v6, v2
	v_mov_b32_e32 v7, v2
	v_mov_b32_e32 v8, v2
	v_mov_b32_e32 v9, v2
	v_mov_b32_e32 v10, v2
	v_mov_b32_e32 v11, v2
	v_mov_b32_e32 v12, v2
	v_mov_b32_e32 v13, v2
	v_mov_b32_e32 v14, v2
	v_mov_b32_e32 v15, v2
	v_mov_b32_e32 v16, v2
	v_mov_b32_e32 v17, v2
	v_mov_b32_e32 v18, v2
	v_mov_b32_e32 v19, v2
	v_mov_b32_e32 v20, v2
	v_mov_b32_e32 v21, v2
	v_mov_b32_e32 v22, v2
	v_mov_b32_e32 v23, v2
	v_mov_b32_e32 v24, v2
	v_mov_b32_e32 v25, v2
	v_mov_b32_e32 v26, v2
	v_mov_b32_e32 v27, v2
	v_mov_b32_e32 v28, v2
	v_mov_b32_e32 v29, v2
	v_mov_b32_e32 v30, v2
	v_mov_b32_e32 v31, v2
	v_mov_b32_e32 v32, v2
	v_mov_b32_e32 v33, v2
	v_mov_b32_e32 v34, v2
	v_mov_b32_e32 v35, v2
	v_mov_b32_e32 v36, v2
	v_mov_b32_e32 v37, v2
	v_mov_b32_e32 v38, v2
	v_mov_b32_e32 v39, v2
	v_mov_b32_e32 v40, v2
	v_mov_b32_e32 v41, v2
	v_mov_b32_e32 v42, v2
	v_mov_b32_e32 v43, v2
	v_mov_b32_e32 v44, v2
	v_mov_b32_e32 v45, v2
	v_mov_b32_e32 v46, v2
	v_mov_b32_e32 v47, v2
	v_mov_b32_e32 v48, v2
	v_mov_b32_e32 v49, v2
	v_mov_b32_e32 v50, v2
	v_mov_b32_e32 v51, v2
	v_mov_b32_e32 v52, v2
	v_mov_b32_e32 v53, v2
	v_mov_b32_e32 v54, v2
	v_mov_b32_e32 v55, v2
	v_mov_b32_e32 v56, v2
	v_mov_b32_e32 v57, v2
	v_mov_b32_e32 v58, v2
	v_mov_b32_e32 v59, v2
	v_mov_b32_e32 v60, v2
	v_mov_b32_e32 v61, v2
	v_mov_b32_e32 v62, v2
	v_mov_b32_e32 v63, v2
	v_mov_b32_e32 v64, v2
	v_mov_b32_e32 v65, v2
	v_mov_b32_e32 v66, v2
	v_mov_b32_e32 v67, v2
	v_mov_b32_e32 v68, v2
	v_mov_b32_e32 v69, v2
	v_mov_b32_e32 v70, v2
	v_mov_b32_e32 v71, v2
	v_mov_b32_e32 v72, v2
	v_mov_b32_e32 v73, v2
	v_mov_b32_e32 v74, v2
	v_mov_b32_e32 v75, v2
	v_mov_b32_e32 v76, v2
	v_mov_b32_e32 v77, v2
	v_mov_b32_e32 v78, v2
	v_mov_b32_e32 v79, v2
	v_mov_b32_e32 v80, v2
	v_mov_b32_e32 v81, v2
	v_mov_b32_e32 v82, v2
	v_mov_b32_e32 v83, v2
	v_mov_b32_e32 v84, v2
	v_mov_b32_e32 v85, v2
	v_mov_b32_e32 v86, v2
	v_mov_b32_e32 v87, v2
	v_mov_b32_e32 v88, v2
	v_mov_b32_e32 v89, v2
	v_mov_b32_e32 v90, v2
	v_mov_b32_e32 v91, v2
	v_mov_b32_e32 v92, v2
	v_mov_b32_e32 v93, v2
	v_mov_b32_e32 v94, v2
	v_mov_b32_e32 v95, v2
	v_mov_b32_e32 v96, v2
	v_mov_b32_e32 v97, v2
	v_mov_b32_e32 v98, v2
	v_mov_b32_e32 v99, v2
	v_mov_b32_e32 v100, v2
	v_mov_b32_e32 v101, v2
	v_mov_b32_e32 v102, v2
	v_mov_b32_e32 v103, v2
	v_mov_b32_e32 v104, v2
	v_mov_b32_e32 v105, v2
	v_mov_b32_e32 v106, v2
	v_mov_b32_e32 v107, v2
	v_mov_b32_e32 v108, v2
	v_mov_b32_e32 v109, v2
	v_mov_b32_e32 v110, v2
	v_mov_b32_e32 v111, v2
	v_mov_b32_e32 v112, v2
	v_mov_b32_e32 v113, v2
	v_mov_b32_e32 v114, v2
	v_mov_b32_e32 v115, v2
	v_mov_b32_e32 v116, v2
	v_mov_b32_e32 v117, v2
	v_mov_b32_e32 v118, v2
	v_mov_b32_e32 v119, v2
	v_mov_b32_e32 v120, v2
	v_mov_b32_e32 v121, v2
	v_mov_b32_e32 v122, v2
	v_mov_b32_e32 v123, v2
	v_mov_b32_e32 v124, v2
	v_mov_b32_e32 v125, v2
	v_mov_b32_e32 v126, v2
	v_mov_b32_e32 v127, v2
	v_mov_b32_e32 v128, v2
	v_mov_b32_e32 v129, v2
	s_waitcnt vmcnt(0) lgkmcnt(0)
	s_barrier
	v_mov_b32_e32 v132, v169
	v_mov_b32_e32 v171, v170
	s_add_u32 s28, s28, 0x80
	s_addc_u32 s29, s29, 0
	s_add_i32 s27, s27, 0x10000
	v_add_u32_e32 v252, v132, v165
	v_add_u32_e32 v253, v171, v165
	ds_read_b128 v[224:227], v252
	ds_read_b128 v[232:235], v253 offset:32768
	ds_read_b128 v[236:239], v253 offset:36864
	ds_read_b128 v[240:243], v253 offset:40960
	ds_read_b128 v[244:247], v253 offset:45056
	ds_read_b128 v[228:231], v252 offset:4096

; DI void phase_p6(const Params& P, unsigned char* lds) {
;     ...
;         gemm_mainloop<4>(acc, A2, 1024, m0, W, 1024, n0, 1024, lds, pre);
;         { const int tn = tile + gridDim.x; pre = tn < 128 * NTN; if (pre) { const int mtn = tn / NTN, ntn_ = tn % NTN; f32x16 (&dummy)[2][4] = acc; gemm_mainloop<4>(dummy, A2, 1024, (mtn >> 5) * LP + OFF + (mtn & 31) * 256, W, 1024, ntn_ * 256, 1024, lds, false, true); } }
.LBB0_1642:
	v_readlane_b32 s28, v223, 3
	s_add_i32 s39, s39, s28
	v_readlane_b32 s29, v223, 4
	s_cmpk_gt_i32 s39, 0x7ff
	s_cselect_b64 s[28:29], -1, 0
	s_and_b64 vcc, exec, s[28:29]
	s_cbranch_vccnz .LBB0_1633
	v_mov_b32_e32 v132, v1
	s_ashr_i32 s25, s39, 31
	v_ashrrev_i32_e32 v166, 6, v132
	v_bfe_u32 v134, v132, 3, 3
	v_lshl_or_b32 v142, v166, 3, v134
	v_lshrrev_b32_e32 v134, 1, v142
	v_and_b32_e32 v167, 63, v132
	v_xor_b32_e32 v164, v134, v132
	v_ashrrev_i32_e32 v132, 31, v132
	v_lshrrev_b32_e32 v132, 25, v132
	v_add_u32_e32 v132, v142, v132
	v_lshrrev_b32_e32 v136, 7, v132
	v_mul_i32_i24_e32 v136, 0x80, v136
	v_sub_u32_e32 v136, v142, v136
	v_lshlrev_b32_e32 v137, 2, v136
	v_and_b32_e32 v132, 0xffffff80, v132
	v_and_b32_e32 v137, 0x7c, v137
	v_ashrrev_i32_e32 v136, 5, v136
	v_add3_u32 v136, v136, v132, v137
	v_add_u32_e32 v132, 64, v142
	v_ashrrev_i32_e32 v138, 31, v132
	v_lshrrev_b32_e32 v138, 25, v138
	v_add_u32_e32 v138, v132, v138
	v_lshrrev_b32_e32 v139, 7, v138
	v_mul_i32_i24_e32 v139, 0x80, v139
	v_sub_u32_e32 v132, v132, v139
	v_lshlrev_b32_e32 v139, 2, v132
	v_and_b32_e32 v138, 0xffffff80, v138
	v_and_b32_e32 v139, 0x7c, v139
	v_ashrrev_i32_e32 v132, 5, v132
	v_add3_u32 v138, v132, v138, v139
	v_add_u32_e32 v132, 0x80, v142
	v_ashrrev_i32_e32 v140, 31, v132
	v_lshrrev_b32_e32 v140, 25, v140
	s_lshr_b32 s25, s25, 28
	v_add_u32_e32 v140, v132, v140
	s_add_i32 s25, s39, s25
	v_lshrrev_b32_e32 v141, 7, v140
	s_ashr_i32 s27, s25, 4
	v_mul_i32_i24_e32 v141, 0x80, v141
	s_lshr_b32 s30, s27, 5
	s_lshl_b32 s27, s27, 8
	v_sub_u32_e32 v132, v132, v141
	s_mulk_i32 s30, 0x2080
	s_and_b32 s27, s27, 0x1f00
	v_lshlrev_b32_e32 v141, 2, v132
	s_add_i32 s27, s30, s27
	v_and_b32_e32 v140, 0xffffff80, v140
	v_and_b32_e32 v141, 0x7c, v141
	v_ashrrev_i32_e32 v132, 5, v132
	s_addk_i32 s27, 0x80
	v_add3_u32 v140, v132, v140, v141
	v_add_u32_e32 v132, 0xc0, v142
	v_add_u32_e32 v134, s27, v142
	v_ashrrev_i32_e32 v142, 31, v132
	v_lshrrev_b32_e32 v142, 25, v142
	v_add_u32_e32 v142, v132, v142
	s_and_b32 s25, s25, 0xfffff0
	v_lshrrev_b32_e32 v143, 7, v142
	s_sub_i32 s25, s39, s25
	v_mul_i32_i24_e32 v143, 0x80, v143
	s_lshl_b32 s30, s25, 8
	v_sub_u32_e32 v132, v132, v143
	s_ashr_i32 s31, s30, 31
	v_lshlrev_b32_e32 v143, 2, v132
	v_ashrrev_i32_e32 v135, 31, v134
	s_lshl_b64 s[30:31], s[30:31], 11
	v_and_b32_e32 v142, 0xffffff80, v142
	v_and_b32_e32 v143, 0x7c, v143
	v_ashrrev_i32_e32 v132, 5, v132
	s_add_u32 s30, s34, s30
	v_add3_u32 v142, v132, v142, v143
	v_lshlrev_b64 v[134:135], 11, v[134:135]
	v_lshlrev_b32_e32 v132, 4, v164
	s_addc_u32 s31, s35, s31
	v_lshl_add_u64 v[134:135], s[4:5], 0, v[134:135]
	v_and_b32_e32 v132, 0x70, v132
	v_lshl_add_u64 v[134:135], v[134:135], 0, v[132:133]
	v_lshl_add_u64 v[164:165], s[30:31], 0, v[132:133]
	v_lshlrev_b32_e32 v132, 10, v166
	v_lshlrev_b32_e32 v166, 4, v167
	v_add3_u32 v132, 0, v132, v166
	v_add_u32_e32 v168, 0x2000, v132
	v_readfirstlane_b32 s25, v132
	s_mov_b32 m0, s25
	v_readfirstlane_b32 s25, v168
	v_add_u32_e32 v168, 0x4000, v132
	global_load_lds_dwordx4 v[134:135], off
	s_nop 0
	s_cselect_b32 s98, 1, 0
	s_add_i32 m0, m0, 0xff80
	s_cmp_lg_u32 s98, 0
	global_load_lds_dwordx4 v[134:135], off offset:128
	s_nop 0
	v_lshl_add_u64 v[166:167], v[134:135], 0, s[10:11]
	s_mov_b32 m0, s25
	v_readfirstlane_b32 s25, v168
	global_load_lds_dwordx4 v[166:167], off
	s_nop 0
	s_cselect_b32 s98, 1, 0
	s_add_i32 m0, m0, 0xff80
	s_cmp_lg_u32 s98, 0
	global_load_lds_dwordx4 v[166:167], off offset:128
	s_nop 0
	v_lshl_add_u64 v[166:167], v[134:135], 0, s[12:13]
	s_mov_b32 m0, s25
	v_ashrrev_i32_e32 v137, 31, v136
	global_load_lds_dwordx4 v[166:167], off
	s_nop 0
	s_cselect_b32 s98, 1, 0
	s_add_i32 m0, m0, 0xff80
	s_cmp_lg_u32 s98, 0
	global_load_lds_dwordx4 v[166:167], off offset:128
	s_nop 0
	v_add_u32_e32 v166, 0x6000, v132
	v_lshl_add_u64 v[134:135], v[134:135], 0, s[14:15]
	v_readfirstlane_b32 s25, v166
	s_mov_b32 m0, s25
	v_add_u32_e32 v166, 0x8000, v132
	global_load_lds_dwordx4 v[134:135], off
	s_nop 0
	s_cselect_b32 s98, 1, 0
	s_add_i32 m0, m0, 0xff80
	s_cmp_lg_u32 s98, 0
	global_load_lds_dwordx4 v[134:135], off offset:128
	s_nop 0
	v_lshlrev_b64 v[134:135], 11, v[136:137]
	v_readfirstlane_b32 s25, v166
	v_ashrrev_i32_e32 v139, 31, v138
	v_lshl_add_u64 v[134:135], v[164:165], 0, v[134:135]
	s_mov_b32 m0, s25
	v_add_u32_e32 v136, 0xa000, v132
	global_load_lds_dwordx4 v[134:135], off
	s_nop 0
	s_cselect_b32 s98, 1, 0
	s_add_i32 m0, m0, 0xff80
	s_cmp_lg_u32 s98, 0
	global_load_lds_dwordx4 v[134:135], off offset:128
	s_nop 0
	v_lshlrev_b64 v[134:135], 11, v[138:139]
	v_readfirstlane_b32 s25, v136
	v_ashrrev_i32_e32 v141, 31, v140
	v_lshl_add_u64 v[134:135], v[164:165], 0, v[134:135]
	s_mov_b32 m0, s25
	v_add_u32_e32 v136, 0xc000, v132
	global_load_lds_dwordx4 v[134:135], off
	s_nop 0
	s_cselect_b32 s98, 1, 0
	s_add_i32 m0, m0, 0xff80
	s_cmp_lg_u32 s98, 0
	global_load_lds_dwordx4 v[134:135], off offset:128
	s_nop 0
	v_lshlrev_b64 v[134:135], 11, v[140:141]
	v_readfirstlane_b32 s25, v136
	v_ashrrev_i32_e32 v143, 31, v142
	v_lshl_add_u64 v[134:135], v[164:165], 0, v[134:135]
	s_mov_b32 m0, s25
	v_add_u32_e32 v132, 0xe000, v132
	global_load_lds_dwordx4 v[134:135], off
	s_nop 0
	s_cselect_b32 s98, 1, 0
	s_add_i32 m0, m0, 0xff80
	s_cmp_lg_u32 s98, 0
	global_load_lds_dwordx4 v[134:135], off offset:128
	s_nop 0
	v_lshlrev_b64 v[134:135], 11, v[142:143]
	v_readfirstlane_b32 s25, v132
	v_lshl_add_u64 v[134:135], v[164:165], 0, v[134:135]
	s_mov_b32 m0, s25
	s_nop 0
	global_load_lds_dwordx4 v[134:135], off
	s_nop 0
	s_cselect_b32 s98, 1, 0
	s_add_i32 m0, m0, 0xff80
	s_cmp_lg_u32 s98, 0
	global_load_lds_dwordx4 v[134:135], off offset:128
	s_nop 0
	s_branch .LBB0_1633

; DI int opaque_tid() { int t = threadIdx.x; asm volatile("" : "+v"(t)); return t; }
; #define GEMM_ISSUE(KT, ST) do { const int k1_ = (KT) << 6; unsigned char* d_ = ldst + (ST) * STAGE; \
;         _Pragma("unroll") for (int j_ = 0; j_ < 4; ++j_) dma16(ap + (size_t)(64 * j_) * lda + k1_, d_ + j_ * 8192); \
;         _Pragma("unroll") for (int j_ = 0; j_ < NBW; ++j_) dma16(bp + bro[j_] + k1_, d_ + BOFF + j_ * 8192); } while (0)
; template <int NBW>
; DI void gemm_mainloop(f32x16 (&acc)[2][NBW], const bf16_t* A, size_t lda, int m0, const bf16_t* Bt, size_t ldb, int n0, int K, unsigned char* lds, bool pre = false, bool only_issue = false) {
;     ...
;     const int t = opaque_tid(), w = t >> 6, lane = t & 63, r = lane & 31, hh = lane >> 5, wm = w >> 1, wn = w & 1;
;     const int drow = w * 8 + (lane >> 3);
;     const int lchunk = (lane & 7) ^ ((drow >> 1) & 7);
;     const bf16_t* ap = A + (size_t)(m0 + drow) * lda + lchunk * 8;
;     const bf16_t* bp = Bt + (size_t)n0 * ldb + lchunk * 8;
;     size_t bro[NBW];
; #pragma unroll
;     for (int j = 0; j < NBW; ++j) {
;         const int rho = 64 * j + drow; const int wnh = rho / (32 * NBW), wi = rho % (32 * NBW);
;         bro[j] = (size_t)(wnh * 32 * NBW + NBW * (wi & 31) + (wi >> 5)) * ldb;
;     }
;     unsigned char* ldst = lds + w * 1024 + lane * 16;
;     ...
;     if (!pre) GEMM_ISSUE(0, 0);
.LBB0_1719:
	v_mov_b32_e32 v13, v1
	s_ashr_i32 s18, s47, 31
	v_ashrrev_i32_e32 v12, 6, v13
	v_lshlrev_b32_e32 v2, 3, v12
	v_bfe_u32 v7, v13, 3, 3
	v_or_b32_e32 v15, v2, v7
	v_lshrrev_b32_e32 v3, 1, v15
	v_xor_b32_e32 v20, v3, v13
	v_ashrrev_i32_e32 v3, 31, v13
	v_lshrrev_b32_e32 v3, 25, v3
	v_add_u32_e32 v4, v15, v3
	v_lshrrev_b32_e32 v3, 7, v4
	v_mul_i32_i24_e32 v3, 0x80, v3
	v_sub_u32_e32 v16, v15, v3
	v_and_b32_e32 v4, 0xffffff80, v4
	v_ashrrev_i32_e32 v5, 5, v16
	v_add_u32_e32 v8, v5, v4
	v_add_u32_e32 v5, 64, v15
	v_ashrrev_i32_e32 v4, 31, v5
	v_lshrrev_b32_e32 v4, 25, v4
	v_add_u32_e32 v6, v5, v4
	v_lshrrev_b32_e32 v4, 7, v6
	v_mul_i32_i24_e32 v4, 0x80, v4
	v_sub_u32_e32 v17, v5, v4
	v_and_b32_e32 v5, 0xffffff80, v6
	v_ashrrev_i32_e32 v6, 5, v17
	v_add_u32_e32 v9, v6, v5
	v_add_u32_e32 v6, 0x80, v15
	v_ashrrev_i32_e32 v5, 31, v6
	v_lshrrev_b32_e32 v5, 25, v5
	v_add_u32_e32 v10, v6, v5
	v_lshrrev_b32_e32 v5, 7, v10
	v_mul_i32_i24_e32 v5, 0x80, v5
	v_sub_u32_e32 v18, v6, v5
	v_and_b32_e32 v6, 0xffffff80, v10
	v_ashrrev_i32_e32 v10, 5, v18
	v_add_u32_e32 v11, 0xc0, v15
	v_add_u32_e32 v10, v10, v6
	v_ashrrev_i32_e32 v6, 31, v11
	v_lshrrev_b32_e32 v6, 25, v6
	s_lshr_b32 s18, s18, 30
	v_add_u32_e32 v21, v11, v6
	s_add_i32 s20, s47, s18
	v_lshrrev_b32_e32 v6, 7, v21
	s_ashr_i32 s18, s20, 2
	s_and_b32 s20, s20, 0xfffffc
	v_mul_i32_i24_e32 v6, 0x80, v6
	s_sub_i32 s20, s47, s20
	v_sub_u32_e32 v19, v11, v6
	s_lshl_b32 s21, s18, 8
	s_lshl_b32 s20, s20, 8
	v_and_b32_e32 v14, 63, v13
	v_and_b32_e32 v11, 0xffffff80, v21
	v_ashrrev_i32_e32 v21, 5, v19
	s_lshr_b32 s19, s18, 5
	s_and_b32 s48, s21, 0x1f00
	s_ashr_i32 s21, s20, 31
	v_add_u32_e32 v11, v21, v11
	v_lshlrev_b32_e32 v21, 10, v12
	v_lshlrev_b32_e32 v22, 4, v14
	v_lshlrev_b32_e32 v20, 4, v20
	s_mulk_i32 s19, 0x2080
	s_lshl_b64 s[22:23], s[20:21], 13
	v_add3_u32 v147, 0, v21, v22
	s_and_b64 vcc, exec, s[24:25]
	v_and_b32_e32 v132, 0x70, v20
	s_cbranch_vccnz .LBB0_1721
	s_add_i32 s21, s19, s48
	s_addk_i32 s21, 0x80
	v_add_u32_e32 v20, s21, v15
	v_lshlrev_b32_e32 v15, 2, v16
	v_and_b32_e32 v15, 0x7c, v15
	v_add_u32_e32 v22, v8, v15
	v_lshlrev_b32_e32 v15, 2, v17
	v_and_b32_e32 v15, 0x7c, v15
	v_add_u32_e32 v16, v9, v15
	v_lshlrev_b32_e32 v15, 2, v18
	v_and_b32_e32 v15, 0x7c, v15
	v_ashrrev_i32_e32 v21, 31, v20
	v_add_u32_e32 v24, v10, v15
	v_lshlrev_b32_e32 v15, 2, v19
	v_and_b32_e32 v15, 0x7c, v15
	v_lshlrev_b64 v[20:21], 13, v[20:21]
	v_add_u32_e32 v18, v11, v15
	v_lshl_add_u64 v[20:21], s[0:1], 0, v[20:21]
	v_readfirstlane_b32 s21, v147
	v_add_u32_e32 v15, 0x2000, v147
	v_lshl_add_u64 v[20:21], v[20:21], 0, v[132:133]
	s_mov_b32 m0, s21
	v_readfirstlane_b32 s21, v15
	v_add_u32_e32 v15, 0x4000, v147
	global_load_lds_dwordx4 v[20:21], off
	s_nop 0
	s_cselect_b32 s98, 1, 0
	s_add_i32 m0, m0, 0xff80
	s_cmp_lg_u32 s98, 0
	global_load_lds_dwordx4 v[20:21], off offset:128
	s_nop 0
	v_lshl_add_u64 v[28:29], v[20:21], 0, s[4:5]
	s_mov_b32 m0, s21
	v_readfirstlane_b32 s21, v15
	v_add_u32_e32 v15, 0x6000, v147
	s_add_u32 s24, s26, s22
	global_load_lds_dwordx4 v[28:29], off
	s_nop 0
	s_cselect_b32 s98, 1, 0
	s_add_i32 m0, m0, 0xff80
	s_cmp_lg_u32 s98, 0
	global_load_lds_dwordx4 v[28:29], off offset:128
	s_nop 0
	v_lshl_add_u64 v[28:29], v[20:21], 0, s[6:7]
	s_mov_b32 m0, s21
	v_readfirstlane_b32 s21, v15
	s_addc_u32 s25, s27, s23
	v_ashrrev_i32_e32 v23, 31, v22
	global_load_lds_dwordx4 v[28:29], off
	s_nop 0
	s_cselect_b32 s98, 1, 0
	s_add_i32 m0, m0, 0xff80
	s_cmp_lg_u32 s98, 0
	global_load_lds_dwordx4 v[28:29], off offset:128
	s_nop 0
	v_lshl_add_u64 v[20:21], v[20:21], 0, s[8:9]
	s_mov_b32 m0, s21
	v_add_u32_e32 v15, 0x8000, v147
	v_ashrrev_i32_e32 v17, 31, v16
	v_lshl_add_u64 v[26:27], s[24:25], 0, v[132:133]
	global_load_lds_dwordx4 v[20:21], off
	s_nop 0
	s_cselect_b32 s98, 1, 0
	s_add_i32 m0, m0, 0xff80
	s_cmp_lg_u32 s98, 0
	global_load_lds_dwordx4 v[20:21], off offset:128
	s_nop 0
	v_lshlrev_b64 v[20:21], 13, v[22:23]
	v_readfirstlane_b32 s21, v15
	v_add_u32_e32 v15, 0xa000, v147
	v_lshl_add_u64 v[20:21], v[26:27], 0, v[20:21]
	s_mov_b32 m0, s21
	v_lshlrev_b64 v[16:17], 13, v[16:17]
	v_readfirstlane_b32 s21, v15
	v_ashrrev_i32_e32 v25, 31, v24
	global_load_lds_dwordx4 v[20:21], off
	s_nop 0
	s_cselect_b32 s98, 1, 0
	s_add_i32 m0, m0, 0xff80
	s_cmp_lg_u32 s98, 0
	global_load_lds_dwordx4 v[20:21], off offset:128
	s_nop 0
	v_lshl_add_u64 v[16:17], v[26:27], 0, v[16:17]
	s_mov_b32 m0, s21
	v_add_u32_e32 v15, 0xc000, v147
	global_load_lds_dwordx4 v[16:17], off
	s_nop 0
	s_cselect_b32 s98, 1, 0
	s_add_i32 m0, m0, 0xff80
	s_cmp_lg_u32 s98, 0
	global_load_lds_dwordx4 v[16:17], off offset:128
	s_nop 0
	v_lshlrev_b64 v[16:17], 13, v[24:25]
	v_readfirstlane_b32 s21, v15
	v_ashrrev_i32_e32 v19, 31, v18
	v_lshl_add_u64 v[16:17], v[26:27], 0, v[16:17]
	s_mov_b32 m0, s21
	v_add_u32_e32 v15, 0xe000, v147
	global_load_lds_dwordx4 v[16:17], off
	s_nop 0
	s_cselect_b32 s98, 1, 0
	s_add_i32 m0, m0, 0xff80
	s_cmp_lg_u32 s98, 0
	global_load_lds_dwordx4 v[16:17], off offset:128
	s_nop 0
	v_lshlrev_b64 v[16:17], 13, v[18:19]
	v_readfirstlane_b32 s21, v15
	v_lshl_add_u64 v[16:17], v[26:27], 0, v[16:17]
	s_mov_b32 m0, s21
	s_nop 0
	global_load_lds_dwordx4 v[16:17], off
	s_nop 0
	s_cselect_b32 s98, 1, 0
	s_add_i32 m0, m0, 0xff80
	s_cmp_lg_u32 s98, 0
	global_load_lds_dwordx4 v[16:17], off offset:128
	s_nop 0
; #define GEMM_ISSUE(KT, ST) do { const int k1_ = (KT) << 6; unsigned char* d_ = ldst + (ST) * STAGE; \
;         _Pragma("unroll") for (int j_ = 0; j_ < 4; ++j_) dma16(ap + (size_t)(64 * j_) * lda + k1_, d_ + j_ * 8192); \
;         _Pragma("unroll") for (int j_ = 0; j_ < NBW; ++j_) dma16(bp + bro[j_] + k1_, d_ + BOFF + j_ * 8192); } while (0)
; template <int NBW>
; DI void gemm_mainloop(f32x16 (&acc)[2][NBW], const bf16_t* A, size_t lda, int m0, const bf16_t* Bt, size_t ldb, int n0, int K, unsigned char* lds, bool pre = false, bool only_issue = false) {
;     ...
;     __syncthreads();
;     const int nk = K >> 6;
;     const int xr = (r >> 1) & 7;
;     int xo[4];
; #pragma unroll
;     for (int s = 0; s < 4; ++s) xo[s] = ((2 * s + hh) ^ xr) << 4;
;     const int aofs = (wm * 64 + r) * 128;
;     const int bofs = BOFF + (wn * 32 * NBW + r) * 128;
; #pragma unroll 1
;     for (int kt = 0; kt < nk; ++kt) {
;         const unsigned char* st = lds + (kt & 1) * STAGE;
; #pragma unroll
;         for (int s = 0; s < 4; ++s) {
;             if (s == 1 && kt + 1 < nk) GEMM_ISSUE(kt + 1, (kt + 1) & 1);
;             bf16x8 a[2], b[NBW];
; #pragma unroll
;             for (int mb = 0; mb < 2; ++mb) a[mb] = *(const bf16x8*)(st + aofs + mb * 4096 + xo[s]);
; #pragma unroll
;             for (int nb = 0; nb < NBW; ++nb) b[nb] = *(const bf16x8*)(st + bofs + nb * 4096 + xo[s]);
.LBB0_1721:
	v_and_b32_e32 v15, 31, v13
	v_lshlrev_b32_e32 v12, 7, v12
	s_add_i32 s48, s48, s19
	v_lshrrev_b32_e32 v17, 6, v13
	v_and_or_b32 v12, v12, s28, v15
	v_add_u32_e32 v7, s48, v7
	v_lshrrev_b32_e32 v16, 5, v14
	v_lshrrev_b32_e32 v14, 3, v14
	v_lshlrev_b32_e32 v153, 7, v12
	v_add3_u32 v12, v7, v2, s28
	v_lshlrev_b16_e32 v2, 3, v17
	v_or_b32_e32 v7, v2, v14
	v_sub_u16_e32 v2, v7, v3
	v_and_b32_e32 v2, 31, v2
	v_lshl_add_u32 v2, v2, 2, v8
	v_ashrrev_i32_e32 v3, 31, v2
	v_lshlrev_b64 v[2:3], 13, v[2:3]
	v_lshl_add_u64 v[2:3], v[2:3], 0, s[22:23]
	v_lshl_add_u64 v[2:3], v[2:3], 0, v[132:133]
	v_lshl_add_u64 v[136:137], s[2:3], 0, v[2:3]
	v_sub_u16_e32 v2, v7, v4
	v_and_b32_e32 v2, 31, v2
	v_lshl_add_u32 v2, v2, 2, v9
	v_ashrrev_i32_e32 v3, 31, v2
	v_lshlrev_b64 v[2:3], 13, v[2:3]
	v_lshl_add_u64 v[2:3], v[2:3], 0, s[22:23]
	v_lshl_add_u64 v[2:3], v[2:3], 0, v[132:133]
	v_lshl_add_u64 v[138:139], s[2:3], 0, v[2:3]
	v_sub_u16_e32 v2, v7, v5
	v_and_b32_e32 v2, 31, v2
	v_lshl_add_u32 v2, v2, 2, v10
	v_ashrrev_i32_e32 v3, 31, v2
	v_lshlrev_b64 v[2:3], 13, v[2:3]
	v_lshl_add_u64 v[2:3], v[2:3], 0, s[22:23]
	v_lshl_add_u64 v[2:3], v[2:3], 0, v[132:133]
	v_lshrrev_b32_e32 v18, 1, v13
	v_lshl_add_u64 v[140:141], s[2:3], 0, v[2:3]
	v_sub_u16_e32 v2, v7, v6
	v_bfe_u32 v13, v13, 1, 3
	v_bitop3_b32 v19, v16, v18, 7 bitop3:0x78
	v_and_b32_e32 v2, 31, v2
	v_lshlrev_b32_e32 v148, 4, v19
	v_bitop3_b32 v19, v16, v13, 2 bitop3:0x36
	v_lshl_add_u32 v2, v2, 2, v11
	v_lshlrev_b32_e32 v149, 4, v19
	v_bitop3_b32 v19, v16, v13, 4 bitop3:0x36
	v_bitop3_b32 v13, v16, v13, 6 bitop3:0x36
	v_ashrrev_i32_e32 v3, 31, v2
	v_lshlrev_b32_e32 v151, 4, v13
	v_and_or_b32 v13, v18, s34, v15
	v_lshlrev_b64 v[2:3], 13, v[2:3]
	v_lshlrev_b32_e32 v152, 7, v13
	v_ashrrev_i32_e32 v13, 31, v12
	v_lshl_add_u64 v[2:3], v[2:3], 0, s[22:23]
	v_lshlrev_b64 v[12:13], 13, v[12:13]
	v_lshl_add_u64 v[2:3], v[2:3], 0, v[132:133]
	v_or_b32_e32 v12, v12, v132
	v_lshl_add_u64 v[142:143], s[2:3], 0, v[2:3]
	v_mov_b32_e32 v2, 0
	v_lshlrev_b32_e32 v150, 4, v19
	v_lshl_add_u64 v[134:135], s[50:51], 0, v[12:13]
	s_mov_b32 s19, 0
	s_mov_b64 s[22:23], 0
	s_mov_b32 s21, 0x10000
	v_mov_b32_e32 v3, v2
	v_mov_b32_e32 v4, v2
	v_mov_b32_e32 v5, v2
	v_mov_b32_e32 v6, v2
	v_mov_b32_e32 v7, v2
	v_mov_b32_e32 v8, v2
	v_mov_b32_e32 v9, v2
	v_mov_b32_e32 v10, v2
	v_mov_b32_e32 v11, v2
	v_mov_b32_e32 v12, v2
	v_mov_b32_e32 v13, v2
	v_mov_b32_e32 v14, v2
	v_mov_b32_e32 v15, v2
	v_mov_b32_e32 v16, v2
	v_mov_b32_e32 v17, v2
	v_mov_b32_e32 v18, v2
	v_mov_b32_e32 v19, v2
	v_mov_b32_e32 v20, v2
	v_mov_b32_e32 v21, v2
	v_mov_b32_e32 v22, v2
	v_mov_b32_e32 v23, v2
	v_mov_b32_e32 v24, v2
	v_mov_b32_e32 v25, v2
	v_mov_b32_e32 v26, v2
	v_mov_b32_e32 v27, v2
	v_mov_b32_e32 v28, v2
	v_mov_b32_e32 v29, v2
	v_mov_b32_e32 v30, v2
	v_mov_b32_e32 v31, v2
	v_mov_b32_e32 v32, v2
	v_mov_b32_e32 v33, v2
	v_mov_b32_e32 v34, v2
	v_mov_b32_e32 v35, v2
	v_mov_b32_e32 v36, v2
	v_mov_b32_e32 v37, v2
	v_mov_b32_e32 v38, v2
	v_mov_b32_e32 v39, v2
	v_mov_b32_e32 v40, v2
	v_mov_b32_e32 v41, v2
	v_mov_b32_e32 v42, v2
	v_mov_b32_e32 v43, v2
	v_mov_b32_e32 v44, v2
	v_mov_b32_e32 v45, v2
	v_mov_b32_e32 v46, v2
	v_mov_b32_e32 v47, v2
	v_mov_b32_e32 v48, v2
	v_mov_b32_e32 v49, v2
	v_mov_b32_e32 v50, v2
	v_mov_b32_e32 v51, v2
	v_mov_b32_e32 v52, v2
	v_mov_b32_e32 v53, v2
	v_mov_b32_e32 v54, v2
	v_mov_b32_e32 v55, v2
	v_mov_b32_e32 v56, v2
	v_mov_b32_e32 v57, v2
	v_mov_b32_e32 v58, v2
	v_mov_b32_e32 v59, v2
	v_mov_b32_e32 v60, v2
	v_mov_b32_e32 v61, v2
	v_mov_b32_e32 v62, v2
	v_mov_b32_e32 v63, v2
	v_mov_b32_e32 v64, v2
	v_mov_b32_e32 v65, v2
	v_mov_b32_e32 v66, v2
	v_mov_b32_e32 v67, v2
	v_mov_b32_e32 v68, v2
	v_mov_b32_e32 v69, v2
	v_mov_b32_e32 v70, v2
	v_mov_b32_e32 v71, v2
	v_mov_b32_e32 v72, v2
	v_mov_b32_e32 v73, v2
	v_mov_b32_e32 v74, v2
	v_mov_b32_e32 v75, v2
	v_mov_b32_e32 v76, v2
	v_mov_b32_e32 v77, v2
	v_mov_b32_e32 v78, v2
	v_mov_b32_e32 v79, v2
	v_mov_b32_e32 v80, v2
	v_mov_b32_e32 v81, v2
	v_mov_b32_e32 v82, v2
	v_mov_b32_e32 v83, v2
	v_mov_b32_e32 v84, v2
	v_mov_b32_e32 v85, v2
	v_mov_b32_e32 v86, v2
	v_mov_b32_e32 v87, v2
	v_mov_b32_e32 v88, v2
	v_mov_b32_e32 v89, v2
	v_mov_b32_e32 v90, v2
	v_mov_b32_e32 v91, v2
	v_mov_b32_e32 v92, v2
	v_mov_b32_e32 v93, v2
	v_mov_b32_e32 v94, v2
	v_mov_b32_e32 v95, v2
	v_mov_b32_e32 v96, v2
	v_mov_b32_e32 v97, v2
	v_mov_b32_e32 v98, v2
	v_mov_b32_e32 v99, v2
	v_mov_b32_e32 v100, v2
	v_mov_b32_e32 v101, v2
	v_mov_b32_e32 v102, v2
	v_mov_b32_e32 v103, v2
	v_mov_b32_e32 v104, v2
	v_mov_b32_e32 v105, v2
	v_mov_b32_e32 v106, v2
	v_mov_b32_e32 v107, v2
	v_mov_b32_e32 v108, v2
	v_mov_b32_e32 v109, v2
	v_mov_b32_e32 v110, v2
	v_mov_b32_e32 v111, v2
	v_mov_b32_e32 v112, v2
	v_mov_b32_e32 v113, v2
	v_mov_b32_e32 v114, v2
	v_mov_b32_e32 v115, v2
	v_mov_b32_e32 v116, v2
	v_mov_b32_e32 v117, v2
	v_mov_b32_e32 v118, v2
	v_mov_b32_e32 v119, v2
	v_mov_b32_e32 v120, v2
	v_mov_b32_e32 v121, v2
	v_mov_b32_e32 v122, v2
	v_mov_b32_e32 v123, v2
	v_mov_b32_e32 v124, v2
	v_mov_b32_e32 v125, v2
	v_mov_b32_e32 v126, v2
	v_mov_b32_e32 v127, v2
	v_mov_b32_e32 v128, v2
	v_mov_b32_e32 v129, v2
	s_waitcnt vmcnt(0) lgkmcnt(0)
	s_barrier
	v_mov_b32_e32 v132, v152
	v_mov_b32_e32 v154, v153
	s_add_u32 s22, s22, 0x80
	s_addc_u32 s23, s23, 0
	s_add_i32 s21, s21, 0x10000
	v_add_u32_e32 v252, v132, v148
	v_add_u32_e32 v253, v154, v148
	ds_read_b128 v[224:227], v252
	ds_read_b128 v[232:235], v253 offset:32768
	ds_read_b128 v[236:239], v253 offset:36864
	ds_read_b128 v[240:243], v253 offset:40960
	ds_read_b128 v[244:247], v253 offset:45056
	ds_read_b128 v[228:231], v252 offset:4096

; DI void phase_p7(const Params& P, unsigned char* lds) {
;     ...
;         gemm_mainloop<4>(acc, U, 4096, m0, W, 4096, n0, 4096, lds, pre);
;         { const int tn = tile + gridDim.x; pre = tn < 128 * NTN; if (pre) { const int mtn = tn / NTN, ntn_ = tn % NTN; f32x16 (&dummy)[2][4] = acc; gemm_mainloop<4>(dummy, U, 4096, (mtn >> 5) * LP + OFF + (mtn & 31) * 256, W, 4096, ntn_ * 256, 4096, lds, false, true); } }
.LBB0_1725:
	v_readlane_b32 s22, v223, 3
	s_add_i32 s47, s47, s22
	v_readlane_b32 s23, v223, 4
	s_cmpk_gt_i32 s47, 0x1ff
	s_cselect_b64 s[22:23], -1, 0
	s_and_b64 vcc, exec, s[22:23]
	s_cbranch_vccnz .LBB0_1718
	v_mov_b32_e32 v132, v1
	s_ashr_i32 s19, s47, 31
	v_ashrrev_i32_e32 v147, 6, v132
	v_bfe_u32 v134, v132, 3, 3
	v_lshl_or_b32 v142, v147, 3, v134
	v_lshrrev_b32_e32 v134, 1, v142
	v_and_b32_e32 v150, 63, v132
	v_xor_b32_e32 v148, v134, v132
	v_ashrrev_i32_e32 v132, 31, v132
	v_lshrrev_b32_e32 v132, 25, v132
	v_add_u32_e32 v132, v142, v132
	v_lshrrev_b32_e32 v136, 7, v132
	v_mul_i32_i24_e32 v136, 0x80, v136
	v_sub_u32_e32 v136, v142, v136
	v_lshlrev_b32_e32 v137, 2, v136
	v_and_b32_e32 v132, 0xffffff80, v132
	v_and_b32_e32 v137, 0x7c, v137
	v_ashrrev_i32_e32 v136, 5, v136
	v_add3_u32 v136, v136, v132, v137
	v_add_u32_e32 v132, 64, v142
	v_ashrrev_i32_e32 v138, 31, v132
	v_lshrrev_b32_e32 v138, 25, v138
	v_add_u32_e32 v138, v132, v138
	v_lshrrev_b32_e32 v139, 7, v138
	v_mul_i32_i24_e32 v139, 0x80, v139
	v_sub_u32_e32 v132, v132, v139
	v_lshlrev_b32_e32 v139, 2, v132
	v_and_b32_e32 v138, 0xffffff80, v138
	v_and_b32_e32 v139, 0x7c, v139
	v_ashrrev_i32_e32 v132, 5, v132
	v_add3_u32 v138, v132, v138, v139
	v_add_u32_e32 v132, 0x80, v142
	v_ashrrev_i32_e32 v140, 31, v132
	v_lshrrev_b32_e32 v140, 25, v140
	s_lshr_b32 s19, s19, 30
	v_add_u32_e32 v140, v132, v140
	s_add_i32 s19, s47, s19
	v_lshrrev_b32_e32 v141, 7, v140
	s_ashr_i32 s21, s19, 2
	v_mul_i32_i24_e32 v141, 0x80, v141
	s_lshr_b32 s24, s21, 5
	s_lshl_b32 s21, s21, 8
	v_sub_u32_e32 v132, v132, v141
	s_mulk_i32 s24, 0x2080
	s_and_b32 s21, s21, 0x1f00
	v_lshlrev_b32_e32 v141, 2, v132
	s_add_i32 s21, s24, s21
	v_and_b32_e32 v140, 0xffffff80, v140
	v_and_b32_e32 v141, 0x7c, v141
	v_ashrrev_i32_e32 v132, 5, v132
	s_addk_i32 s21, 0x80
	v_add3_u32 v140, v132, v140, v141
	v_add_u32_e32 v132, 0xc0, v142
	v_add_u32_e32 v134, s21, v142
	v_ashrrev_i32_e32 v142, 31, v132
	v_lshrrev_b32_e32 v142, 25, v142
	v_add_u32_e32 v142, v132, v142
	s_and_b32 s19, s19, 0xfffffc
	v_lshrrev_b32_e32 v143, 7, v142
	s_sub_i32 s19, s47, s19
	v_mul_i32_i24_e32 v143, 0x80, v143
	s_lshl_b32 s24, s19, 8
	v_sub_u32_e32 v132, v132, v143
	s_ashr_i32 s25, s24, 31
	v_lshlrev_b32_e32 v143, 2, v132
	v_ashrrev_i32_e32 v135, 31, v134
	s_lshl_b64 s[24:25], s[24:25], 13
	v_and_b32_e32 v142, 0xffffff80, v142
	v_and_b32_e32 v143, 0x7c, v143
	v_ashrrev_i32_e32 v132, 5, v132
	s_add_u32 s24, s26, s24
	v_add3_u32 v142, v132, v142, v143
	v_lshlrev_b64 v[134:135], 13, v[134:135]
	v_lshlrev_b32_e32 v132, 4, v148
	s_addc_u32 s25, s27, s25
	v_lshl_add_u64 v[134:135], s[0:1], 0, v[134:135]
	v_and_b32_e32 v132, 0x70, v132
	v_lshl_add_u64 v[134:135], v[134:135], 0, v[132:133]
	v_lshl_add_u64 v[148:149], s[24:25], 0, v[132:133]
	v_lshlrev_b32_e32 v132, 10, v147
	v_lshlrev_b32_e32 v147, 4, v150
	v_add3_u32 v132, 0, v132, v147
	v_add_u32_e32 v147, 0x2000, v132
	v_readfirstlane_b32 s19, v132
	s_mov_b32 m0, s19
	v_readfirstlane_b32 s19, v147
	v_add_u32_e32 v147, 0x4000, v132
	global_load_lds_dwordx4 v[134:135], off
	s_nop 0
	s_cselect_b32 s98, 1, 0
	s_add_i32 m0, m0, 0xff80
	s_cmp_lg_u32 s98, 0
	global_load_lds_dwordx4 v[134:135], off offset:128
	s_nop 0
	v_lshl_add_u64 v[150:151], v[134:135], 0, s[4:5]
	s_mov_b32 m0, s19
	v_readfirstlane_b32 s19, v147
	v_add_u32_e32 v147, 0x6000, v132
	global_load_lds_dwordx4 v[150:151], off
	s_nop 0
	s_cselect_b32 s98, 1, 0
	s_add_i32 m0, m0, 0xff80
	s_cmp_lg_u32 s98, 0
	global_load_lds_dwordx4 v[150:151], off offset:128
	s_nop 0
	v_lshl_add_u64 v[150:151], v[134:135], 0, s[6:7]
	s_mov_b32 m0, s19
	v_readfirstlane_b32 s19, v147
	v_ashrrev_i32_e32 v137, 31, v136
	global_load_lds_dwordx4 v[150:151], off
	s_nop 0
	s_cselect_b32 s98, 1, 0
	s_add_i32 m0, m0, 0xff80
	s_cmp_lg_u32 s98, 0
	global_load_lds_dwordx4 v[150:151], off offset:128
	s_nop 0
	v_lshl_add_u64 v[134:135], v[134:135], 0, s[8:9]
	s_mov_b32 m0, s19
	v_add_u32_e32 v147, 0x8000, v132
	global_load_lds_dwordx4 v[134:135], off
	s_nop 0
	s_cselect_b32 s98, 1, 0
	s_add_i32 m0, m0, 0xff80
	s_cmp_lg_u32 s98, 0
	global_load_lds_dwordx4 v[134:135], off offset:128
	s_nop 0
	v_lshlrev_b64 v[134:135], 13, v[136:137]
	v_readfirstlane_b32 s19, v147
	v_ashrrev_i32_e32 v139, 31, v138
	v_lshl_add_u64 v[134:135], v[148:149], 0, v[134:135]
	s_mov_b32 m0, s19
	v_add_u32_e32 v136, 0xa000, v132
	global_load_lds_dwordx4 v[134:135], off
	s_nop 0
	s_cselect_b32 s98, 1, 0
	s_add_i32 m0, m0, 0xff80
	s_cmp_lg_u32 s98, 0
	global_load_lds_dwordx4 v[134:135], off offset:128
	s_nop 0
	v_lshlrev_b64 v[134:135], 13, v[138:139]
	v_readfirstlane_b32 s19, v136
	v_ashrrev_i32_e32 v141, 31, v140
	v_lshl_add_u64 v[134:135], v[148:149], 0, v[134:135]
	s_mov_b32 m0, s19
	v_add_u32_e32 v136, 0xc000, v132
	global_load_lds_dwordx4 v[134:135], off
	s_nop 0
	s_cselect_b32 s98, 1, 0
	s_add_i32 m0, m0, 0xff80
	s_cmp_lg_u32 s98, 0
	global_load_lds_dwordx4 v[134:135], off offset:128
	s_nop 0
	v_lshlrev_b64 v[134:135], 13, v[140:141]
	v_readfirstlane_b32 s19, v136
	v_ashrrev_i32_e32 v143, 31, v142
	v_lshl_add_u64 v[134:135], v[148:149], 0, v[134:135]
	s_mov_b32 m0, s19
	v_add_u32_e32 v132, 0xe000, v132
	global_load_lds_dwordx4 v[134:135], off
	s_nop 0
	s_cselect_b32 s98, 1, 0
	s_add_i32 m0, m0, 0xff80
	s_cmp_lg_u32 s98, 0
	global_load_lds_dwordx4 v[134:135], off offset:128
	s_nop 0
	v_lshlrev_b64 v[134:135], 13, v[142:143]
	v_readfirstlane_b32 s19, v132
	v_lshl_add_u64 v[134:135], v[148:149], 0, v[134:135]
	s_mov_b32 m0, s19
	s_nop 0
	global_load_lds_dwordx4 v[134:135], off
	s_nop 0
	s_cselect_b32 s98, 1, 0
	s_add_i32 m0, m0, 0xff80
	s_cmp_lg_u32 s98, 0
	global_load_lds_dwordx4 v[134:135], off offset:128
	s_nop 0
	s_branch .LBB0_1718

; #define AS_LDS __attribute__((address_space(3)))
; #define RUN_PHASE(K, BODY) do { if (P.ph_lo <= (K) && (K) < P.ph_hi) { BODY; if (P.coop && (K) + 1 < P.ph_hi) { if (P.pad) grid.sync();     xcd_barrier(xb); } } } while (0)
; __global__ void __launch_bounds__(512) mega_fwd(Params P) {
;     extern __shared__ __attribute__((aligned(16))) unsigned char lds[];
;     cg::grid_group grid = cg::this_grid();
;     volatile AS_LDS unsigned* xst = (volatile AS_LDS unsigned*)(lds + LDS_BYTES - 32);
;     if (threadIdx.x < 2) xst[threadIdx.x] = 0u;
;     __syncthreads();
;     const XcdBarrier xb = xcd_barrier_post((unsigned*)(P.ws + WS_BAR), xst);
;     ...
;     RUN_PHASE(0, (p0_rows(P, lds), p0_weights(P, lds), p0_misc(P)));
;     RUN_PHASE(1, phase_p1(P, lds));
;     RUN_PHASE(2, phase_p2(P, lds));
;     RUN_PHASE(3, phase_p3(P, lds));
;     RUN_PHASE(4, phase_p4(P, lds));
;     RUN_PHASE(5, phase_p5(P, lds));
;     RUN_PHASE(6, phase_p6(P, lds));
;     RUN_PHASE(7, phase_p7(P, lds));
;     ...
; }
	.amdhsa_kernel _Z8mega_fwd6Params
		.amdhsa_group_segment_fixed_size 0
		.amdhsa_private_segment_fixed_size 0
		.amdhsa_kernarg_size 440
		.amdhsa_user_sgpr_count 2
		.amdhsa_user_sgpr_dispatch_ptr 0
		.amdhsa_user_sgpr_queue_ptr 0
		.amdhsa_user_sgpr_kernarg_segment_ptr 1
		.amdhsa_user_sgpr_dispatch_id 0
		.amdhsa_user_sgpr_kernarg_preload_length 0
		.amdhsa_user_sgpr_kernarg_preload_offset 0
		.amdhsa_user_sgpr_private_segment_size 0
		.amdhsa_uses_dynamic_stack 0
		.amdhsa_enable_private_segment 0
		.amdhsa_system_sgpr_workgroup_id_x 1
		.amdhsa_system_sgpr_workgroup_id_y 0
		.amdhsa_system_sgpr_workgroup_id_z 0
		.amdhsa_system_sgpr_workgroup_info 0
		.amdhsa_system_vgpr_workitem_id 2
		.amdhsa_next_free_vgpr 256
		.amdhsa_next_free_sgpr 102
		.amdhsa_accum_offset 256
		.amdhsa_reserve_vcc 1
		.amdhsa_float_round_mode_32 0
		.amdhsa_float_round_mode_16_64 0
		.amdhsa_float_denorm_mode_32 3
		.amdhsa_float_denorm_mode_16_64 3
		.amdhsa_dx10_clamp 1
		.amdhsa_ieee_mode 1
		.amdhsa_fp16_overflow 0
		.amdhsa_tg_split 0
		.amdhsa_exception_fp_ieee_invalid_op 0
		.amdhsa_exception_fp_denorm_src 0
		.amdhsa_exception_fp_ieee_div_zero 0
		.amdhsa_exception_fp_ieee_overflow 0
		.amdhsa_exception_fp_ieee_underflow 0
		.amdhsa_exception_fp_ieee_inexact 0
		.amdhsa_exception_int_div_zero 0
	.end_amdhsa_kernel

; #define AS_LDS __attribute__((address_space(3)))
; #define RUN_PHASE(K, BODY) do { if (P.ph_lo <= (K) && (K) < P.ph_hi) { BODY; if (P.coop && (K) + 1 < P.ph_hi) { if (P.pad) grid.sync();     xcd_barrier(xb); } } } while (0)
; __global__ void __launch_bounds__(512) mega_fwd(Params P) {
;     extern __shared__ __attribute__((aligned(16))) unsigned char lds[];
;     cg::grid_group grid = cg::this_grid();
;     volatile AS_LDS unsigned* xst = (volatile AS_LDS unsigned*)(lds + LDS_BYTES - 32);
;     if (threadIdx.x < 2) xst[threadIdx.x] = 0u;
;     __syncthreads();
;     const XcdBarrier xb = xcd_barrier_post((unsigned*)(P.ws + WS_BAR), xst);
;     ...
;     RUN_PHASE(0, (p0_rows(P, lds), p0_weights(P, lds), p0_misc(P)));
;     RUN_PHASE(1, phase_p1(P, lds));
;     RUN_PHASE(2, phase_p2(P, lds));
;     RUN_PHASE(3, phase_p3(P, lds));
;     RUN_PHASE(4, phase_p4(P, lds));
;     RUN_PHASE(5, phase_p5(P, lds));
;     RUN_PHASE(6, phase_p6(P, lds));
;     RUN_PHASE(7, phase_p7(P, lds));
;     ...
; }
amdhsa.kernels:
  - .agpr_count:     0
    .args:
      - .offset:         0
        .size:           184
        .value_kind:     by_value
      - .offset:         184
        .size:           4
        .value_kind:     hidden_block_count_x
      - .offset:         188
        .size:           4
        .value_kind:     hidden_block_count_y
      - .offset:         192
        .size:           4
        .value_kind:     hidden_block_count_z
      - .offset:         196
        .size:           2
        .value_kind:     hidden_group_size_x
      - .offset:         198
        .size:           2
        .value_kind:     hidden_group_size_y
      - .offset:         200
        .size:           2
        .value_kind:     hidden_group_size_z
      - .offset:         202
        .size:           2
        .value_kind:     hidden_remainder_x
      - .offset:         204
        .size:           2
        .value_kind:     hidden_remainder_y
      - .offset:         206
        .size:           2
        .value_kind:     hidden_remainder_z
      - .offset:         224
        .size:           8
        .value_kind:     hidden_global_offset_x
      - .offset:         232
        .size:           8
        .value_kind:     hidden_global_offset_y
      - .offset:         240
        .size:           8
        .value_kind:     hidden_global_offset_z
      - .offset:         248
        .size:           2
        .value_kind:     hidden_grid_dims
      - .offset:         272
        .size:           8
        .value_kind:     hidden_multigrid_sync_arg
      - .offset:         304
        .size:           4
        .value_kind:     hidden_dynamic_lds_size
    .group_segment_fixed_size: 0
    .kernarg_segment_align: 8
    .kernarg_segment_size: 440
    .language:       OpenCL C
    .language_version:
      - 2
      - 0
    .max_flat_workgroup_size: 512
    .name:           _Z8mega_fwd6Params
    .private_segment_fixed_size: 0
    .sgpr_count:     108
    .sgpr_spill_count: 84
    .symbol:         _Z8mega_fwd6Params.kd
    .uniform_work_group_size: 1
    .uses_dynamic_stack: false
    .vgpr_count:     256
    .vgpr_spill_count: 0
    .wavefront_size: 64
